# dead address computations left behind by the earlier preloading edits removed from four GEMM epilogues (52 VALU instructions, exact)
# baseline (speedup 1.0000x reference)
;     __device__ __forceinline__ void operator()(EPI_ARGS) const {
;     ...
;             for (int m = 0; m < 4; ++m) { const int row = row0 + ai * HALF + m * 16;
;                 f32x4 c4 = (f32x4){1.f, 1.f, 1.f, 1.f}, s4 = (f32x4){0.f, 0.f, 0.f, 0.f};
;                 if (rot) { c4 = *(const f32x4*)(cs + (size_t)row * 64 + fi); s4 = *(const f32x4*)(sn + (size_t)row * 64 + fi); }
.LBB0_1098:
	v_or_b32_e32 v120, 16, v160
	v_cndmask_b32_e64 v112, 0, 1, s[36:37]
	v_cmp_ne_u32_e64 s[8:9], 1, v112
	s_andn2_b64 vcc, exec, s[36:37]
	v_ashrrev_i32_e32 v121, 31, v120
	s_cbranch_vccnz .LBB0_1100
	s_waitcnt lgkmcnt(0)
	v_mov_b32_e32 v116, v178
	v_mov_b32_e32 v117, v179
	v_mov_b32_e32 v118, v180
	v_mov_b32_e32 v119, v181
	v_mov_b32_e32 v112, v182
	v_mov_b32_e32 v113, v183
	v_mov_b32_e32 v114, v184
	v_mov_b32_e32 v115, v185
	s_branch .LBB0_1101

;     __device__ __forceinline__ void operator()(EPI_ARGS) const {
;     ...
;             for (int m = 0; m < 4; ++m) { const int row = row0 + ai * HALF + m * 16;
;                 f32x4 c4 = (f32x4){1.f, 1.f, 1.f, 1.f}, s4 = (f32x4){0.f, 0.f, 0.f, 0.f};
;                 if (rot) { c4 = *(const f32x4*)(cs + (size_t)row * 64 + fi); s4 = *(const f32x4*)(sn + (size_t)row * 64 + fi); }
.LBB0_1109:
	v_or_b32_e32 v104, 32, v160
	s_and_b64 vcc, exec, s[8:9]
	v_ashrrev_i32_e32 v105, 31, v104
	s_cbranch_vccnz .LBB0_1111
	s_waitcnt lgkmcnt(0)
	v_mov_b32_e32 v100, v186
	v_mov_b32_e32 v101, v187
	v_mov_b32_e32 v102, v188
	v_mov_b32_e32 v103, v189
	v_mov_b32_e32 v96, v190
	v_mov_b32_e32 v97, v191
	v_mov_b32_e32 v98, v192
	v_mov_b32_e32 v99, v193
	s_branch .LBB0_1112

;     __device__ __forceinline__ void operator()(EPI_ARGS) const {
;     ...
;             for (int m = 0; m < 4; ++m) { const int row = row0 + ai * HALF + m * 16;
;                 f32x4 c4 = (f32x4){1.f, 1.f, 1.f, 1.f}, s4 = (f32x4){0.f, 0.f, 0.f, 0.f};
;                 if (rot) { c4 = *(const f32x4*)(cs + (size_t)row * 64 + fi); s4 = *(const f32x4*)(sn + (size_t)row * 64 + fi); }
.LBB0_1120:
	v_or_b32_e32 v88, 48, v160
	s_and_b64 vcc, exec, s[8:9]
	v_ashrrev_i32_e32 v89, 31, v88
	s_cbranch_vccnz .LBB0_1122
	s_waitcnt lgkmcnt(0)
	v_mov_b32_e32 v84, v194
	v_mov_b32_e32 v85, v195
	v_mov_b32_e32 v86, v196
	v_mov_b32_e32 v87, v197
	v_mov_b32_e32 v80, v198
	v_mov_b32_e32 v81, v199
	v_mov_b32_e32 v82, v200
	v_mov_b32_e32 v83, v201
	s_branch .LBB0_1123

;     __device__ __forceinline__ void operator()(EPI_ARGS) const {
;     ...
;             for (int m = 0; m < 4; ++m) { const int row = row0 + ai * HALF + m * 16;
;                 f32x4 c4 = (f32x4){1.f, 1.f, 1.f, 1.f}, s4 = (f32x4){0.f, 0.f, 0.f, 0.f};
;                 if (rot) { c4 = *(const f32x4*)(cs + (size_t)row * 64 + fi); s4 = *(const f32x4*)(sn + (size_t)row * 64 + fi); }
.LBB0_1131:
	v_add_u32_e32 v72, 0x80, v160
	s_and_b64 vcc, exec, s[8:9]
	v_ashrrev_i32_e32 v73, 31, v72
	s_cbranch_vccnz .LBB0_1133
	s_waitcnt lgkmcnt(0)
	v_mov_b32_e32 v68, v202
	v_mov_b32_e32 v69, v203
	v_mov_b32_e32 v70, v204
	v_mov_b32_e32 v71, v205
	v_mov_b32_e32 v64, v206
	v_mov_b32_e32 v65, v207
	v_mov_b32_e32 v66, v208
	v_mov_b32_e32 v67, v209
	s_branch .LBB0_1134

;     __device__ __forceinline__ void operator()(EPI_ARGS) const {
;     ...
;             for (int m = 0; m < 4; ++m) { const int row = row0 + ai * HALF + m * 16;
;                 f32x4 c4 = (f32x4){1.f, 1.f, 1.f, 1.f}, s4 = (f32x4){0.f, 0.f, 0.f, 0.f};
;                 if (rot) { c4 = *(const f32x4*)(cs + (size_t)row * 64 + fi); s4 = *(const f32x4*)(sn + (size_t)row * 64 + fi); }
.LBB0_1142:
	v_add_u32_e32 v56, 0x90, v160
	s_and_b64 vcc, exec, s[8:9]
	v_ashrrev_i32_e32 v57, 31, v56
	s_cbranch_vccnz .LBB0_1144
	s_waitcnt lgkmcnt(0)
	v_mov_b32_e32 v52, v210
	v_mov_b32_e32 v53, v211
	v_mov_b32_e32 v54, v212
	v_mov_b32_e32 v55, v213
	v_mov_b32_e32 v48, v214
	v_mov_b32_e32 v49, v215
	v_mov_b32_e32 v50, v216
	v_mov_b32_e32 v51, v217
	s_branch .LBB0_1145

;     __device__ __forceinline__ void operator()(EPI_ARGS) const {
;     ...
;             for (int m = 0; m < 4; ++m) { const int row = row0 + ai * HALF + m * 16;
;                 f32x4 c4 = (f32x4){1.f, 1.f, 1.f, 1.f}, s4 = (f32x4){0.f, 0.f, 0.f, 0.f};
;                 if (rot) { c4 = *(const f32x4*)(cs + (size_t)row * 64 + fi); s4 = *(const f32x4*)(sn + (size_t)row * 64 + fi); }
.LBB0_1153:
	v_add_u32_e32 v40, 0xa0, v160
	s_and_b64 vcc, exec, s[8:9]
	v_ashrrev_i32_e32 v41, 31, v40
	s_cbranch_vccnz .LBB0_1155
	s_waitcnt lgkmcnt(0)
	v_mov_b32_e32 v36, v218
	v_mov_b32_e32 v37, v219
	v_mov_b32_e32 v38, v220
	v_mov_b32_e32 v39, v221
	v_mov_b32_e32 v32, v222
	v_mov_b32_e32 v33, v223
	v_mov_b32_e32 v34, v224
	v_mov_b32_e32 v35, v225
	s_branch .LBB0_1156

;     __device__ __forceinline__ void operator()(EPI_ARGS) const {
;     ...
;             for (int m = 0; m < 4; ++m) { const int row = row0 + ai * HALF + m * 16;
;                 f32x4 c4 = (f32x4){1.f, 1.f, 1.f, 1.f}, s4 = (f32x4){0.f, 0.f, 0.f, 0.f};
;                 if (rot) { c4 = *(const f32x4*)(cs + (size_t)row * 64 + fi); s4 = *(const f32x4*)(sn + (size_t)row * 64 + fi); }
.LBB0_1164:
	v_add_u32_e32 v24, 0xb0, v160
	s_and_b64 vcc, exec, s[8:9]
	v_ashrrev_i32_e32 v25, 31, v24
	s_cbranch_vccnz .LBB0_1166
	s_waitcnt lgkmcnt(0)
	v_mov_b32_e32 v20, v226
	v_mov_b32_e32 v21, v227
	v_mov_b32_e32 v22, v228
	v_mov_b32_e32 v23, v229
	v_mov_b32_e32 v16, v230
	v_mov_b32_e32 v17, v231
	v_mov_b32_e32 v18, v232
	v_mov_b32_e32 v19, v233
	s_branch .LBB0_1167

; __device__ __forceinline__ u32x4 pack8bf(const f32x4 a, const f32x4 b) { u32x4 w; w.x = cvt_pk_bf16(a[0], a[1]); w.y = cvt_pk_bf16(a[2], a[3]); w.z = cvt_pk_bf16(b[0], b[1]); w.w = cvt_pk_bf16(b[2], b[3]); return w; }
;     ...
;         if constexpr (QM == 2) { const float qs0_ = g.qs * E.qscale(cur), qs1_ = qs0_ * g.qs_b1; _Pragma("unroll") for (int a = 0; a < 2; ++a) _Pragma("unroll") for (int b = 0; b < 2; ++b) _Pragma("unroll") for (int m = 0; m < 4; ++m) _Pragma("unroll") for (int n = 0; n < 2; ++n) { const v4i t_ = __builtin_bit_cast(v4i, acc[a][b][m][n]); acc[a][b][m][n] = (f32x4){(float)t_[0], (float)t_[1], (float)t_[2], (float)t_[3]} * (b == 0 ? qs0_ : qs1_); } }
;     __device__ __forceinline__ void operator()(EPI_ARGS) const {
;         const int row0 = u.pm * BM + wr * 64 + fr, col0 = u.pn * HALF + wc * 32 + 8 * fq, n0 = u.pn * BM + wc * 32 + 8 * fq;
;         f32x4 cg[2], dg[2], cu[2], du[2];
;         if constexpr (FOLD) {
; #pragma unroll
;             for (int n = 0; n < 2; ++n) { cg[n] = *(const f32x4*)(C + n0 + 4 * n); dg[n] = *(const f32x4*)(D + n0 + 4 * n); cu[n] = *(const f32x4*)(C + n0 + HALF + 4 * n); du[n] = *(const f32x4*)(D + n0 + HALF + 4 * n);
;                 if constexpr (PRE) { float os_ = oscale; asm volatile("" : "+s"(os_)); cu[n] = cu[n] * os_; du[n] = du[n] * os_; } } }
; #pragma unroll
;         for (int ai = 0; ai < 2; ++ai)
; #pragma unroll
;             for (int m = 0; m < 4; ++m) { const int row = row0 + ai * HALF + m * 16; f32x4 r[2];
;                 float mu = 0.f, rs = 1.f; if constexpr (FOLD) ln_stats(st, row, mu, rs);
; #pragma unroll
;                 for (int n = 0; n < 2; ++n) { f32x4 g = acc[ai][0][m][n], up = acc[ai][1][m][n];
;                     if constexpr (!PRE) { g = g * ascale; up = up * ascale; }
;                     if constexpr (FOLD) { g = (g - cg[n] * mu) * rs + dg[n]; up = (up - cu[n] * mu) * rs + du[n]; }
;                     if constexpr (!PRE) up = up * oscale;
; #pragma unroll
;                     for (int j = 0; j < 4; ++j) { const float e = __builtin_amdgcn_exp2f(g[j] * -1.4426950408889634f); r[n][j] = g[j] * __builtin_amdgcn_rcpf(1.0f + e) * up[j]; } }
;                 if constexpr (F8OUT) *(u32x2*)((unsigned char*)O + (size_t)row * ldc + col0) = pack8fp8(r[0], r[1]);
;                 else *(u32x4*)((bf16_t*)O + (size_t)row * ldc + col0) = pack8bf(r[0], r[1]); }
.LBB0_3779:
	v_lshl_or_b32 v84, s5, 8, v168
	v_lshl_add_u32 v160, s4, 8, v166
	v_ashrrev_i32_e32 v85, 31, v84
	v_lshlrev_b64 v[84:85], 2, v[84:85]
	v_ashrrev_i32_e32 v161, 31, v160
	v_lshl_add_u64 v[88:89], s[8:9], 0, v[84:85]
	v_lshl_add_u64 v[182:183], s[10:11], 0, v[84:85]
	s_mov_b32 s4, 0x41800000
	s_mov_b32 s40, 0x41800000
	v_lshl_add_u64 v[186:187], v[160:161], 3, s[14:15]
	global_load_dwordx4 v[96:99], v[88:89], off
	global_load_dwordx4 v[162:165], v[88:89], off offset:512
	global_load_dwordx4 v[100:103], v[182:183], off
	global_load_dwordx4 v[174:177], v[182:183], off offset:512
	global_load_dwordx4 v[84:87], v[88:89], off offset:16
	global_load_dwordx4 v[178:181], v[88:89], off offset:528
	s_nop 0
	global_load_dwordx4 v[88:91], v[182:183], off offset:16
	s_nop 0
	global_load_dwordx4 v[182:185], v[182:183], off offset:528
	global_load_dwordx2 v[226:227], v[186:187], off offset:128
	global_load_dwordx2 v[228:229], v[186:187], off offset:256
	global_load_dwordx2 v[230:231], v[186:187], off offset:384
	global_load_dwordx2 v[232:233], v[186:187], off offset:1024
	global_load_dwordx2 v[234:235], v[186:187], off offset:1152
	global_load_dwordx2 v[236:237], v[186:187], off offset:1280
	global_load_dwordx2 v[238:239], v[186:187], off offset:1408
	global_load_dwordx2 v[186:187], v[186:187], off
	v_cvt_f32_i32_e32 v131, v131
	v_cvt_f32_i32_e32 v130, v130
	v_cvt_f32_i32_e32 v137, v137
	v_cvt_f32_i32_e32 v136, v136
	v_cvt_f32_i32_e32 v141, v141
	v_mul_f32_e32 v194, s24, v130
	v_mul_f32_e32 v195, s24, v131
	v_cvt_f32_i32_e32 v140, v140
	v_cvt_f32_i32_e32 v133, v133
	v_cvt_f32_i32_e32 v132, v132
	v_mul_f32_e32 v192, s20, v136
	v_mul_f32_e32 v193, s20, v137
	v_cvt_f32_i32_e32 v139, v139
	v_cvt_f32_i32_e32 v138, v138
	v_cvt_f32_i32_e32 v135, v135
	v_cvt_f32_i32_e32 v134, v134
	v_mul_f32_e32 v140, s20, v140
	v_mul_f32_e32 v141, s20, v141
	v_mul_f32_e32 v132, s24, v132
	v_mul_f32_e32 v133, s24, v133
	v_mul_f32_e32 v190, s20, v138
	v_mul_f32_e32 v191, s20, v139
	v_mul_f32_e32 v134, s24, v134
	v_mul_f32_e32 v135, s24, v135
	v_mov_b32_e32 v138, v132
	v_mov_b32_e32 v139, v140
	v_mov_b32_e32 v140, v133
	v_cvt_f32_i32_e32 v188, v128
	v_lshl_or_b32 v128, s5, 7, v168
	v_mov_b32_e32 v196, v134
	v_cvt_f32_i32_e32 v143, v143
	v_cvt_f32_i32_e32 v142, v142
	v_cvt_f32_i32_e32 v189, v129
	v_ashrrev_i32_e32 v129, 31, v128
	v_cvt_f32_i32_e32 v125, v125
	v_mul_f32_e32 v142, s20, v142
	v_mul_f32_e32 v143, s20, v143
	v_mul_f32_e32 v188, s24, v188
	v_mul_f32_e32 v189, s24, v189
	v_mov_b32_e32 v197, v142
	v_mov_b32_e32 v142, v135
	v_cvt_f32_i32_e32 v124, v124
	v_cvt_f32_i32_e32 v117, v117
	v_cvt_f32_i32_e32 v116, v116
	v_cvt_f32_i32_e32 v127, v127
	v_mul_f32_e32 v124, s20, v124
	v_mul_f32_e32 v125, s20, v125
	v_cvt_f32_i32_e32 v126, v126
	v_mul_f32_e32 v116, s24, v116
	v_mul_f32_e32 v117, s24, v117
	v_cvt_f32_i32_e32 v119, v119
	v_cvt_f32_i32_e32 v118, v118
	v_mul_f32_e32 v126, s20, v126
	v_mul_f32_e32 v127, s20, v127
	v_cvt_f32_i32_e32 v121, v121
	v_cvt_f32_i32_e32 v120, v120
	v_mul_f32_e32 v118, s24, v118
	v_mul_f32_e32 v119, s24, v119
	v_cvt_f32_i32_e32 v113, v113
	v_cvt_f32_i32_e32 v112, v112
	v_mul_f32_e32 v120, s20, v120
	v_mul_f32_e32 v121, s20, v121
	v_cvt_f32_i32_e32 v123, v123
	v_cvt_f32_i32_e32 v122, v122
	v_mul_f32_e32 v112, s24, v112
	v_mul_f32_e32 v113, s24, v113
	v_cvt_f32_i32_e32 v115, v115
	v_cvt_f32_i32_e32 v114, v114
	v_mul_f32_e32 v122, s20, v122
	v_mul_f32_e32 v123, s20, v123
	v_cvt_f32_i32_e32 v109, v109
	v_cvt_f32_i32_e32 v108, v108
	v_mul_f32_e32 v114, s24, v114
	v_mul_f32_e32 v115, s24, v115
	v_cvt_f32_i32_e32 v93, v93
	v_cvt_f32_i32_e32 v92, v92
	v_mul_f32_e32 v108, s20, v108
	v_mul_f32_e32 v109, s20, v109
	v_cvt_f32_i32_e32 v111, v111
	v_cvt_f32_i32_e32 v110, v110
	v_mul_f32_e32 v92, s24, v92
	v_mul_f32_e32 v93, s24, v93
	v_cvt_f32_i32_e32 v95, v95
	v_cvt_f32_i32_e32 v94, v94
	v_mul_f32_e32 v110, s20, v110
	v_mul_f32_e32 v111, s20, v111
	v_cvt_f32_i32_e32 v105, v105
	v_cvt_f32_i32_e32 v104, v104
	v_mul_f32_e32 v94, s24, v94
	v_mul_f32_e32 v95, s24, v95
	v_cvt_f32_i32_e32 v81, v81
	v_cvt_f32_i32_e32 v80, v80
	s_waitcnt vmcnt(0)
	v_mov_b32_e32 v137, v96
	v_mul_f32_e32 v162, s4, v162
	v_mul_f32_e32 v163, s4, v163
	v_mov_b32_e32 v131, v102
	v_mov_b32_e32 v136, v162
	v_mul_f32_e32 v164, s4, v164
	v_mul_f32_e32 v165, s4, v165
	v_mov_b32_e32 v96, v163
	v_mul_f32_e32 v174, s4, v174
	v_mul_f32_e32 v175, s4, v175
	v_mul_f32_e32 v186, s26, v186
	v_mul_f32_e32 v187, s26, v187
	v_mov_b32_e32 v133, v98
	v_fma_f32 v102, -v186, v186, v187
	v_add_f32_e32 v102, 0x3727c5ac, v102
	v_rsq_f32_e32 v242, v102
	v_mov_b32_e32 v132, v164
	v_mov_b32_e32 v98, v165
	v_mul_f32_e32 v176, s4, v176
	v_mul_f32_e32 v177, s4, v177
	v_mov_b32_e32 v134, v174
	v_mov_b32_e32 v135, v100
	v_mov_b32_e32 v100, v175
	v_mov_b32_e32 v130, v176
	v_fma_f32 v138, -v136, v186, v138
	v_fma_f32 v139, -v137, v186, v139
	v_fma_f32 v140, -v96, v186, v140
	v_fma_f32 v141, -v97, v186, v141
	v_mov_b32_e32 v102, v177
	v_fma_f32 v142, -v98, v186, v142
	v_fma_f32 v143, -v99, v186, v143
	v_fma_f32 v162, -v132, v186, v196
	v_fma_f32 v163, -v133, v186, v197
	v_fma_f32 v138,v138,v242,v134
	v_fma_f32 v139,v139,v242,v135
	v_fma_f32 v140,v140,v242,v100
	v_fma_f32 v141,v141,v242,v101
	v_mul_f32_e32 v161, 0xbfb8aa3b, v139
	v_mul_f32_e32 v165, 0xbfb8aa3b, v141
	v_exp_f32_e32 v161, v161
	v_exp_f32_e32 v165, v165
	v_mul_f32_e32 v178, s40, v178
	v_mul_f32_e32 v179, s40, v179
	v_mul_f32_e32 v182, s40, v182
	v_mul_f32_e32 v183, s40, v183
	v_add_f32_e32 v161, 1.0, v161
	v_fma_f32 v162,v162,v242,v130
	v_fma_f32 v163,v163,v242,v131
	v_add_f32_e32 v165, 1.0, v165
	v_rcp_f32_e32 v161, v161
	v_rcp_f32_e32 v165, v165
; __device__ __forceinline__ u32x4 pack8bf(const f32x4 a, const f32x4 b) { u32x4 w; w.x = cvt_pk_bf16(a[0], a[1]); w.y = cvt_pk_bf16(a[2], a[3]); w.z = cvt_pk_bf16(b[0], b[1]); w.w = cvt_pk_bf16(b[2], b[3]); return w; }
;     __device__ __forceinline__ float qscale(const Unit& u) const { return ((u.pn >= 8 && u.pn <= 11) || u.pn == 17) ? 0.5f : 1.0f; }
; __device__ __forceinline__ void ln_stats(const float* st, int row, float& mu, float& rs) { const f32x2 s = *(const f32x2*)(st + 2 * (size_t)row); mu = s[0] * (1.0f / DM); rs = 1.0f / sqrtf(s[1] * (1.0f / DM) - mu * mu + LN_EPS); }
;     ...
;         if constexpr (QM == 2) { const float qs0_ = g.qs * E.qscale(cur), qs1_ = qs0_ * g.qs_b1; _Pragma("unroll") for (int a = 0; a < 2; ++a) _Pragma("unroll") for (int b = 0; b < 2; ++b) _Pragma("unroll") for (int m = 0; m < 4; ++m) _Pragma("unroll") for (int n = 0; n < 2; ++n) { const v4i t_ = __builtin_bit_cast(v4i, acc[a][b][m][n]); acc[a][b][m][n] = (f32x4){(float)t_[0], (float)t_[1], (float)t_[2], (float)t_[3]} * (b == 0 ? qs0_ : qs1_); } }
;     __device__ __forceinline__ void operator()(EPI_ARGS) const {
;     ...
;         for (int ai = 0; ai < 2; ++ai)
; #pragma unroll
;             for (int m = 0; m < 4; ++m) { const int row = row0 + ai * HALF + m * 16; f32x4 r[2];
;                 float mu = 0.f, rs = 1.f; if constexpr (FOLD) ln_stats(st, row, mu, rs);
; #pragma unroll
;                 for (int n = 0; n < 2; ++n) { f32x4 g = acc[ai][0][m][n], up = acc[ai][1][m][n];
;                     if constexpr (!PRE) { g = g * ascale; up = up * ascale; }
;                     if constexpr (FOLD) { g = (g - cg[n] * mu) * rs + dg[n]; up = (up - cu[n] * mu) * rs + du[n]; }
;                     if constexpr (!PRE) up = up * oscale;
; #pragma unroll
;                     for (int j = 0; j < 4; ++j) { const float e = __builtin_amdgcn_exp2f(g[j] * -1.4426950408889634f); r[n][j] = g[j] * __builtin_amdgcn_rcpf(1.0f + e) * up[j]; } }
;                 if constexpr (F8OUT) *(u32x2*)((unsigned char*)O + (size_t)row * ldc + col0) = pack8fp8(r[0], r[1]);
;                 else *(u32x4*)((bf16_t*)O + (size_t)row * ldc + col0) = pack8bf(r[0], r[1]); }
	v_mul_f32_e32 v174, 0xbfb8aa3b, v163
	v_exp_f32_e32 v174, v174
	v_mul_f32_e32 v139, v139, v161
	v_fma_f32 v142,v142,v242,v102
	v_fma_f32 v143,v143,v242,v103
	v_mul_f32_e32 v161, v138, v139
	v_mul_f32_e32 v138, 0xbfb8aa3b, v143
	v_exp_f32_e32 v138, v138
	v_add_f32_e32 v139, 1.0, v174
	v_mul_f32_e32 v141, v141, v165
	v_rcp_f32_e32 v165, v139
	v_add_f32_e32 v138, 1.0, v138
	v_mul_f32_e32 v196, v140, v141
	v_rcp_f32_e32 v176, v138
	v_mov_b32_e32 v138, v178
	v_mov_b32_e32 v139, v84
	v_fma_f32 v174,-v186,v138,v188
	v_fma_f32 v175,-v186,v139,v192
	v_mov_b32_e32 v140, v182
	v_mov_b32_e32 v141, v88
	v_fma_f32 v174,v174,v242,v140
	v_fma_f32 v175,v175,v242,v141
	v_mul_f32_e32 v88, v163, v165
	v_mul_f32_e32 v84, 0xbfb8aa3b, v175
	v_exp_f32_e32 v84, v84
	v_mov_b32_e32 v192, v189
	v_mul_f32_e32 v182, v162, v88
	v_mov_b32_e32 v88, v183
	v_add_f32_e32 v84, 1.0, v84
	v_rcp_f32_e32 v165, v84
	v_mov_b32_e32 v84, v179
	v_fma_f32 v162, -v186, v84, v192
	v_fma_f32 v163, -v186, v85, v193
	v_mul_f32_e32 v143, v143, v176
	v_fma_f32 v176,v162,v242,v88
	v_fma_f32 v177,v163,v242,v89
	v_mul_f32_e32 v183, v142, v143
	v_mul_f32_e32 v162, 0xbfb8aa3b, v177
	v_exp_f32_e32 v162, v162
	v_mul_f32_e32 v142, v175, v165
	v_mul_f32_e32 v180, s40, v180
	v_mul_f32_e32 v181, s40, v181
	v_mul_f32_e32 v188, v174, v142
	v_add_f32_e32 v142, 1.0, v162
	v_mul_f32_e32 v184, s40, v184
	v_mul_f32_e32 v185, s40, v185
	v_rcp_f32_e32 v189, v142
	v_mov_b32_e32 v142, v180
	v_mov_b32_e32 v143, v86
	v_fma_f32 v174,-v186,v142,v194
	v_fma_f32 v175,-v186,v143,v190
	v_mov_b32_e32 v162, v184
	v_mov_b32_e32 v163, v90
	v_fma_f32 v174,v174,v242,v162
	v_fma_f32 v175,v175,v242,v163
	v_mov_b32_e32 v190, v195
	v_mul_f32_e32 v86, 0xbfb8aa3b, v175
	v_exp_f32_e32 v180, v86
	v_mov_b32_e32 v86, v181
	v_fma_f32 v178, -v186, v86, v190
	v_fma_f32 v179, -v186, v87, v191
	v_mov_b32_e32 v90, v185
	v_fma_f32 v165,v179,v242,v91
	v_fma_f32 v164,v178,v242,v90
	v_add_f32_e32 v179, 1.0, v180
	v_mul_f32_e32 v178, 0xbfb8aa3b, v165
	v_exp_f32_e32 v178, v178
	v_rcp_f32_e32 v179, v179
	v_mul_f32_e32 v177, v177, v189
	v_mul_f32_e32 v176, v176, v177
	v_add_f32_e32 v178, 1.0, v178
	v_rcp_f32_e32 v178, v178
	v_mul_f32_e32 v175, v175, v179
	v_mul_f32_e32 v177, v174, v175
	v_med3_f32 v161, v161, s62, v173
	v_mul_f32_e32 v165, v165, v178
	v_mul_f32_e32 v164, v164, v165
	v_med3_f32 v165, v196, s62, v173
	v_cvt_pk_fp8_f32 v174, v161, v165
	v_med3_f32 v178, v188, s62, v173
	v_med3_f32 v176, v176, s62, v173
	v_cvt_pk_fp8_f32 v175, v178, v176
	v_med3_f32 v161, v182, s62, v173
	v_med3_f32 v165, v183, s62, v173
	v_cvt_pk_fp8_f32 v174, v161, v165 op_sel:[0,0,1]
	v_med3_f32 v161, v177, s62, v173
	v_med3_f32 v164, v164, s62, v173
	v_cvt_pk_fp8_f32 v175, v161, v164 op_sel:[0,0,1]
	v_mov_b64_e32 v[164:165], s[12:13]
	v_mad_i64_i32 v[176:177], s[4:5], v160, s63, v[164:165]
	v_lshl_add_u64 v[176:177], v[176:177], 0, v[128:129]
	global_store_dwordx2 v[176:177], v[174:175], off
	v_or_b32_e32 v174, 16, v160
	v_mul_f32_e32 v104, s20, v104
	v_mul_f32_e32 v105, s20, v105
	v_mul_f32_e32 v80, s24, v80
	v_mul_f32_e32 v81, s24, v81
	v_cvt_f32_i32_e32 v107, v107
	v_cvt_f32_i32_e32 v106, v106
	v_cvt_f32_i32_e32 v83, v83
	v_cvt_f32_i32_e32 v82, v82
	v_cvt_f32_i32_e32 v77, v77
	v_mul_f32_e32 v106, s20, v106
	v_mul_f32_e32 v107, s20, v107
	v_cvt_f32_i32_e32 v76, v76
	v_mul_f32_e32 v82, s24, v82
	v_mul_f32_e32 v83, s24, v83
	v_cvt_f32_i32_e32 v69, v69
	v_cvt_f32_i32_e32 v68, v68
	v_mul_f32_e32 v76, s20, v76
	v_mul_f32_e32 v77, s20, v77
	v_cvt_f32_i32_e32 v79, v79
	v_cvt_f32_i32_e32 v78, v78
	v_mul_f32_e32 v68, s24, v68
	v_mul_f32_e32 v69, s24, v69
	v_cvt_f32_i32_e32 v71, v71
	v_cvt_f32_i32_e32 v70, v70
	v_mul_f32_e32 v78, s20, v78
	v_mul_f32_e32 v79, s20, v79
	v_cvt_f32_i32_e32 v73, v73
	v_cvt_f32_i32_e32 v72, v72
	v_mul_f32_e32 v70, s24, v70
	v_mul_f32_e32 v71, s24, v71
	v_cvt_f32_i32_e32 v65, v65
	v_cvt_f32_i32_e32 v64, v64
	v_mul_f32_e32 v72, s20, v72
	v_mul_f32_e32 v73, s20, v73
	v_cvt_f32_i32_e32 v75, v75
	v_cvt_f32_i32_e32 v74, v74
	v_mul_f32_e32 v64, s24, v64
	v_mul_f32_e32 v65, s24, v65
	v_cvt_f32_i32_e32 v67, v67
	v_cvt_f32_i32_e32 v66, v66
	v_mul_f32_e32 v74, s20, v74
	v_mul_f32_e32 v75, s20, v75
	v_cvt_f32_i32_e32 v61, v61
	v_cvt_f32_i32_e32 v60, v60
	v_mul_f32_e32 v66, s24, v66
	v_mul_f32_e32 v67, s24, v67
	v_cvt_f32_i32_e32 v53, v53
	v_cvt_f32_i32_e32 v52, v52
	v_mul_f32_e32 v60, s20, v60
	v_mul_f32_e32 v61, s20, v61
	v_cvt_f32_i32_e32 v63, v63
	v_cvt_f32_i32_e32 v62, v62
	v_mul_f32_e32 v52, s24, v52
	v_mul_f32_e32 v53, s24, v53
	v_cvt_f32_i32_e32 v55, v55
	v_cvt_f32_i32_e32 v54, v54
	v_mul_f32_e32 v62, s20, v62
	v_mul_f32_e32 v63, s20, v63
	v_cvt_f32_i32_e32 v57, v57
	v_cvt_f32_i32_e32 v56, v56
	v_mul_f32_e32 v54, s24, v54
	v_mul_f32_e32 v55, s24, v55
	v_cvt_f32_i32_e32 v49, v49
	v_cvt_f32_i32_e32 v48, v48
	v_mul_f32_e32 v56, s20, v56
	v_mul_f32_e32 v57, s20, v57
	v_cvt_f32_i32_e32 v59, v59
	v_cvt_f32_i32_e32 v58, v58
	v_mul_f32_e32 v48, s24, v48
	v_mul_f32_e32 v49, s24, v49
	v_cvt_f32_i32_e32 v51, v51
	v_cvt_f32_i32_e32 v50, v50
	v_mul_f32_e32 v58, s20, v58
	v_mul_f32_e32 v59, s20, v59
	v_cvt_f32_i32_e32 v45, v45
	v_cvt_f32_i32_e32 v44, v44
	v_mul_f32_e32 v50, s24, v50
	v_mul_f32_e32 v51, s24, v51
	v_cvt_f32_i32_e32 v37, v37
	v_cvt_f32_i32_e32 v36, v36
	v_mul_f32_e32 v44, s20, v44
	v_mul_f32_e32 v45, s20, v45
	v_cvt_f32_i32_e32 v47, v47
	v_cvt_f32_i32_e32 v46, v46
	v_mul_f32_e32 v36, s24, v36
	v_mul_f32_e32 v37, s24, v37
	v_cvt_f32_i32_e32 v39, v39
	v_cvt_f32_i32_e32 v38, v38
	v_mul_f32_e32 v46, s20, v46
	v_mul_f32_e32 v47, s20, v47
	v_cvt_f32_i32_e32 v41, v41
	v_cvt_f32_i32_e32 v40, v40
	v_mul_f32_e32 v38, s24, v38
	v_mul_f32_e32 v39, s24, v39
; __device__ __forceinline__ u32x4 pack8bf(const f32x4 a, const f32x4 b) { u32x4 w; w.x = cvt_pk_bf16(a[0], a[1]); w.y = cvt_pk_bf16(a[2], a[3]); w.z = cvt_pk_bf16(b[0], b[1]); w.w = cvt_pk_bf16(b[2], b[3]); return w; }
;     __device__ __forceinline__ float qscale(const Unit& u) const { return ((u.pn >= 8 && u.pn <= 11) || u.pn == 17) ? 0.5f : 1.0f; }
; __device__ __forceinline__ void ln_stats(const float* st, int row, float& mu, float& rs) { const f32x2 s = *(const f32x2*)(st + 2 * (size_t)row); mu = s[0] * (1.0f / DM); rs = 1.0f / sqrtf(s[1] * (1.0f / DM) - mu * mu + LN_EPS); }
;     ...
;         if constexpr (QM == 2) { const float qs0_ = g.qs * E.qscale(cur), qs1_ = qs0_ * g.qs_b1; _Pragma("unroll") for (int a = 0; a < 2; ++a) _Pragma("unroll") for (int b = 0; b < 2; ++b) _Pragma("unroll") for (int m = 0; m < 4; ++m) _Pragma("unroll") for (int n = 0; n < 2; ++n) { const v4i t_ = __builtin_bit_cast(v4i, acc[a][b][m][n]); acc[a][b][m][n] = (f32x4){(float)t_[0], (float)t_[1], (float)t_[2], (float)t_[3]} * (b == 0 ? qs0_ : qs1_); } }
;     __device__ __forceinline__ void operator()(EPI_ARGS) const {
;     ...
; #pragma unroll
;         for (int ai = 0; ai < 2; ++ai)
; #pragma unroll
;             for (int m = 0; m < 4; ++m) { const int row = row0 + ai * HALF + m * 16; f32x4 r[2];
;                 float mu = 0.f, rs = 1.f; if constexpr (FOLD) ln_stats(st, row, mu, rs);
; #pragma unroll
;                 for (int n = 0; n < 2; ++n) { f32x4 g = acc[ai][0][m][n], up = acc[ai][1][m][n];
;                     if constexpr (!PRE) { g = g * ascale; up = up * ascale; }
;                     if constexpr (FOLD) { g = (g - cg[n] * mu) * rs + dg[n]; up = (up - cu[n] * mu) * rs + du[n]; }
;                     if constexpr (!PRE) up = up * oscale;
; #pragma unroll
;                     for (int j = 0; j < 4; ++j) { const float e = __builtin_amdgcn_exp2f(g[j] * -1.4426950408889634f); r[n][j] = g[j] * __builtin_amdgcn_rcpf(1.0f + e) * up[j]; } }
;                 if constexpr (F8OUT) *(u32x2*)((unsigned char*)O + (size_t)row * ldc + col0) = pack8fp8(r[0], r[1]);
;                 else *(u32x4*)((bf16_t*)O + (size_t)row * ldc + col0) = pack8bf(r[0], r[1]); }
	v_cvt_f32_i32_e32 v33, v33
	v_cvt_f32_i32_e32 v32, v32
	v_mul_f32_e32 v40, s20, v40
	v_mul_f32_e32 v41, s20, v41
	v_cvt_f32_i32_e32 v43, v43
	v_cvt_f32_i32_e32 v42, v42
	v_mul_f32_e32 v32, s24, v32
	v_mul_f32_e32 v33, s24, v33
	v_cvt_f32_i32_e32 v35, v35
	v_cvt_f32_i32_e32 v34, v34
	v_mul_f32_e32 v42, s20, v42
	v_mul_f32_e32 v43, s20, v43
	v_mul_f32_e32 v176,s26,v226
	v_mul_f32_e32 v177,s26,v227
	v_cvt_f32_i32_e32 v29, v29
	v_fma_f32 v161, -v176, v176, v177
	v_add_f32_e32 v161, 0x3727c5ac, v161
	v_rsq_f32_e32 v242, v161
	v_mul_f32_e32 v34, s24, v34
	v_mul_f32_e32 v35, s24, v35
	v_cvt_f32_i32_e32 v28, v28
	v_cvt_f32_i32_e32 v21, v21
	v_cvt_f32_i32_e32 v20, v20
	v_mul_f32_e32 v28, s20, v28
	v_mul_f32_e32 v29, s20, v29
	v_mul_f32_e32 v20, s24, v20
	v_mul_f32_e32 v21, s24, v21
	v_cvt_f32_i32_e32 v31, v31
	v_cvt_f32_i32_e32 v30, v30
	v_cvt_f32_i32_e32 v23, v23
	v_cvt_f32_i32_e32 v22, v22
	v_mul_f32_e32 v30, s20, v30
	v_mul_f32_e32 v31, s20, v31
	v_mul_f32_e32 v22, s24, v22
	v_mul_f32_e32 v23, s24, v23
	v_cvt_f32_i32_e32 v25, v25
	v_mov_b32_e32 v178, v242
	v_fma_f32 v180,-v136,v176,v116
	v_fma_f32 v181,-v137,v176,v124
	v_fma_f32 v180, v180, v178, v134
	v_fma_f32 v181, v181, v178, v135
	v_cvt_f32_i32_e32 v24, v24
	v_mul_f32_e32 v116, 0xbfb8aa3b, v181
	v_exp_f32_e32 v161, v116
	v_fma_f32 v116,-v96,v176,v117
	v_fma_f32 v117, -v97, v176, v125
	v_cvt_f32_i32_e32 v17, v17
	v_fma_f32 v116, v116, v178, v100
	v_fma_f32 v117, v117, v178, v101
	v_add_f32_e32 v125, 1.0, v161
	v_mul_f32_e32 v124, 0xbfb8aa3b, v117
	v_exp_f32_e32 v124, v124
	v_rcp_f32_e32 v125, v125
	v_cvt_f32_i32_e32 v16, v16
	v_mul_f32_e32 v24, s20, v24
	v_mul_f32_e32 v25, s20, v25
	v_add_f32_e32 v124, 1.0, v124
	v_rcp_f32_e32 v124, v124
	v_mul_f32_e32 v125, v181, v125
	v_mul_f32_e32 v161, v180, v125
	v_mul_f32_e32 v117, v117, v124
	v_fma_f32 v124,-v132,v176,v118
	v_fma_f32 v125,-v133,v176,v126
	v_fma_f32 v124, v124, v178, v130
	v_fma_f32 v125, v125, v178, v131
	v_mul_f32_e32 v16, s24, v16
	v_mul_f32_e32 v17, s24, v17
	v_mul_f32_e32 v118, 0xbfb8aa3b, v125
	v_exp_f32_e32 v175, v118
	v_fma_f32 v118,-v98,v176,v119
	v_fma_f32 v119, -v99, v176, v127
	v_mul_f32_e32 v127, v116, v117
	v_fma_f32 v118, v118, v178, v102
	v_fma_f32 v119, v119, v178, v103
	v_add_f32_e32 v116, 1.0, v175
	v_mul_f32_e32 v126, 0xbfb8aa3b, v119
	v_exp_f32_e32 v126, v126
	v_rcp_f32_e32 v175, v116
	v_cvt_f32_i32_e32 v27, v27
	v_add_f32_e32 v116, 1.0, v126
	v_rcp_f32_e32 v126, v116
	v_fma_f32 v116,-v138,v176,v112
	v_fma_f32 v117,-v139,v176,v120
	v_mul_f32_e32 v120, v125, v175
	v_fma_f32 v116, v116, v178, v140
	v_fma_f32 v117, v117, v178, v141
	v_mul_f32_e32 v124, v124, v120
	v_mul_f32_e32 v112, 0xbfb8aa3b, v117
	v_exp_f32_e32 v112, v112
	v_mul_f32_e32 v119, v119, v126
	v_mul_f32_e32 v118, v118, v119
	v_add_f32_e32 v112, 1.0, v112
	v_rcp_f32_e32 v125, v112
	v_fma_f32 v112,-v84,v176,v113
	v_fma_f32 v113, -v85, v176, v121
	v_cvt_f32_i32_e32 v26, v26
	v_fma_f32 v112, v112, v178, v88
	v_fma_f32 v113, v113, v178, v89
	v_mul_f32_e32 v117, v117, v125
	v_mul_f32_e32 v120, 0xbfb8aa3b, v113
	v_exp_f32_e32 v120, v120
	v_mul_f32_e32 v119, v116, v117
	v_mov_b32_e32 v117, v122
	v_add_f32_e32 v116, 1.0, v120
	v_rcp_f32_e32 v120, v116
	v_fma_f32 v116,-v142,v176,v114
	v_fma_f32 v117, -v143, v176, v117
	v_cvt_f32_i32_e32 v19, v19
	v_fma_f32 v116, v116, v178, v162
	v_fma_f32 v117, v117, v178, v163
	v_mul_f32_e32 v113, v113, v120
	v_mul_f32_e32 v114, 0xbfb8aa3b, v117
	v_exp_f32_e32 v121, v114
	v_fma_f32 v114,-v86,v176,v115
	v_fma_f32 v115, -v87, v176, v123
	v_mul_f32_e32 v113, v112, v113
	v_fma_f32 v114, v114, v178, v90
	v_fma_f32 v115, v115, v178, v91
	v_add_f32_e32 v120, 1.0, v121
	v_mul_f32_e32 v122, 0xbfb8aa3b, v115
	v_exp_f32_e32 v122, v122
	v_rcp_f32_e32 v120, v120
	v_cvt_f32_i32_e32 v18, v18
	v_mul_f32_e32 v26, s20, v26
	v_mul_f32_e32 v27, s20, v27
	v_add_f32_e32 v121, 1.0, v122
	v_rcp_f32_e32 v121, v121
	v_mul_f32_e32 v112, v117, v120
	v_mul_f32_e32 v116, v116, v112
	v_med3_f32 v117, v127, s62, v173
	v_mul_f32_e32 v112, v115, v121
	v_mul_f32_e32 v114, v114, v112
	v_med3_f32 v115, v161, s62, v173
	v_cvt_pk_fp8_f32 v112, v115, v117
	v_med3_f32 v117, v118, s62, v173
	v_med3_f32 v118, v119, s62, v173
	v_med3_f32 v119, v113, s62, v173
	v_cvt_pk_fp8_f32 v113, v118, v119
	v_med3_f32 v115, v124, s62, v173
	v_cvt_pk_fp8_f32 v112, v115, v117 op_sel:[0,0,1]
	v_med3_f32 v115, v116, s62, v173
	v_med3_f32 v114, v114, s62, v173
	v_cvt_pk_fp8_f32 v113, v115, v114 op_sel:[0,0,1]
	v_mad_i64_i32 v[114:115], s[4:5], v174, s63, v[164:165]
	v_lshl_add_u64 v[114:115], v[114:115], 0, v[128:129]
	global_store_dwordx2 v[114:115], v[112:113], off
	v_or_b32_e32 v112, 32, v160
	v_mul_f32_e32 v18, s24, v18
	v_mul_f32_e32 v19, s24, v19
	v_cvt_f32_i32_e32 v13, v13
	v_cvt_f32_i32_e32 v12, v12
	v_cvt_f32_i32_e32 v5, v5
	v_cvt_f32_i32_e32 v4, v4
	v_cvt_f32_i32_e32 v15, v15
	v_mul_f32_e32 v12, s20, v12
	v_mul_f32_e32 v13, s20, v13
	v_cvt_f32_i32_e32 v14, v14
	v_mul_f32_e32 v4, s24, v4
	v_mul_f32_e32 v5, s24, v5
	v_cvt_f32_i32_e32 v7, v7
	v_cvt_f32_i32_e32 v6, v6
	v_mul_f32_e32 v14, s20, v14
	v_mul_f32_e32 v15, s20, v15
	v_cvt_f32_i32_e32 v9, v9
	v_cvt_f32_i32_e32 v8, v8
	v_mul_f32_e32 v6, s24, v6
	v_mul_f32_e32 v7, s24, v7
	v_cvt_f32_i32_e32 v1, v1
	v_cvt_f32_i32_e32 v0, v0
	v_mul_f32_e32 v8, s20, v8
	v_mul_f32_e32 v9, s20, v9
	v_cvt_f32_i32_e32 v11, v11
	v_cvt_f32_i32_e32 v10, v10
	v_mul_f32_e32 v0, s24, v0
	v_mul_f32_e32 v1, s24, v1
	v_cvt_f32_i32_e32 v3, v3
	v_cvt_f32_i32_e32 v2, v2
	v_mul_f32_e32 v10, s20, v10
	v_mul_f32_e32 v11, s20, v11
	v_mul_f32_e32 v2, s24, v2
	v_mul_f32_e32 v3, s24, v3
	v_mul_f32_e32 v114,s26,v228
	v_mul_f32_e32 v115,s26,v229
	s_nop 0
; __device__ __forceinline__ u32x4 pack8bf(const f32x4 a, const f32x4 b) { u32x4 w; w.x = cvt_pk_bf16(a[0], a[1]); w.y = cvt_pk_bf16(a[2], a[3]); w.z = cvt_pk_bf16(b[0], b[1]); w.w = cvt_pk_bf16(b[2], b[3]); return w; }
; __device__ __forceinline__ void ln_stats(const float* st, int row, float& mu, float& rs) { const f32x2 s = *(const f32x2*)(st + 2 * (size_t)row); mu = s[0] * (1.0f / DM); rs = 1.0f / sqrtf(s[1] * (1.0f / DM) - mu * mu + LN_EPS); }
;     __device__ __forceinline__ void operator()(EPI_ARGS) const {
;     ...
; #pragma unroll
;         for (int ai = 0; ai < 2; ++ai)
; #pragma unroll
;             for (int m = 0; m < 4; ++m) { const int row = row0 + ai * HALF + m * 16; f32x4 r[2];
;                 float mu = 0.f, rs = 1.f; if constexpr (FOLD) ln_stats(st, row, mu, rs);
; #pragma unroll
;                 for (int n = 0; n < 2; ++n) { f32x4 g = acc[ai][0][m][n], up = acc[ai][1][m][n];
;                     if constexpr (!PRE) { g = g * ascale; up = up * ascale; }
;                     if constexpr (FOLD) { g = (g - cg[n] * mu) * rs + dg[n]; up = (up - cu[n] * mu) * rs + du[n]; }
;                     if constexpr (!PRE) up = up * oscale;
; #pragma unroll
;                     for (int j = 0; j < 4; ++j) { const float e = __builtin_amdgcn_exp2f(g[j] * -1.4426950408889634f); r[n][j] = g[j] * __builtin_amdgcn_rcpf(1.0f + e) * up[j]; } }
;                 if constexpr (F8OUT) *(u32x2*)((unsigned char*)O + (size_t)row * ldc + col0) = pack8fp8(r[0], r[1]);
;                 else *(u32x4*)((bf16_t*)O + (size_t)row * ldc + col0) = pack8bf(r[0], r[1]); }
	v_fma_f32 v113, -v114, v114, v115
	v_add_f32_e32 v113, 0x3727c5ac, v113
	v_rsq_f32_e32 v242, v113
	s_nop 1
	s_nop 0
	s_nop 0
	s_nop 1
	s_nop 1
	s_nop 0
	v_mov_b32_e32 v116, v242
	v_fma_f32 v118,-v136,v114,v92
	v_fma_f32 v119,-v137,v114,v108
	v_fma_f32 v118, v118, v116, v134
	v_fma_f32 v119, v119, v116, v135
	s_nop 0
	v_mul_f32_e32 v92, 0xbfb8aa3b, v119
	v_exp_f32_e32 v113, v92
	v_fma_f32 v92,-v96,v114,v93
	v_fma_f32 v93, -v97, v114, v109
	v_add_f32_e32 v109, 1.0, v113
	v_fma_f32 v92, v92, v116, v100
	v_fma_f32 v93, v93, v116, v101
	v_rcp_f32_e32 v109, v109
	v_mul_f32_e32 v108, 0xbfb8aa3b, v93
	v_exp_f32_e32 v108, v108
	v_mul_f32_e32 v109, v119, v109
	v_mul_f32_e32 v113, v118, v109
	v_add_f32_e32 v108, 1.0, v108
	v_rcp_f32_e32 v108, v108
	v_mov_b32_e32 v109, v110
	v_mul_f32_e32 v93, v93, v108
	v_fma_f32 v108,-v132,v114,v94
	v_fma_f32 v109, -v133, v114, v109
	s_nop 0
	v_fma_f32 v108, v108, v116, v130
	v_fma_f32 v109, v109, v116, v131
	s_nop 0
	v_mul_f32_e32 v94, 0xbfb8aa3b, v109
	v_exp_f32_e32 v117, v94
	v_fma_f32 v94,-v98,v114,v95
	v_fma_f32 v95, -v99, v114, v111
	v_mul_f32_e32 v111, v92, v93
	v_fma_f32 v94, v94, v116, v102
	v_fma_f32 v95, v95, v116, v103
	v_add_f32_e32 v92, 1.0, v117
	v_mul_f32_e32 v110, 0xbfb8aa3b, v95
	v_exp_f32_e32 v110, v110
	v_rcp_f32_e32 v117, v92
	v_add_f32_e32 v92, 1.0, v110
	v_rcp_f32_e32 v110, v92
	v_fma_f32 v92,-v138,v114,v80
	v_fma_f32 v93,-v139,v114,v104
	v_mul_f32_e32 v104, v109, v117
	v_fma_f32 v92, v92, v116, v140
	v_fma_f32 v93, v93, v116, v141
	v_mul_f32_e32 v108, v108, v104
	v_mul_f32_e32 v80, 0xbfb8aa3b, v93
	v_exp_f32_e32 v80, v80
	v_mul_f32_e32 v95, v95, v110
	v_mul_f32_e32 v94, v94, v95
	v_add_f32_e32 v80, 1.0, v80
	v_rcp_f32_e32 v109, v80
	v_fma_f32 v80,-v84,v114,v81
	v_fma_f32 v81, -v85, v114, v105
	v_mul_f32_e32 v93, v93, v109
	v_fma_f32 v80, v80, v116, v88
	v_fma_f32 v81, v81, v116, v89
	v_mul_f32_e32 v95, v92, v93
	v_mul_f32_e32 v104, 0xbfb8aa3b, v81
	v_exp_f32_e32 v104, v104
	v_mov_b32_e32 v93, v106
	v_add_f32_e32 v92, 1.0, v104
	v_rcp_f32_e32 v104, v92
	v_fma_f32 v92,-v142,v114,v82
	v_fma_f32 v93, -v143, v114, v93
	v_mul_f32_e32 v81, v81, v104
	v_fma_f32 v92, v92, v116, v162
	v_fma_f32 v93, v93, v116, v163
	v_mul_f32_e32 v81, v80, v81
	v_mul_f32_e32 v82, 0xbfb8aa3b, v93
	v_exp_f32_e32 v105, v82
	v_fma_f32 v82,-v86,v114,v83
	v_fma_f32 v83, -v87, v114, v107
	v_add_f32_e32 v104, 1.0, v105
	v_fma_f32 v82, v82, v116, v90
	v_fma_f32 v83, v83, v116, v91
	v_rcp_f32_e32 v104, v104
	v_mul_f32_e32 v106, 0xbfb8aa3b, v83
	v_exp_f32_e32 v106, v106
	v_mul_f32_e32 v80, v93, v104
	v_mul_f32_e32 v92, v92, v80
	v_add_f32_e32 v105, 1.0, v106
	v_rcp_f32_e32 v105, v105
	v_med3_f32 v93, v111, s62, v173
	v_mul_f32_e32 v80, v83, v105
	v_mul_f32_e32 v82, v82, v80
	v_med3_f32 v83, v113, s62, v173
	v_cvt_pk_fp8_f32 v80, v83, v93
	v_med3_f32 v93, v94, s62, v173
	v_med3_f32 v94, v95, s62, v173
	v_med3_f32 v95, v81, s62, v173
	v_cvt_pk_fp8_f32 v81, v94, v95
	v_med3_f32 v83, v108, s62, v173
	v_cvt_pk_fp8_f32 v80, v83, v93 op_sel:[0,0,1]
	v_med3_f32 v83, v92, s62, v173
	v_med3_f32 v82, v82, s62, v173
	v_cvt_pk_fp8_f32 v81, v83, v82 op_sel:[0,0,1]
	v_mad_i64_i32 v[82:83], s[4:5], v112, s63, v[164:165]
	v_lshl_add_u64 v[82:83], v[82:83], 0, v[128:129]
	global_store_dwordx2 v[82:83], v[80:81], off
	v_or_b32_e32 v80, 48, v160
	v_mul_f32_e32 v82,s26,v230
	v_mul_f32_e32 v83,s26,v231
	s_nop 0
	v_fma_f32 v81, -v82, v82, v83
	v_add_f32_e32 v81, 0x3727c5ac, v81
	v_rsq_f32_e32 v242, v81
	s_nop 1
	s_nop 0
	s_nop 0
	s_nop 1
	s_nop 1
	s_nop 0
	v_mov_b32_e32 v92, v242
	v_fma_f32 v94,-v136,v82,v68
	v_fma_f32 v95,-v137,v82,v76
	v_fma_f32 v94, v94, v92, v134
	v_fma_f32 v95, v95, v92, v135
	s_nop 0
	v_mul_f32_e32 v68, 0xbfb8aa3b, v95
	v_exp_f32_e32 v81, v68
	v_fma_f32 v68,-v96,v82,v69
	v_fma_f32 v69, -v97, v82, v77
	v_add_f32_e32 v77, 1.0, v81
	v_fma_f32 v68, v68, v92, v100
	v_fma_f32 v69, v69, v92, v101
	v_rcp_f32_e32 v77, v77
	v_mul_f32_e32 v76, 0xbfb8aa3b, v69
	v_exp_f32_e32 v76, v76
	v_mul_f32_e32 v77, v95, v77
	v_mul_f32_e32 v81, v94, v77
	v_add_f32_e32 v76, 1.0, v76
	v_rcp_f32_e32 v76, v76
	v_mov_b32_e32 v77, v78
	v_mul_f32_e32 v69, v69, v76
	v_fma_f32 v76,-v132,v82,v70
	v_fma_f32 v77, -v133, v82, v77
	s_nop 0
	v_fma_f32 v76, v76, v92, v130
	v_fma_f32 v77, v77, v92, v131
	s_nop 0
	v_mul_f32_e32 v70, 0xbfb8aa3b, v77
	v_exp_f32_e32 v93, v70
	v_fma_f32 v70,-v98,v82,v71
	v_fma_f32 v71, -v99, v82, v79
	v_mul_f32_e32 v79, v68, v69
	v_fma_f32 v70, v70, v92, v102
	v_fma_f32 v71, v71, v92, v103
	v_add_f32_e32 v68, 1.0, v93
	v_mul_f32_e32 v78, 0xbfb8aa3b, v71
	v_exp_f32_e32 v78, v78
	v_rcp_f32_e32 v93, v68
	v_add_f32_e32 v68, 1.0, v78
	v_rcp_f32_e32 v78, v68
	v_fma_f32 v68,-v138,v82,v64
	v_fma_f32 v69,-v139,v82,v72
	v_mul_f32_e32 v72, v77, v93
	v_fma_f32 v68, v68, v92, v140
	v_fma_f32 v69, v69, v92, v141
	v_mul_f32_e32 v76, v76, v72
	v_mul_f32_e32 v64, 0xbfb8aa3b, v69
	v_exp_f32_e32 v64, v64
	v_mul_f32_e32 v71, v71, v78
	v_mul_f32_e32 v70, v70, v71
	v_add_f32_e32 v64, 1.0, v64
	v_rcp_f32_e32 v77, v64
	v_fma_f32 v64,-v84,v82,v65
	v_fma_f32 v65, -v85, v82, v73
	v_mul_f32_e32 v69, v69, v77
	v_fma_f32 v64, v64, v92, v88
	v_fma_f32 v65, v65, v92, v89
	v_mul_f32_e32 v71, v68, v69
	v_mul_f32_e32 v72, 0xbfb8aa3b, v65
	v_exp_f32_e32 v72, v72
	v_mov_b32_e32 v69, v74
	v_add_f32_e32 v68, 1.0, v72
	v_rcp_f32_e32 v72, v68
	v_fma_f32 v68,-v142,v82,v66
	v_fma_f32 v69, -v143, v82, v69
	v_mul_f32_e32 v65, v65, v72
	v_fma_f32 v68, v68, v92, v162
	v_fma_f32 v69, v69, v92, v163
	v_mul_f32_e32 v65, v64, v65
	v_mul_f32_e32 v66, 0xbfb8aa3b, v69
	v_exp_f32_e32 v73, v66
	v_fma_f32 v66,-v86,v82,v67
	v_fma_f32 v67, -v87, v82, v75
	v_add_f32_e32 v72, 1.0, v73
; __device__ __forceinline__ u32x4 pack8bf(const f32x4 a, const f32x4 b) { u32x4 w; w.x = cvt_pk_bf16(a[0], a[1]); w.y = cvt_pk_bf16(a[2], a[3]); w.z = cvt_pk_bf16(b[0], b[1]); w.w = cvt_pk_bf16(b[2], b[3]); return w; }
; __device__ __forceinline__ void ln_stats(const float* st, int row, float& mu, float& rs) { const f32x2 s = *(const f32x2*)(st + 2 * (size_t)row); mu = s[0] * (1.0f / DM); rs = 1.0f / sqrtf(s[1] * (1.0f / DM) - mu * mu + LN_EPS); }
;     __device__ __forceinline__ void operator()(EPI_ARGS) const {
;     ...
; #pragma unroll
;         for (int ai = 0; ai < 2; ++ai)
; #pragma unroll
;             for (int m = 0; m < 4; ++m) { const int row = row0 + ai * HALF + m * 16; f32x4 r[2];
;                 float mu = 0.f, rs = 1.f; if constexpr (FOLD) ln_stats(st, row, mu, rs);
; #pragma unroll
;                 for (int n = 0; n < 2; ++n) { f32x4 g = acc[ai][0][m][n], up = acc[ai][1][m][n];
;                     if constexpr (!PRE) { g = g * ascale; up = up * ascale; }
;                     if constexpr (FOLD) { g = (g - cg[n] * mu) * rs + dg[n]; up = (up - cu[n] * mu) * rs + du[n]; }
;                     if constexpr (!PRE) up = up * oscale;
; #pragma unroll
;                     for (int j = 0; j < 4; ++j) { const float e = __builtin_amdgcn_exp2f(g[j] * -1.4426950408889634f); r[n][j] = g[j] * __builtin_amdgcn_rcpf(1.0f + e) * up[j]; } }
;                 if constexpr (F8OUT) *(u32x2*)((unsigned char*)O + (size_t)row * ldc + col0) = pack8fp8(r[0], r[1]);
;                 else *(u32x4*)((bf16_t*)O + (size_t)row * ldc + col0) = pack8bf(r[0], r[1]); }
	v_fma_f32 v66, v66, v92, v90
	v_fma_f32 v67, v67, v92, v91
	v_rcp_f32_e32 v72, v72
	v_mul_f32_e32 v74, 0xbfb8aa3b, v67
	v_exp_f32_e32 v74, v74
	v_mul_f32_e32 v64, v69, v72
	v_mul_f32_e32 v68, v68, v64
	v_add_f32_e32 v73, 1.0, v74
	v_rcp_f32_e32 v73, v73
	v_med3_f32 v69, v79, s62, v173
	v_mul_f32_e32 v64, v67, v73
	v_mul_f32_e32 v66, v66, v64
	v_med3_f32 v67, v81, s62, v173
	v_cvt_pk_fp8_f32 v64, v67, v69
	v_med3_f32 v69, v70, s62, v173
	v_med3_f32 v70, v71, s62, v173
	v_med3_f32 v71, v65, s62, v173
	v_cvt_pk_fp8_f32 v65, v70, v71
	v_med3_f32 v67, v76, s62, v173
	v_cvt_pk_fp8_f32 v64, v67, v69 op_sel:[0,0,1]
	v_med3_f32 v67, v68, s62, v173
	v_med3_f32 v66, v66, s62, v173
	v_cvt_pk_fp8_f32 v65, v67, v66 op_sel:[0,0,1]
	v_mad_i64_i32 v[66:67], s[4:5], v80, s63, v[164:165]
	v_lshl_add_u64 v[66:67], v[66:67], 0, v[128:129]
	global_store_dwordx2 v[66:67], v[64:65], off
	v_add_u32_e32 v64, 0x80, v160
	v_mul_f32_e32 v66,s26,v232
	v_mul_f32_e32 v67,s26,v233
	s_nop 0
	v_fma_f32 v65, -v66, v66, v67
	v_add_f32_e32 v65, 0x3727c5ac, v65
	v_rsq_f32_e32 v242, v65
	s_nop 1
	s_nop 0
	s_nop 0
	s_nop 1
	s_nop 1
	s_nop 0
	v_mov_b32_e32 v68, v242
	v_fma_f32 v70,-v136,v66,v52
	v_fma_f32 v71,-v137,v66,v60
	v_fma_f32 v70, v70, v68, v134
	v_fma_f32 v71, v71, v68, v135
	s_nop 0
	v_mul_f32_e32 v52, 0xbfb8aa3b, v71
	v_exp_f32_e32 v65, v52
	v_fma_f32 v52,-v96,v66,v53
	v_fma_f32 v53, -v97, v66, v61
	v_add_f32_e32 v61, 1.0, v65
	v_fma_f32 v52, v52, v68, v100
	v_fma_f32 v53, v53, v68, v101
	v_rcp_f32_e32 v61, v61
	v_mul_f32_e32 v60, 0xbfb8aa3b, v53
	v_exp_f32_e32 v60, v60
	v_mul_f32_e32 v61, v71, v61
	v_mul_f32_e32 v65, v70, v61
	v_add_f32_e32 v60, 1.0, v60
	v_rcp_f32_e32 v60, v60
	v_mov_b32_e32 v61, v62
	v_mul_f32_e32 v53, v53, v60
	v_fma_f32 v60,-v132,v66,v54
	v_fma_f32 v61, -v133, v66, v61
	s_nop 0
	v_fma_f32 v60, v60, v68, v130
	v_fma_f32 v61, v61, v68, v131
	s_nop 0
	v_mul_f32_e32 v54, 0xbfb8aa3b, v61
	v_exp_f32_e32 v69, v54
	v_fma_f32 v54,-v98,v66,v55
	v_fma_f32 v55, -v99, v66, v63
	v_mul_f32_e32 v63, v52, v53
	v_fma_f32 v54, v54, v68, v102
	v_fma_f32 v55, v55, v68, v103
	v_add_f32_e32 v52, 1.0, v69
	v_mul_f32_e32 v62, 0xbfb8aa3b, v55
	v_exp_f32_e32 v62, v62
	v_rcp_f32_e32 v69, v52
	v_add_f32_e32 v52, 1.0, v62
	v_rcp_f32_e32 v62, v52
	v_fma_f32 v52,-v138,v66,v48
	v_fma_f32 v53,-v139,v66,v56
	v_mul_f32_e32 v56, v61, v69
	v_fma_f32 v52, v52, v68, v140
	v_fma_f32 v53, v53, v68, v141
	v_mul_f32_e32 v60, v60, v56
	v_mul_f32_e32 v48, 0xbfb8aa3b, v53
	v_exp_f32_e32 v48, v48
	v_mul_f32_e32 v55, v55, v62
	v_mul_f32_e32 v54, v54, v55
	v_add_f32_e32 v48, 1.0, v48
	v_rcp_f32_e32 v61, v48
	v_fma_f32 v48,-v84,v66,v49
	v_fma_f32 v49, -v85, v66, v57
	v_mul_f32_e32 v53, v53, v61
	v_fma_f32 v48, v48, v68, v88
	v_fma_f32 v49, v49, v68, v89
	v_mul_f32_e32 v55, v52, v53
	v_mul_f32_e32 v56, 0xbfb8aa3b, v49
	v_exp_f32_e32 v56, v56
	v_mov_b32_e32 v53, v58
	v_add_f32_e32 v52, 1.0, v56
	v_rcp_f32_e32 v56, v52
	v_fma_f32 v52,-v142,v66,v50
	v_fma_f32 v53, -v143, v66, v53
	v_mul_f32_e32 v49, v49, v56
	v_fma_f32 v52, v52, v68, v162
	v_fma_f32 v53, v53, v68, v163
	v_mul_f32_e32 v49, v48, v49
	v_mul_f32_e32 v50, 0xbfb8aa3b, v53
	v_exp_f32_e32 v57, v50
	v_fma_f32 v50,-v86,v66,v51
	v_fma_f32 v51, -v87, v66, v59
	v_add_f32_e32 v56, 1.0, v57
	v_fma_f32 v50, v50, v68, v90
	v_fma_f32 v51, v51, v68, v91
	v_rcp_f32_e32 v56, v56
	v_mul_f32_e32 v58, 0xbfb8aa3b, v51
	v_exp_f32_e32 v58, v58
	v_mul_f32_e32 v48, v53, v56
	v_mul_f32_e32 v52, v52, v48
	v_add_f32_e32 v57, 1.0, v58
	v_rcp_f32_e32 v57, v57
	v_med3_f32 v53, v63, s62, v173
	v_mul_f32_e32 v48, v51, v57
	v_mul_f32_e32 v50, v50, v48
	v_med3_f32 v51, v65, s62, v173
	v_cvt_pk_fp8_f32 v48, v51, v53
	v_med3_f32 v53, v54, s62, v173
	v_med3_f32 v54, v55, s62, v173
	v_med3_f32 v55, v49, s62, v173
	v_cvt_pk_fp8_f32 v49, v54, v55
	v_med3_f32 v51, v60, s62, v173
	v_cvt_pk_fp8_f32 v48, v51, v53 op_sel:[0,0,1]
	v_med3_f32 v51, v52, s62, v173
	v_med3_f32 v50, v50, s62, v173
	v_cvt_pk_fp8_f32 v49, v51, v50 op_sel:[0,0,1]
	v_mad_i64_i32 v[50:51], s[4:5], v64, s63, v[164:165]
	v_lshl_add_u64 v[50:51], v[50:51], 0, v[128:129]
	global_store_dwordx2 v[50:51], v[48:49], off
	v_add_u32_e32 v48, 0x90, v160
	v_mul_f32_e32 v50,s26,v234
	v_mul_f32_e32 v51,s26,v235
	s_nop 0
	v_fma_f32 v49, -v50, v50, v51
	v_add_f32_e32 v49, 0x3727c5ac, v49
	v_rsq_f32_e32 v242, v49
	s_nop 1
	s_nop 0
	s_nop 0
	s_nop 1
	s_nop 1
	s_nop 0
	v_mov_b32_e32 v52, v242
	v_fma_f32 v54,-v136,v50,v36
	v_fma_f32 v55,-v137,v50,v44
	v_fma_f32 v54, v54, v52, v134
	v_fma_f32 v55, v55, v52, v135
	s_nop 0
	v_mul_f32_e32 v36, 0xbfb8aa3b, v55
	v_exp_f32_e32 v49, v36
	v_fma_f32 v36,-v96,v50,v37
	v_fma_f32 v37, -v97, v50, v45
	v_add_f32_e32 v45, 1.0, v49
	v_fma_f32 v36, v36, v52, v100
	v_fma_f32 v37, v37, v52, v101
	v_rcp_f32_e32 v45, v45
	v_mul_f32_e32 v44, 0xbfb8aa3b, v37
	v_exp_f32_e32 v44, v44
	v_mul_f32_e32 v45, v55, v45
	v_mul_f32_e32 v49, v54, v45
	v_add_f32_e32 v44, 1.0, v44
	v_rcp_f32_e32 v44, v44
	v_mov_b32_e32 v45, v46
	v_mul_f32_e32 v37, v37, v44
	v_fma_f32 v44,-v132,v50,v38
	v_fma_f32 v45, -v133, v50, v45
	s_nop 0
	v_fma_f32 v44, v44, v52, v130
	v_fma_f32 v45, v45, v52, v131
	s_nop 0
	v_mul_f32_e32 v38, 0xbfb8aa3b, v45
	v_exp_f32_e32 v53, v38
	v_fma_f32 v38,-v98,v50,v39
	v_fma_f32 v39, -v99, v50, v47
	v_mul_f32_e32 v47, v36, v37
	v_fma_f32 v38, v38, v52, v102
	v_fma_f32 v39, v39, v52, v103
	v_add_f32_e32 v36, 1.0, v53
	v_mul_f32_e32 v46, 0xbfb8aa3b, v39
	v_exp_f32_e32 v46, v46
	v_rcp_f32_e32 v53, v36
	v_add_f32_e32 v36, 1.0, v46
	v_rcp_f32_e32 v46, v36
	v_fma_f32 v36,-v138,v50,v32
	v_fma_f32 v37,-v139,v50,v40
	v_mul_f32_e32 v40, v45, v53
	v_fma_f32 v36, v36, v52, v140
	v_fma_f32 v37, v37, v52, v141
; __device__ __forceinline__ u32x4 pack8bf(const f32x4 a, const f32x4 b) { u32x4 w; w.x = cvt_pk_bf16(a[0], a[1]); w.y = cvt_pk_bf16(a[2], a[3]); w.z = cvt_pk_bf16(b[0], b[1]); w.w = cvt_pk_bf16(b[2], b[3]); return w; }
; __device__ __forceinline__ void ln_stats(const float* st, int row, float& mu, float& rs) { const f32x2 s = *(const f32x2*)(st + 2 * (size_t)row); mu = s[0] * (1.0f / DM); rs = 1.0f / sqrtf(s[1] * (1.0f / DM) - mu * mu + LN_EPS); }
;     __device__ __forceinline__ void operator()(EPI_ARGS) const {
;     ...
; #pragma unroll
;         for (int ai = 0; ai < 2; ++ai)
; #pragma unroll
;             for (int m = 0; m < 4; ++m) { const int row = row0 + ai * HALF + m * 16; f32x4 r[2];
;                 float mu = 0.f, rs = 1.f; if constexpr (FOLD) ln_stats(st, row, mu, rs);
; #pragma unroll
;                 for (int n = 0; n < 2; ++n) { f32x4 g = acc[ai][0][m][n], up = acc[ai][1][m][n];
;                     if constexpr (!PRE) { g = g * ascale; up = up * ascale; }
;                     if constexpr (FOLD) { g = (g - cg[n] * mu) * rs + dg[n]; up = (up - cu[n] * mu) * rs + du[n]; }
;                     if constexpr (!PRE) up = up * oscale;
; #pragma unroll
;                     for (int j = 0; j < 4; ++j) { const float e = __builtin_amdgcn_exp2f(g[j] * -1.4426950408889634f); r[n][j] = g[j] * __builtin_amdgcn_rcpf(1.0f + e) * up[j]; } }
;                 if constexpr (F8OUT) *(u32x2*)((unsigned char*)O + (size_t)row * ldc + col0) = pack8fp8(r[0], r[1]);
;                 else *(u32x4*)((bf16_t*)O + (size_t)row * ldc + col0) = pack8bf(r[0], r[1]); }
	v_mul_f32_e32 v44, v44, v40
	v_mul_f32_e32 v32, 0xbfb8aa3b, v37
	v_exp_f32_e32 v32, v32
	v_mul_f32_e32 v39, v39, v46
	v_mul_f32_e32 v38, v38, v39
	v_add_f32_e32 v32, 1.0, v32
	v_rcp_f32_e32 v45, v32
	v_fma_f32 v32,-v84,v50,v33
	v_fma_f32 v33, -v85, v50, v41
	v_mul_f32_e32 v37, v37, v45
	v_fma_f32 v32, v32, v52, v88
	v_fma_f32 v33, v33, v52, v89
	v_mul_f32_e32 v39, v36, v37
	v_mul_f32_e32 v40, 0xbfb8aa3b, v33
	v_exp_f32_e32 v40, v40
	v_mov_b32_e32 v37, v42
	v_add_f32_e32 v36, 1.0, v40
	v_rcp_f32_e32 v40, v36
	v_fma_f32 v36,-v142,v50,v34
	v_fma_f32 v37, -v143, v50, v37
	v_mul_f32_e32 v33, v33, v40
	v_fma_f32 v36, v36, v52, v162
	v_fma_f32 v37, v37, v52, v163
	v_mul_f32_e32 v33, v32, v33
	v_mul_f32_e32 v34, 0xbfb8aa3b, v37
	v_exp_f32_e32 v41, v34
	v_fma_f32 v34,-v86,v50,v35
	v_fma_f32 v35, -v87, v50, v43
	v_add_f32_e32 v40, 1.0, v41
	v_fma_f32 v34, v34, v52, v90
	v_fma_f32 v35, v35, v52, v91
	v_rcp_f32_e32 v40, v40
	v_mul_f32_e32 v42, 0xbfb8aa3b, v35
	v_exp_f32_e32 v42, v42
	v_mul_f32_e32 v32, v37, v40
	v_mul_f32_e32 v36, v36, v32
	v_add_f32_e32 v41, 1.0, v42
	v_rcp_f32_e32 v41, v41
	v_med3_f32 v37, v47, s62, v173
	v_mul_f32_e32 v32, v35, v41
	v_mul_f32_e32 v34, v34, v32
	v_med3_f32 v35, v49, s62, v173
	v_cvt_pk_fp8_f32 v32, v35, v37
	v_med3_f32 v37, v38, s62, v173
	v_med3_f32 v38, v39, s62, v173
	v_med3_f32 v39, v33, s62, v173
	v_cvt_pk_fp8_f32 v33, v38, v39
	v_med3_f32 v35, v44, s62, v173
	v_cvt_pk_fp8_f32 v32, v35, v37 op_sel:[0,0,1]
	v_med3_f32 v35, v36, s62, v173
	v_med3_f32 v34, v34, s62, v173
	v_cvt_pk_fp8_f32 v33, v35, v34 op_sel:[0,0,1]
	v_mad_i64_i32 v[34:35], s[4:5], v48, s63, v[164:165]
	v_lshl_add_u64 v[34:35], v[34:35], 0, v[128:129]
	global_store_dwordx2 v[34:35], v[32:33], off
	v_add_u32_e32 v32, 0xa0, v160
	v_mul_f32_e32 v34,s26,v236
	v_mul_f32_e32 v35,s26,v237
	s_nop 0
	v_fma_f32 v33, -v34, v34, v35
	v_add_f32_e32 v33, 0x3727c5ac, v33
	v_rsq_f32_e32 v242, v33
	s_nop 1
	s_nop 0
	s_nop 0
	s_nop 1
	s_nop 1
	s_nop 0
	v_mov_b32_e32 v36, v242
	v_fma_f32 v38,-v136,v34,v20
	v_fma_f32 v39,-v137,v34,v28
	v_fma_f32 v38, v38, v36, v134
	v_fma_f32 v39, v39, v36, v135
	s_nop 0
	v_mul_f32_e32 v20, 0xbfb8aa3b, v39
	v_exp_f32_e32 v33, v20
	v_fma_f32 v20,-v96,v34,v21
	v_fma_f32 v21, -v97, v34, v29
	v_add_f32_e32 v29, 1.0, v33
	v_fma_f32 v20, v20, v36, v100
	v_fma_f32 v21, v21, v36, v101
	v_rcp_f32_e32 v29, v29
	v_mul_f32_e32 v28, 0xbfb8aa3b, v21
	v_exp_f32_e32 v28, v28
	v_mul_f32_e32 v29, v39, v29
	v_mul_f32_e32 v33, v38, v29
	v_add_f32_e32 v28, 1.0, v28
	v_rcp_f32_e32 v28, v28
	v_mov_b32_e32 v29, v30
	v_mul_f32_e32 v21, v21, v28
	v_fma_f32 v28,-v132,v34,v22
	v_fma_f32 v29, -v133, v34, v29
	s_nop 0
	v_fma_f32 v28, v28, v36, v130
	v_fma_f32 v29, v29, v36, v131
	s_nop 0
	v_mul_f32_e32 v22, 0xbfb8aa3b, v29
	v_exp_f32_e32 v37, v22
	v_fma_f32 v22,-v98,v34,v23
	v_fma_f32 v23, -v99, v34, v31
	v_mul_f32_e32 v31, v20, v21
	v_fma_f32 v22, v22, v36, v102
	v_fma_f32 v23, v23, v36, v103
	v_add_f32_e32 v20, 1.0, v37
	v_mul_f32_e32 v30, 0xbfb8aa3b, v23
	v_exp_f32_e32 v30, v30
	v_rcp_f32_e32 v37, v20
	v_add_f32_e32 v20, 1.0, v30
	v_rcp_f32_e32 v30, v20
	v_fma_f32 v20,-v138,v34,v16
	v_fma_f32 v21,-v139,v34,v24
	v_mul_f32_e32 v24, v29, v37
	v_fma_f32 v20, v20, v36, v140
	v_fma_f32 v21, v21, v36, v141
	v_mul_f32_e32 v28, v28, v24
	v_mul_f32_e32 v16, 0xbfb8aa3b, v21
	v_exp_f32_e32 v16, v16
	v_mul_f32_e32 v23, v23, v30
	v_mul_f32_e32 v22, v22, v23
	v_add_f32_e32 v16, 1.0, v16
	v_rcp_f32_e32 v29, v16
	v_fma_f32 v16,-v84,v34,v17
	v_fma_f32 v17, -v85, v34, v25
	v_mul_f32_e32 v21, v21, v29
	v_fma_f32 v16, v16, v36, v88
	v_fma_f32 v17, v17, v36, v89
	v_mul_f32_e32 v23, v20, v21
	v_mul_f32_e32 v24, 0xbfb8aa3b, v17
	v_exp_f32_e32 v24, v24
	v_mov_b32_e32 v21, v26
	v_add_f32_e32 v20, 1.0, v24
	v_rcp_f32_e32 v24, v20
	v_fma_f32 v20,-v142,v34,v18
	v_fma_f32 v21, -v143, v34, v21
	v_mul_f32_e32 v17, v17, v24
	v_fma_f32 v20, v20, v36, v162
	v_fma_f32 v21, v21, v36, v163
	v_mul_f32_e32 v17, v16, v17
	v_mul_f32_e32 v18, 0xbfb8aa3b, v21
	v_exp_f32_e32 v25, v18
	v_fma_f32 v18,-v86,v34,v19
	v_fma_f32 v19, -v87, v34, v27
	v_add_f32_e32 v24, 1.0, v25
; #define PG8_BAR __builtin_amdgcn_s_barrier()
; __device__ __forceinline__ u32x4 pack8bf(const f32x4 a, const f32x4 b) { u32x4 w; w.x = cvt_pk_bf16(a[0], a[1]); w.y = cvt_pk_bf16(a[2], a[3]); w.z = cvt_pk_bf16(b[0], b[1]); w.w = cvt_pk_bf16(b[2], b[3]); return w; }
; __device__ __forceinline__ void ln_stats(const float* st, int row, float& mu, float& rs) { const f32x2 s = *(const f32x2*)(st + 2 * (size_t)row); mu = s[0] * (1.0f / DM); rs = 1.0f / sqrtf(s[1] * (1.0f / DM) - mu * mu + LN_EPS); }
;     ...
;         if (!has_next) break;
; #pragma unroll
;         for (int a = 0; a < 2; ++a)
; #pragma unroll
;             for (int b = 0; b < 2; ++b)
; #pragma unroll
;                 for (int m = 0; m < 4; ++m)
; #pragma unroll
;                     for (int n = 0; n < 2; ++n) acc[a][b][m][n] = (f32x4){0.f, 0.f, 0.f, 0.f};
;         cur = nxt; cA = nA; cB = nB; ++ui;
;         if (wr == 1) PG8_BAR;
;     __device__ __forceinline__ void operator()(EPI_ARGS) const {
;     ...
; #pragma unroll
;         for (int ai = 0; ai < 2; ++ai)
; #pragma unroll
;             for (int m = 0; m < 4; ++m) { const int row = row0 + ai * HALF + m * 16; f32x4 r[2];
;                 float mu = 0.f, rs = 1.f; if constexpr (FOLD) ln_stats(st, row, mu, rs);
; #pragma unroll
;                 for (int n = 0; n < 2; ++n) { f32x4 g = acc[ai][0][m][n], up = acc[ai][1][m][n];
;                     if constexpr (!PRE) { g = g * ascale; up = up * ascale; }
;                     if constexpr (FOLD) { g = (g - cg[n] * mu) * rs + dg[n]; up = (up - cu[n] * mu) * rs + du[n]; }
;                     if constexpr (!PRE) up = up * oscale;
; #pragma unroll
;                     for (int j = 0; j < 4; ++j) { const float e = __builtin_amdgcn_exp2f(g[j] * -1.4426950408889634f); r[n][j] = g[j] * __builtin_amdgcn_rcpf(1.0f + e) * up[j]; } }
;                 if constexpr (F8OUT) *(u32x2*)((unsigned char*)O + (size_t)row * ldc + col0) = pack8fp8(r[0], r[1]);
;                 else *(u32x4*)((bf16_t*)O + (size_t)row * ldc + col0) = pack8bf(r[0], r[1]); }
	v_fma_f32 v18, v18, v36, v90
	v_fma_f32 v19, v19, v36, v91
	v_rcp_f32_e32 v24, v24
	v_mul_f32_e32 v26, 0xbfb8aa3b, v19
	v_exp_f32_e32 v26, v26
	v_mul_f32_e32 v16, v21, v24
	v_mul_f32_e32 v20, v20, v16
	v_add_f32_e32 v25, 1.0, v26
	v_rcp_f32_e32 v25, v25
	v_med3_f32 v21, v31, s62, v173
	v_mul_f32_e32 v16, v19, v25
	v_mul_f32_e32 v18, v18, v16
	v_med3_f32 v19, v33, s62, v173
	v_cvt_pk_fp8_f32 v16, v19, v21
	v_med3_f32 v21, v22, s62, v173
	v_med3_f32 v22, v23, s62, v173
	v_med3_f32 v23, v17, s62, v173
	v_cvt_pk_fp8_f32 v17, v22, v23
	v_med3_f32 v19, v28, s62, v173
	v_cvt_pk_fp8_f32 v16, v19, v21 op_sel:[0,0,1]
	v_med3_f32 v19, v20, s62, v173
	v_med3_f32 v18, v18, s62, v173
	v_cvt_pk_fp8_f32 v17, v19, v18 op_sel:[0,0,1]
	v_mad_i64_i32 v[18:19], s[4:5], v32, s63, v[164:165]
	v_lshl_add_u64 v[18:19], v[18:19], 0, v[128:129]
	global_store_dwordx2 v[18:19], v[16:17], off
	v_add_u32_e32 v16, 0xb0, v160
	v_mul_f32_e32 v18,s26,v238
	v_mul_f32_e32 v19,s26,v239
	s_nop 0
	v_fma_f32 v17, -v18, v18, v19
	v_add_f32_e32 v17, 0x3727c5ac, v17
	v_rsq_f32_e32 v242, v17
	s_nop 1
	s_nop 0
	s_nop 0
	s_nop 1
	s_nop 1
	s_nop 0
	v_mov_b32_e32 v20, v242
	v_fma_f32 v22,-v136,v18,v4
	v_fma_f32 v23,-v137,v18,v12
	v_fma_f32 v22, v22, v20, v134
	v_fma_f32 v23, v23, v20, v135
	s_andn2_b64 vcc, exec, s[2:3]
	v_mul_f32_e32 v4, 0xbfb8aa3b, v23
	v_exp_f32_e32 v17, v4
	v_fma_f32 v4,-v96,v18,v5
	v_fma_f32 v5, -v97, v18, v13
	s_mov_b64 s[2:3], -1
	v_fma_f32 v4, v4, v20, v100
	v_fma_f32 v5, v5, v20, v101
	v_add_f32_e32 v13, 1.0, v17
	v_mul_f32_e32 v12, 0xbfb8aa3b, v5
	v_exp_f32_e32 v12, v12
	v_rcp_f32_e32 v13, v13
	v_add_f32_e32 v12, 1.0, v12
	v_rcp_f32_e32 v12, v12
	v_mul_f32_e32 v13, v23, v13
	v_mul_f32_e32 v17, v22, v13
	v_mul_f32_e32 v5, v5, v12
	v_fma_f32 v12,-v132,v18,v6
	v_fma_f32 v13,-v133,v18,v14
	v_fma_f32 v12, v12, v20, v130
	v_fma_f32 v13, v13, v20, v131
	s_nop 0
	v_mul_f32_e32 v6, 0xbfb8aa3b, v13
	v_exp_f32_e32 v21, v6
	v_fma_f32 v6,-v98,v18,v7
	v_fma_f32 v7, -v99, v18, v15
	v_mul_f32_e32 v15, v4, v5
	v_fma_f32 v6, v6, v20, v102
	v_fma_f32 v7, v7, v20, v103
	v_add_f32_e32 v4, 1.0, v21
	v_mul_f32_e32 v14, 0xbfb8aa3b, v7
	v_exp_f32_e32 v14, v14
	v_rcp_f32_e32 v21, v4
	v_add_f32_e32 v4, 1.0, v14
	v_rcp_f32_e32 v14, v4
	v_fma_f32 v4,-v138,v18,v0
	v_fma_f32 v5,-v139,v18,v8
	v_mul_f32_e32 v8, v13, v21
	v_fma_f32 v4, v4, v20, v140
	v_fma_f32 v5, v5, v20, v141
	v_mul_f32_e32 v12, v12, v8
	v_mul_f32_e32 v0, 0xbfb8aa3b, v5
	v_exp_f32_e32 v0, v0
	v_mul_f32_e32 v7, v7, v14
	v_mul_f32_e32 v6, v6, v7
	v_add_f32_e32 v0, 1.0, v0
	v_rcp_f32_e32 v13, v0
	v_fma_f32 v0,-v84,v18,v1
	v_fma_f32 v1, -v85, v18, v9
	v_mul_f32_e32 v5, v5, v13
	v_fma_f32 v0, v0, v20, v88
	v_fma_f32 v1, v1, v20, v89
	v_mul_f32_e32 v7, v4, v5
	v_mul_f32_e32 v8, 0xbfb8aa3b, v1
	v_exp_f32_e32 v8, v8
	v_mov_b32_e32 v5, v10
	v_add_f32_e32 v4, 1.0, v8
	v_rcp_f32_e32 v8, v4
	v_fma_f32 v4,-v142,v18,v2
	v_fma_f32 v5, -v143, v18, v5
	v_mul_f32_e32 v1, v1, v8
	v_fma_f32 v4, v4, v20, v162
	v_fma_f32 v5, v5, v20, v163
	v_mul_f32_e32 v1, v0, v1
	v_mul_f32_e32 v2, 0xbfb8aa3b, v5
	v_exp_f32_e32 v9, v2
	v_fma_f32 v2,-v86,v18,v3
	v_fma_f32 v3, -v87, v18, v11
	v_add_f32_e32 v8, 1.0, v9
	v_fma_f32 v2, v2, v20, v90
	v_fma_f32 v3, v3, v20, v91
	v_rcp_f32_e32 v8, v8
	v_mul_f32_e32 v10, 0xbfb8aa3b, v3
	v_exp_f32_e32 v10, v10
	v_mul_f32_e32 v0, v5, v8
	v_mul_f32_e32 v4, v4, v0
	v_add_f32_e32 v9, 1.0, v10
	v_rcp_f32_e32 v9, v9
	v_med3_f32 v5, v15, s62, v173
	v_mul_f32_e32 v0, v3, v9
	v_mul_f32_e32 v2, v2, v0
	v_med3_f32 v3, v17, s62, v173
	v_cvt_pk_fp8_f32 v0, v3, v5
	v_med3_f32 v5, v6, s62, v173
	v_med3_f32 v6, v7, s62, v173
	v_med3_f32 v7, v1, s62, v173
	v_cvt_pk_fp8_f32 v1, v6, v7
	v_med3_f32 v3, v12, s62, v173
	v_cvt_pk_fp8_f32 v0, v3, v5 op_sel:[0,0,1]
	v_med3_f32 v3, v4, s62, v173
	v_med3_f32 v2, v2, s62, v173
	v_cvt_pk_fp8_f32 v1, v3, v2 op_sel:[0,0,1]
	v_mad_i64_i32 v[2:3], s[4:5], v16, s63, v[164:165]
	v_lshl_add_u64 v[2:3], v[2:3], 0, v[128:129]
	global_store_dwordx2 v[2:3], v[0:1], off
	s_cbranch_vccnz .LBB0_3772
	s_andn2_b64 vcc, exec, s[6:7]
	s_cbranch_vccnz .LBB0_3771
	s_barrier
	s_branch .LBB0_3771

; __device__ __forceinline__ u32x4 pack8bf(const f32x4 a, const f32x4 b) { u32x4 w; w.x = cvt_pk_bf16(a[0], a[1]); w.y = cvt_pk_bf16(a[2], a[3]); w.z = cvt_pk_bf16(b[0], b[1]); w.w = cvt_pk_bf16(b[2], b[3]); return w; }
; __device__ __forceinline__ float rms_scale(const float* ssq, int row, int which) {
;     const f32x4 a = *(const f32x4*)(ssq + (size_t)row * 16 + which * 8), b = *(const f32x4*)(ssq + (size_t)row * 16 + which * 8 + 4);
;     const float s = ((a[0] + a[1]) + (a[2] + a[3])) + ((b[0] + b[1]) + (b[2] + b[3]));
;     return 1.0f / sqrtf(s * (1.0f / 512.0f) + RMS_EPS);
; }
;     __device__ __forceinline__ void operator()(EPI_ARGS) const {
;     ...
;             for (int m = 0; m < 4; ++m) { const int row = row0 + ai * HALF + m * 16; const float rs = rms_scale(ssq, row, 0);
;                 if (u.pn < 8) {
; #pragma unroll
;                     for (int bj = 0; bj < 2; ++bj) { const int h = 2 * u.pn + bj;
;                         *(u32x4*)(Q + ((size_t)h * NTOK + row) * 192 + 32 * wc + 8 * fq) = pack8bf(acc[ai][bj][m][0] * rs, acc[ai][bj][m][1] * rs); }
;                 } else { const int fi = 16 * (wc & 1) + 4 * fq;
;                     const f32x4 c4 = *(const f32x4*)(cs + (size_t)row * 32 + fi), s4 = *(const f32x4*)(sn + (size_t)row * 32 + fi);
; #pragma unroll
;                     for (int bj = 0; bj < 2; ++bj) { const int h = 4 * (u.pn - 8) + 2 * bj + (wc >> 1); const f32x4 v0 = acc[ai][bj][m][0] * rs, v1 = acc[ai][bj][m][1] * rs;
;                         *(u32x4*)(Q + ((size_t)h * NTOK + row) * 192 + 128 + 32 * (wc & 1) + 8 * fq) = pack8bf(v0 * c4 - v1 * s4, v1 * c4 + v0 * s4); } }
.LBB0_4061:
	v_lshlrev_b32_e32 v136, 1, v138
	v_lshl_add_u64 v[116:117], v[158:159], 0, v[136:137]
	global_store_dwordx4 v[116:117], v[112:115], off
	v_cvt_f32_i32_e32 v109, v109
	v_cvt_f32_i32_e32 v108, v108
	v_or_b32_e32 v112, 16, v152
	v_ashrrev_i32_e32 v113, 31, v112
	v_mov_b32_e32 v118, v198
	v_mov_b32_e32 v119, v199
	v_mov_b32_e32 v120, v200
	v_mov_b32_e32 v121, v201
	v_mov_b32_e32 v122, v202
	v_mov_b32_e32 v123, v203
	v_mov_b32_e32 v124, v204
	v_mov_b32_e32 v125, v205
	v_cvt_f32_i32_e32 v111, v111
	v_cvt_f32_i32_e32 v110, v110
	v_cvt_f32_i32_e32 v105, v105
	v_cvt_f32_i32_e32 v104, v104
	v_cvt_f32_i32_e32 v107, v107
	v_cvt_f32_i32_e32 v106, v106
	v_cndmask_b32_e64 v114, 0, 1, s[44:45]
	v_cmp_ne_u32_e64 s[4:5], 1, v114
	v_pk_mul_f32 v[114:115], v[110:111], s[26:27] op_sel_hi:[1,0]
	v_pk_mul_f32 v[116:117], v[108:109], s[26:27] op_sel_hi:[1,0]
	v_pk_mul_f32 v[108:109], v[106:107], s[26:27] op_sel_hi:[1,0]
	v_pk_mul_f32 v[110:111], v[104:105], s[26:27] op_sel_hi:[1,0]
	v_cvt_f32_i32_e32 v101, v101
	v_cvt_f32_i32_e32 v100, v100
	v_cvt_f32_i32_e32 v99, v99
	v_cvt_f32_i32_e32 v98, v98
	v_cvt_f32_i32_e32 v97, v97
	v_cvt_f32_i32_e32 v96, v96
	v_cvt_f32_i32_e32 v103, v103
	v_cvt_f32_i32_e32 v102, v102
	v_pk_mul_f32 v[102:103], v[102:103], s[26:27] op_sel_hi:[1,0]
	v_add_f32_e32 v104, v118, v119
	v_add_f32_e32 v105, v120, v121
	v_add_f32_e32 v106, v122, v123
	v_add_f32_e32 v107, v124, v125
	v_add_f32_e32 v104, v104, v105
	v_add_f32_e32 v105, v106, v107
	v_add_f32_e32 v104, v104, v105
	v_fmamk_f32 v104, v104, 0x3b000000, v162
	v_rsq_f32_e32 v254, v104
	s_nop 1
	v_pk_mul_f32 v[104:105], v[100:101], s[26:27] op_sel_hi:[1,0]
	v_pk_mul_f32 v[100:101], v[98:99], s[26:27] op_sel_hi:[1,0]
	s_nop 1
	s_nop 1
	s_nop 1
	v_pk_mul_f32 v[106:107], v[96:97], s[26:27] op_sel_hi:[1,0]
	s_andn2_b64 vcc, exec, s[44:45]
	v_mov_b32_e32 v118, v254
	s_mov_b64 s[6:7], -1
	s_cbranch_vccnz .LBB0_4063
	v_lshlrev_b64 v[120:121], 7, v[112:113]
	v_lshl_add_u64 v[96:97], v[142:143], 0, v[120:121]
	global_load_dwordx4 v[96:99], v[96:97], off
	v_lshl_add_u64 v[120:121], v[140:141], 0, v[120:121]
	global_load_dwordx4 v[122:125], v[120:121], off
	s_or_b32 s6, s40, 2
	s_ashr_i32 s41, s40, 31
	s_ashr_i32 s7, s6, 31
	s_lshl_b64 s[44:45], s[40:41], 14
	s_lshl_b64 s[6:7], s[6:7], 14
	v_mov_b64_e32 v[120:121], s[20:21]
	v_lshl_add_u64 v[172:173], s[44:45], 0, v[112:113]
	v_lshl_add_u64 v[176:177], s[6:7], 0, v[112:113]
	v_pk_mul_f32 v[126:127], v[114:115], v[118:119] op_sel_hi:[1,0]
	v_pk_mul_f32 v[154:155], v[116:117], v[118:119] op_sel_hi:[1,0]
	v_pk_mul_f32 v[156:157], v[108:109], v[118:119] op_sel_hi:[1,0]
	v_pk_mul_f32 v[158:159], v[110:111], v[118:119] op_sel_hi:[1,0]
	v_pk_mul_f32 v[164:165], v[102:103], v[118:119] op_sel_hi:[1,0]
	v_pk_mul_f32 v[166:167], v[104:105], v[118:119] op_sel_hi:[1,0]
	v_pk_mul_f32 v[168:169], v[100:101], v[118:119] op_sel_hi:[1,0]
	v_pk_mul_f32 v[170:171], v[106:107], v[118:119] op_sel_hi:[1,0]
	v_mad_u64_u32 v[174:175], s[44:45], v172, s81, v[146:147]
	v_mad_u64_u32 v[120:121], s[6:7], v176, s81, v[120:121]
	v_mad_i32_i24 v175, v173, s81, v175
	v_mad_i32_i24 v121, v177, s81, v121
	v_lshl_add_u64 v[120:121], v[120:121], 0, s[24:25]
	s_mov_b64 s[6:7], 0
	s_waitcnt vmcnt(1)
	v_pk_mul_f32 v[172:173], v[156:157], v[98:99]
	v_pk_mul_f32 v[176:177], v[158:159], v[96:97]
	v_pk_mul_f32 v[178:179], v[126:127], v[98:99]
	v_pk_mul_f32 v[180:181], v[154:155], v[96:97]
	v_pk_mul_f32 v[182:183], v[168:169], v[98:99]
	v_pk_mul_f32 v[184:185], v[170:171], v[96:97]
	v_pk_mul_f32 v[98:99], v[164:165], v[98:99]
	v_pk_mul_f32 v[96:97], v[166:167], v[96:97]
	s_waitcnt vmcnt(0)
	v_pk_fma_f32 v[126:127], v[126:127], v[124:125], v[172:173] neg_lo:[0,0,1] neg_hi:[0,0,1]
	v_pk_fma_f32 v[154:155], v[154:155], v[122:123], v[176:177] neg_lo:[0,0,1] neg_hi:[0,0,1]
	v_pk_fma_f32 v[156:157], v[156:157], v[124:125], v[178:179]
	v_pk_fma_f32 v[158:159], v[158:159], v[122:123], v[180:181]
	v_pk_fma_f32 v[164:165], v[164:165], v[124:125], v[182:183] neg_lo:[0,0,1] neg_hi:[0,0,1]
	v_pk_fma_f32 v[166:167], v[166:167], v[122:123], v[184:185] neg_lo:[0,0,1] neg_hi:[0,0,1]
	v_pk_fma_f32 v[124:125], v[168:169], v[124:125], v[98:99]
	v_pk_fma_f32 v[122:123], v[170:171], v[122:123], v[96:97]
	v_cvt_pk_bf16_f32 v96, v154, v155
	v_cvt_pk_bf16_f32 v97, v126, v127
	v_cvt_pk_bf16_f32 v98, v158, v159
	v_cvt_pk_bf16_f32 v99, v156, v157
	global_store_dwordx4 v[174:175], v[96:99], off offset:256
	s_nop 1
	v_cvt_pk_bf16_f32 v96, v166, v167
	v_cvt_pk_bf16_f32 v97, v164, v165
	v_cvt_pk_bf16_f32 v98, v122, v123
	v_cvt_pk_bf16_f32 v99, v124, v125

; __device__ __forceinline__ u32x4 pack8bf(const f32x4 a, const f32x4 b) { u32x4 w; w.x = cvt_pk_bf16(a[0], a[1]); w.y = cvt_pk_bf16(a[2], a[3]); w.z = cvt_pk_bf16(b[0], b[1]); w.w = cvt_pk_bf16(b[2], b[3]); return w; }
; __device__ __forceinline__ float rms_scale(const float* ssq, int row, int which) {
;     const f32x4 a = *(const f32x4*)(ssq + (size_t)row * 16 + which * 8), b = *(const f32x4*)(ssq + (size_t)row * 16 + which * 8 + 4);
;     const float s = ((a[0] + a[1]) + (a[2] + a[3])) + ((b[0] + b[1]) + (b[2] + b[3]));
;     return 1.0f / sqrtf(s * (1.0f / 512.0f) + RMS_EPS);
; }
;     __device__ __forceinline__ void operator()(EPI_ARGS) const {
;     ...
;             for (int m = 0; m < 4; ++m) { const int row = row0 + ai * HALF + m * 16; const float rs = rms_scale(ssq, row, 0);
;                 if (u.pn < 8) {
; #pragma unroll
;                     for (int bj = 0; bj < 2; ++bj) { const int h = 2 * u.pn + bj;
;                         *(u32x4*)(Q + ((size_t)h * NTOK + row) * 192 + 32 * wc + 8 * fq) = pack8bf(acc[ai][bj][m][0] * rs, acc[ai][bj][m][1] * rs); }
;                 } else { const int fi = 16 * (wc & 1) + 4 * fq;
;                     const f32x4 c4 = *(const f32x4*)(cs + (size_t)row * 32 + fi), s4 = *(const f32x4*)(sn + (size_t)row * 32 + fi);
; #pragma unroll
;                     for (int bj = 0; bj < 2; ++bj) { const int h = 4 * (u.pn - 8) + 2 * bj + (wc >> 1); const f32x4 v0 = acc[ai][bj][m][0] * rs, v1 = acc[ai][bj][m][1] * rs;
;                         *(u32x4*)(Q + ((size_t)h * NTOK + row) * 192 + 128 + 32 * (wc & 1) + 8 * fq) = pack8bf(v0 * c4 - v1 * s4, v1 * c4 + v0 * s4); } }
.LBB0_4065:
	v_lshl_add_u64 v[100:101], v[120:121], 0, v[136:137]
	global_store_dwordx4 v[100:101], v[96:99], off
	v_cvt_f32_i32_e32 v93, v93
	v_cvt_f32_i32_e32 v92, v92
	v_or_b32_e32 v96, 32, v152
	v_ashrrev_i32_e32 v97, 31, v96
	v_mov_b32_e32 v102, v206
	v_mov_b32_e32 v103, v207
	v_mov_b32_e32 v104, v208
	v_mov_b32_e32 v105, v209
	v_mov_b32_e32 v106, v210
	v_mov_b32_e32 v107, v211
	v_mov_b32_e32 v108, v212
	v_mov_b32_e32 v109, v213
	v_cvt_f32_i32_e32 v95, v95
	v_cvt_f32_i32_e32 v94, v94
	v_cvt_f32_i32_e32 v89, v89
	v_cvt_f32_i32_e32 v88, v88
	v_pk_mul_f32 v[100:101], v[92:93], s[26:27] op_sel_hi:[1,0]
	v_pk_mul_f32 v[98:99], v[94:95], s[26:27] op_sel_hi:[1,0]
	v_cvt_f32_i32_e32 v85, v85
	v_pk_mul_f32 v[94:95], v[88:89], s[26:27] op_sel_hi:[1,0]
	v_cvt_f32_i32_e32 v84, v84
	v_cvt_f32_i32_e32 v83, v83
	v_cvt_f32_i32_e32 v82, v82
	v_cvt_f32_i32_e32 v81, v81
	v_cvt_f32_i32_e32 v80, v80
	v_cvt_f32_i32_e32 v91, v91
	v_cvt_f32_i32_e32 v90, v90
	v_cvt_f32_i32_e32 v87, v87
	v_cvt_f32_i32_e32 v86, v86
	v_pk_mul_f32 v[90:91], v[90:91], s[26:27] op_sel_hi:[1,0]
	v_pk_mul_f32 v[86:87], v[86:87], s[26:27] op_sel_hi:[1,0]
	v_add_f32_e32 v88, v102, v103
	v_add_f32_e32 v89, v104, v105
	v_add_f32_e32 v92, v106, v107
	v_add_f32_e32 v93, v108, v109
	v_add_f32_e32 v88, v88, v89
	v_add_f32_e32 v89, v92, v93
	v_add_f32_e32 v88, v88, v89
	v_fmamk_f32 v88, v88, 0x3b000000, v162
	v_rsq_f32_e32 v254, v88
	s_nop 1
	v_pk_mul_f32 v[88:89], v[84:85], s[26:27] op_sel_hi:[1,0]
	v_pk_mul_f32 v[84:85], v[82:83], s[26:27] op_sel_hi:[1,0]
	s_nop 1
	s_nop 1
	s_nop 1
	v_pk_mul_f32 v[92:93], v[80:81], s[26:27] op_sel_hi:[1,0]
	s_and_b64 vcc, exec, s[4:5]
	v_mov_b32_e32 v102, v254
	s_mov_b64 s[6:7], -1
	s_cbranch_vccnz .LBB0_4067
	v_lshlrev_b64 v[104:105], 7, v[96:97]
	v_lshl_add_u64 v[80:81], v[142:143], 0, v[104:105]
	global_load_dwordx4 v[80:83], v[80:81], off
	v_lshl_add_u64 v[104:105], v[140:141], 0, v[104:105]
	global_load_dwordx4 v[106:109], v[104:105], off
	s_or_b32 s6, s40, 2
	s_ashr_i32 s41, s40, 31
	s_ashr_i32 s7, s6, 31
	s_lshl_b64 s[44:45], s[40:41], 14
	s_lshl_b64 s[6:7], s[6:7], 14
	v_mov_b64_e32 v[104:105], s[20:21]
	v_lshl_add_u64 v[126:127], s[44:45], 0, v[96:97]
	v_lshl_add_u64 v[156:157], s[6:7], 0, v[96:97]
	v_pk_mul_f32 v[110:111], v[98:99], v[102:103] op_sel_hi:[1,0]
	v_pk_mul_f32 v[112:113], v[100:101], v[102:103] op_sel_hi:[1,0]
	v_pk_mul_f32 v[114:115], v[90:91], v[102:103] op_sel_hi:[1,0]
	v_pk_mul_f32 v[116:117], v[94:95], v[102:103] op_sel_hi:[1,0]
	v_pk_mul_f32 v[118:119], v[86:87], v[102:103] op_sel_hi:[1,0]
	v_pk_mul_f32 v[120:121], v[88:89], v[102:103] op_sel_hi:[1,0]
	v_pk_mul_f32 v[122:123], v[84:85], v[102:103] op_sel_hi:[1,0]
	v_pk_mul_f32 v[124:125], v[92:93], v[102:103] op_sel_hi:[1,0]
	v_mad_u64_u32 v[154:155], s[44:45], v126, s81, v[146:147]
	v_mad_u64_u32 v[104:105], s[6:7], v156, s81, v[104:105]
	v_mad_i32_i24 v155, v127, s81, v155
	v_mad_i32_i24 v105, v157, s81, v105
	v_lshl_add_u64 v[104:105], v[104:105], 0, s[24:25]
	s_mov_b64 s[6:7], 0
	s_waitcnt vmcnt(1)
	v_pk_mul_f32 v[126:127], v[114:115], v[82:83]
	v_pk_mul_f32 v[156:157], v[116:117], v[80:81]
	v_pk_mul_f32 v[158:159], v[110:111], v[82:83]
	v_pk_mul_f32 v[164:165], v[112:113], v[80:81]
	v_pk_mul_f32 v[166:167], v[122:123], v[82:83]
	v_pk_mul_f32 v[168:169], v[124:125], v[80:81]
	v_pk_mul_f32 v[82:83], v[118:119], v[82:83]
	v_pk_mul_f32 v[80:81], v[120:121], v[80:81]
	s_waitcnt vmcnt(0)
	v_pk_fma_f32 v[110:111], v[110:111], v[108:109], v[126:127] neg_lo:[0,0,1] neg_hi:[0,0,1]
	v_pk_fma_f32 v[112:113], v[112:113], v[106:107], v[156:157] neg_lo:[0,0,1] neg_hi:[0,0,1]
	v_pk_fma_f32 v[114:115], v[114:115], v[108:109], v[158:159]
	v_pk_fma_f32 v[116:117], v[116:117], v[106:107], v[164:165]
	v_pk_fma_f32 v[118:119], v[118:119], v[108:109], v[166:167] neg_lo:[0,0,1] neg_hi:[0,0,1]
	v_pk_fma_f32 v[120:121], v[120:121], v[106:107], v[168:169] neg_lo:[0,0,1] neg_hi:[0,0,1]
	v_pk_fma_f32 v[108:109], v[122:123], v[108:109], v[82:83]
	v_pk_fma_f32 v[106:107], v[124:125], v[106:107], v[80:81]
	v_cvt_pk_bf16_f32 v80, v112, v113
	v_cvt_pk_bf16_f32 v81, v110, v111
	v_cvt_pk_bf16_f32 v82, v116, v117
	v_cvt_pk_bf16_f32 v83, v114, v115
	global_store_dwordx4 v[154:155], v[80:83], off offset:256
	s_nop 1
	v_cvt_pk_bf16_f32 v80, v120, v121
	v_cvt_pk_bf16_f32 v81, v118, v119
	v_cvt_pk_bf16_f32 v82, v106, v107
	v_cvt_pk_bf16_f32 v83, v108, v109

; __device__ __forceinline__ u32x4 pack8bf(const f32x4 a, const f32x4 b) { u32x4 w; w.x = cvt_pk_bf16(a[0], a[1]); w.y = cvt_pk_bf16(a[2], a[3]); w.z = cvt_pk_bf16(b[0], b[1]); w.w = cvt_pk_bf16(b[2], b[3]); return w; }
; __device__ __forceinline__ float rms_scale(const float* ssq, int row, int which) {
;     const f32x4 a = *(const f32x4*)(ssq + (size_t)row * 16 + which * 8), b = *(const f32x4*)(ssq + (size_t)row * 16 + which * 8 + 4);
;     const float s = ((a[0] + a[1]) + (a[2] + a[3])) + ((b[0] + b[1]) + (b[2] + b[3]));
;     return 1.0f / sqrtf(s * (1.0f / 512.0f) + RMS_EPS);
; }
;     __device__ __forceinline__ void operator()(EPI_ARGS) const {
;     ...
;             for (int m = 0; m < 4; ++m) { const int row = row0 + ai * HALF + m * 16; const float rs = rms_scale(ssq, row, 0);
;                 if (u.pn < 8) {
; #pragma unroll
;                     for (int bj = 0; bj < 2; ++bj) { const int h = 2 * u.pn + bj;
;                         *(u32x4*)(Q + ((size_t)h * NTOK + row) * 192 + 32 * wc + 8 * fq) = pack8bf(acc[ai][bj][m][0] * rs, acc[ai][bj][m][1] * rs); }
;                 } else { const int fi = 16 * (wc & 1) + 4 * fq;
;                     const f32x4 c4 = *(const f32x4*)(cs + (size_t)row * 32 + fi), s4 = *(const f32x4*)(sn + (size_t)row * 32 + fi);
; #pragma unroll
;                     for (int bj = 0; bj < 2; ++bj) { const int h = 4 * (u.pn - 8) + 2 * bj + (wc >> 1); const f32x4 v0 = acc[ai][bj][m][0] * rs, v1 = acc[ai][bj][m][1] * rs;
;                         *(u32x4*)(Q + ((size_t)h * NTOK + row) * 192 + 128 + 32 * (wc & 1) + 8 * fq) = pack8bf(v0 * c4 - v1 * s4, v1 * c4 + v0 * s4); } }
.LBB0_4069:
	v_lshl_add_u64 v[84:85], v[104:105], 0, v[136:137]
	global_store_dwordx4 v[84:85], v[80:83], off
	v_cvt_f32_i32_e32 v77, v77
	v_cvt_f32_i32_e32 v76, v76
	v_or_b32_e32 v80, 48, v152
	v_ashrrev_i32_e32 v81, 31, v80
	v_mov_b32_e32 v86, v214
	v_mov_b32_e32 v87, v215
	v_mov_b32_e32 v88, v216
	v_mov_b32_e32 v89, v217
	v_mov_b32_e32 v90, v218
	v_mov_b32_e32 v91, v219
	v_mov_b32_e32 v92, v220
	v_mov_b32_e32 v93, v221
	v_cvt_f32_i32_e32 v79, v79
	v_cvt_f32_i32_e32 v78, v78
	v_cvt_f32_i32_e32 v73, v73
	v_cvt_f32_i32_e32 v72, v72
	v_pk_mul_f32 v[84:85], v[76:77], s[26:27] op_sel_hi:[1,0]
	v_pk_mul_f32 v[82:83], v[78:79], s[26:27] op_sel_hi:[1,0]
	v_cvt_f32_i32_e32 v69, v69
	v_pk_mul_f32 v[78:79], v[72:73], s[26:27] op_sel_hi:[1,0]
	v_cvt_f32_i32_e32 v68, v68
	v_cvt_f32_i32_e32 v67, v67
	v_cvt_f32_i32_e32 v66, v66
	v_cvt_f32_i32_e32 v65, v65
	v_cvt_f32_i32_e32 v64, v64
	v_cvt_f32_i32_e32 v75, v75
	v_cvt_f32_i32_e32 v74, v74
	v_cvt_f32_i32_e32 v71, v71
	v_cvt_f32_i32_e32 v70, v70
	v_pk_mul_f32 v[74:75], v[74:75], s[26:27] op_sel_hi:[1,0]
	v_pk_mul_f32 v[70:71], v[70:71], s[26:27] op_sel_hi:[1,0]
	v_add_f32_e32 v72, v86, v87
	v_add_f32_e32 v73, v88, v89
	v_add_f32_e32 v76, v90, v91
	v_add_f32_e32 v77, v92, v93
	v_add_f32_e32 v72, v72, v73
	v_add_f32_e32 v73, v76, v77
	v_add_f32_e32 v72, v72, v73
	v_fmamk_f32 v72, v72, 0x3b000000, v162
	v_rsq_f32_e32 v254, v72
	s_nop 1
	v_pk_mul_f32 v[72:73], v[68:69], s[26:27] op_sel_hi:[1,0]
	v_pk_mul_f32 v[68:69], v[66:67], s[26:27] op_sel_hi:[1,0]
	s_nop 1
	s_nop 1
	s_nop 1
	v_pk_mul_f32 v[76:77], v[64:65], s[26:27] op_sel_hi:[1,0]
	s_and_b64 vcc, exec, s[4:5]
	v_mov_b32_e32 v86, v254
	s_mov_b64 s[6:7], -1
	s_cbranch_vccnz .LBB0_4071
	v_lshlrev_b64 v[88:89], 7, v[80:81]
	v_lshl_add_u64 v[64:65], v[142:143], 0, v[88:89]
	global_load_dwordx4 v[64:67], v[64:65], off
	v_lshl_add_u64 v[88:89], v[140:141], 0, v[88:89]
	global_load_dwordx4 v[90:93], v[88:89], off
	s_or_b32 s6, s40, 2
	s_ashr_i32 s41, s40, 31
	s_ashr_i32 s7, s6, 31
	s_lshl_b64 s[44:45], s[40:41], 14
	s_lshl_b64 s[6:7], s[6:7], 14
	v_mov_b64_e32 v[88:89], s[20:21]
	v_lshl_add_u64 v[110:111], s[44:45], 0, v[80:81]
	v_lshl_add_u64 v[114:115], s[6:7], 0, v[80:81]
	v_pk_mul_f32 v[94:95], v[82:83], v[86:87] op_sel_hi:[1,0]
	v_pk_mul_f32 v[96:97], v[84:85], v[86:87] op_sel_hi:[1,0]
	v_pk_mul_f32 v[98:99], v[74:75], v[86:87] op_sel_hi:[1,0]
	v_pk_mul_f32 v[100:101], v[78:79], v[86:87] op_sel_hi:[1,0]
	v_pk_mul_f32 v[102:103], v[70:71], v[86:87] op_sel_hi:[1,0]
	v_pk_mul_f32 v[104:105], v[72:73], v[86:87] op_sel_hi:[1,0]
	v_pk_mul_f32 v[106:107], v[68:69], v[86:87] op_sel_hi:[1,0]
	v_pk_mul_f32 v[108:109], v[76:77], v[86:87] op_sel_hi:[1,0]
	v_mad_u64_u32 v[112:113], s[44:45], v110, s81, v[146:147]
	v_mad_u64_u32 v[88:89], s[6:7], v114, s81, v[88:89]
	v_mad_i32_i24 v113, v111, s81, v113
	v_mad_i32_i24 v89, v115, s81, v89
	v_lshl_add_u64 v[88:89], v[88:89], 0, s[24:25]
	s_mov_b64 s[6:7], 0
	s_waitcnt vmcnt(1)
	v_pk_mul_f32 v[110:111], v[98:99], v[66:67]
	v_pk_mul_f32 v[114:115], v[100:101], v[64:65]
	v_pk_mul_f32 v[116:117], v[94:95], v[66:67]
	v_pk_mul_f32 v[118:119], v[96:97], v[64:65]
	v_pk_mul_f32 v[120:121], v[106:107], v[66:67]
	v_pk_mul_f32 v[122:123], v[108:109], v[64:65]
	v_pk_mul_f32 v[66:67], v[102:103], v[66:67]
	v_pk_mul_f32 v[64:65], v[104:105], v[64:65]
	s_waitcnt vmcnt(0)
	v_pk_fma_f32 v[94:95], v[94:95], v[92:93], v[110:111] neg_lo:[0,0,1] neg_hi:[0,0,1]
	v_pk_fma_f32 v[96:97], v[96:97], v[90:91], v[114:115] neg_lo:[0,0,1] neg_hi:[0,0,1]
	v_pk_fma_f32 v[98:99], v[98:99], v[92:93], v[116:117]
	v_pk_fma_f32 v[100:101], v[100:101], v[90:91], v[118:119]
	v_pk_fma_f32 v[102:103], v[102:103], v[92:93], v[120:121] neg_lo:[0,0,1] neg_hi:[0,0,1]
	v_pk_fma_f32 v[104:105], v[104:105], v[90:91], v[122:123] neg_lo:[0,0,1] neg_hi:[0,0,1]
	v_pk_fma_f32 v[92:93], v[106:107], v[92:93], v[66:67]
	v_pk_fma_f32 v[90:91], v[108:109], v[90:91], v[64:65]
	v_cvt_pk_bf16_f32 v64, v96, v97
	v_cvt_pk_bf16_f32 v65, v94, v95
	v_cvt_pk_bf16_f32 v66, v100, v101
	v_cvt_pk_bf16_f32 v67, v98, v99
	global_store_dwordx4 v[112:113], v[64:67], off offset:256
	s_nop 1
	v_cvt_pk_bf16_f32 v64, v104, v105
	v_cvt_pk_bf16_f32 v65, v102, v103
	v_cvt_pk_bf16_f32 v66, v90, v91
	v_cvt_pk_bf16_f32 v67, v92, v93

; __device__ __forceinline__ u32x4 pack8bf(const f32x4 a, const f32x4 b) { u32x4 w; w.x = cvt_pk_bf16(a[0], a[1]); w.y = cvt_pk_bf16(a[2], a[3]); w.z = cvt_pk_bf16(b[0], b[1]); w.w = cvt_pk_bf16(b[2], b[3]); return w; }
; __device__ __forceinline__ float rms_scale(const float* ssq, int row, int which) {
;     const f32x4 a = *(const f32x4*)(ssq + (size_t)row * 16 + which * 8), b = *(const f32x4*)(ssq + (size_t)row * 16 + which * 8 + 4);
;     const float s = ((a[0] + a[1]) + (a[2] + a[3])) + ((b[0] + b[1]) + (b[2] + b[3]));
;     return 1.0f / sqrtf(s * (1.0f / 512.0f) + RMS_EPS);
; }
;     __device__ __forceinline__ void operator()(EPI_ARGS) const {
;     ...
;             for (int m = 0; m < 4; ++m) { const int row = row0 + ai * HALF + m * 16; const float rs = rms_scale(ssq, row, 0);
;                 if (u.pn < 8) {
; #pragma unroll
;                     for (int bj = 0; bj < 2; ++bj) { const int h = 2 * u.pn + bj;
;                         *(u32x4*)(Q + ((size_t)h * NTOK + row) * 192 + 32 * wc + 8 * fq) = pack8bf(acc[ai][bj][m][0] * rs, acc[ai][bj][m][1] * rs); }
;                 } else { const int fi = 16 * (wc & 1) + 4 * fq;
;                     const f32x4 c4 = *(const f32x4*)(cs + (size_t)row * 32 + fi), s4 = *(const f32x4*)(sn + (size_t)row * 32 + fi);
; #pragma unroll
;                     for (int bj = 0; bj < 2; ++bj) { const int h = 4 * (u.pn - 8) + 2 * bj + (wc >> 1); const f32x4 v0 = acc[ai][bj][m][0] * rs, v1 = acc[ai][bj][m][1] * rs;
;                         *(u32x4*)(Q + ((size_t)h * NTOK + row) * 192 + 128 + 32 * (wc & 1) + 8 * fq) = pack8bf(v0 * c4 - v1 * s4, v1 * c4 + v0 * s4); } }
.LBB0_4073:
	v_lshl_add_u64 v[68:69], v[88:89], 0, v[136:137]
	global_store_dwordx4 v[68:69], v[64:67], off
	v_cvt_f32_i32_e32 v61, v61
	v_cvt_f32_i32_e32 v60, v60
	v_add_u32_e32 v64, 0x80, v152
	v_ashrrev_i32_e32 v65, 31, v64
	v_mov_b32_e32 v70, v222
	v_mov_b32_e32 v71, v223
	v_mov_b32_e32 v72, v224
	v_mov_b32_e32 v73, v225
	v_mov_b32_e32 v74, v226
	v_mov_b32_e32 v75, v227
	v_mov_b32_e32 v76, v228
	v_mov_b32_e32 v77, v229
	v_cvt_f32_i32_e32 v63, v63
	v_cvt_f32_i32_e32 v62, v62
	v_cvt_f32_i32_e32 v57, v57
	v_cvt_f32_i32_e32 v56, v56
	v_pk_mul_f32 v[68:69], v[60:61], s[26:27] op_sel_hi:[1,0]
	v_pk_mul_f32 v[66:67], v[62:63], s[26:27] op_sel_hi:[1,0]
	v_cvt_f32_i32_e32 v53, v53
	v_pk_mul_f32 v[62:63], v[56:57], s[26:27] op_sel_hi:[1,0]
	v_cvt_f32_i32_e32 v52, v52
	v_cvt_f32_i32_e32 v51, v51
	v_cvt_f32_i32_e32 v50, v50
	v_cvt_f32_i32_e32 v49, v49
	v_cvt_f32_i32_e32 v48, v48
	v_cvt_f32_i32_e32 v59, v59
	v_cvt_f32_i32_e32 v58, v58
	v_cvt_f32_i32_e32 v55, v55
	v_cvt_f32_i32_e32 v54, v54
	v_pk_mul_f32 v[58:59], v[58:59], s[26:27] op_sel_hi:[1,0]
	v_pk_mul_f32 v[54:55], v[54:55], s[26:27] op_sel_hi:[1,0]
	v_add_f32_e32 v56, v70, v71
	v_add_f32_e32 v57, v72, v73
	v_add_f32_e32 v60, v74, v75
	v_add_f32_e32 v61, v76, v77
	v_add_f32_e32 v56, v56, v57
	v_add_f32_e32 v57, v60, v61
	v_add_f32_e32 v56, v56, v57
	v_fmamk_f32 v56, v56, 0x3b000000, v162
	v_rsq_f32_e32 v254, v56
	s_nop 1
	v_pk_mul_f32 v[56:57], v[52:53], s[26:27] op_sel_hi:[1,0]
	v_pk_mul_f32 v[52:53], v[50:51], s[26:27] op_sel_hi:[1,0]
	s_nop 1
	s_nop 1
	s_nop 1
	v_pk_mul_f32 v[60:61], v[48:49], s[26:27] op_sel_hi:[1,0]
	s_and_b64 vcc, exec, s[4:5]
	v_mov_b32_e32 v70, v254
	s_mov_b64 s[6:7], -1
	s_cbranch_vccnz .LBB0_4075
	v_lshlrev_b64 v[72:73], 7, v[64:65]
	v_lshl_add_u64 v[48:49], v[142:143], 0, v[72:73]
	global_load_dwordx4 v[48:51], v[48:49], off
	v_lshl_add_u64 v[72:73], v[140:141], 0, v[72:73]
	global_load_dwordx4 v[74:77], v[72:73], off
	s_or_b32 s6, s40, 2
	s_ashr_i32 s41, s40, 31
	s_ashr_i32 s7, s6, 31
	s_lshl_b64 s[44:45], s[40:41], 14
	s_lshl_b64 s[6:7], s[6:7], 14
	v_mov_b64_e32 v[72:73], s[20:21]
	v_lshl_add_u64 v[94:95], s[44:45], 0, v[64:65]
	v_lshl_add_u64 v[98:99], s[6:7], 0, v[64:65]
	v_pk_mul_f32 v[78:79], v[66:67], v[70:71] op_sel_hi:[1,0]
	v_pk_mul_f32 v[80:81], v[68:69], v[70:71] op_sel_hi:[1,0]
	v_pk_mul_f32 v[82:83], v[58:59], v[70:71] op_sel_hi:[1,0]
	v_pk_mul_f32 v[84:85], v[62:63], v[70:71] op_sel_hi:[1,0]
	v_pk_mul_f32 v[86:87], v[54:55], v[70:71] op_sel_hi:[1,0]
	v_pk_mul_f32 v[88:89], v[56:57], v[70:71] op_sel_hi:[1,0]
	v_pk_mul_f32 v[90:91], v[52:53], v[70:71] op_sel_hi:[1,0]
	v_pk_mul_f32 v[92:93], v[60:61], v[70:71] op_sel_hi:[1,0]
	v_mad_u64_u32 v[96:97], s[44:45], v94, s81, v[146:147]
	v_mad_u64_u32 v[72:73], s[6:7], v98, s81, v[72:73]
	v_mad_i32_i24 v97, v95, s81, v97
	v_mad_i32_i24 v73, v99, s81, v73
	v_lshl_add_u64 v[72:73], v[72:73], 0, s[24:25]
	s_mov_b64 s[6:7], 0
	s_waitcnt vmcnt(1)
	v_pk_mul_f32 v[94:95], v[82:83], v[50:51]
	v_pk_mul_f32 v[98:99], v[84:85], v[48:49]
	v_pk_mul_f32 v[100:101], v[78:79], v[50:51]
	v_pk_mul_f32 v[102:103], v[80:81], v[48:49]
	v_pk_mul_f32 v[104:105], v[90:91], v[50:51]
	v_pk_mul_f32 v[106:107], v[92:93], v[48:49]
	v_pk_mul_f32 v[50:51], v[86:87], v[50:51]
	v_pk_mul_f32 v[48:49], v[88:89], v[48:49]
	s_waitcnt vmcnt(0)
	v_pk_fma_f32 v[78:79], v[78:79], v[76:77], v[94:95] neg_lo:[0,0,1] neg_hi:[0,0,1]
	v_pk_fma_f32 v[80:81], v[80:81], v[74:75], v[98:99] neg_lo:[0,0,1] neg_hi:[0,0,1]
	v_pk_fma_f32 v[82:83], v[82:83], v[76:77], v[100:101]
	v_pk_fma_f32 v[84:85], v[84:85], v[74:75], v[102:103]
	v_pk_fma_f32 v[86:87], v[86:87], v[76:77], v[104:105] neg_lo:[0,0,1] neg_hi:[0,0,1]
	v_pk_fma_f32 v[88:89], v[88:89], v[74:75], v[106:107] neg_lo:[0,0,1] neg_hi:[0,0,1]
	v_pk_fma_f32 v[76:77], v[90:91], v[76:77], v[50:51]
	v_pk_fma_f32 v[74:75], v[92:93], v[74:75], v[48:49]
	v_cvt_pk_bf16_f32 v48, v80, v81
	v_cvt_pk_bf16_f32 v49, v78, v79
	v_cvt_pk_bf16_f32 v50, v84, v85
	v_cvt_pk_bf16_f32 v51, v82, v83
	global_store_dwordx4 v[96:97], v[48:51], off offset:256
	s_nop 1
	v_cvt_pk_bf16_f32 v48, v88, v89
	v_cvt_pk_bf16_f32 v49, v86, v87
	v_cvt_pk_bf16_f32 v50, v74, v75
	v_cvt_pk_bf16_f32 v51, v76, v77

; __device__ __forceinline__ u32x4 pack8bf(const f32x4 a, const f32x4 b) { u32x4 w; w.x = cvt_pk_bf16(a[0], a[1]); w.y = cvt_pk_bf16(a[2], a[3]); w.z = cvt_pk_bf16(b[0], b[1]); w.w = cvt_pk_bf16(b[2], b[3]); return w; }
; __device__ __forceinline__ float rms_scale(const float* ssq, int row, int which) {
;     const f32x4 a = *(const f32x4*)(ssq + (size_t)row * 16 + which * 8), b = *(const f32x4*)(ssq + (size_t)row * 16 + which * 8 + 4);
;     const float s = ((a[0] + a[1]) + (a[2] + a[3])) + ((b[0] + b[1]) + (b[2] + b[3]));
;     return 1.0f / sqrtf(s * (1.0f / 512.0f) + RMS_EPS);
; }
;     __device__ __forceinline__ void operator()(EPI_ARGS) const {
;     ...
;             for (int m = 0; m < 4; ++m) { const int row = row0 + ai * HALF + m * 16; const float rs = rms_scale(ssq, row, 0);
;                 if (u.pn < 8) {
; #pragma unroll
;                     for (int bj = 0; bj < 2; ++bj) { const int h = 2 * u.pn + bj;
;                         *(u32x4*)(Q + ((size_t)h * NTOK + row) * 192 + 32 * wc + 8 * fq) = pack8bf(acc[ai][bj][m][0] * rs, acc[ai][bj][m][1] * rs); }
;                 } else { const int fi = 16 * (wc & 1) + 4 * fq;
;                     const f32x4 c4 = *(const f32x4*)(cs + (size_t)row * 32 + fi), s4 = *(const f32x4*)(sn + (size_t)row * 32 + fi);
; #pragma unroll
;                     for (int bj = 0; bj < 2; ++bj) { const int h = 4 * (u.pn - 8) + 2 * bj + (wc >> 1); const f32x4 v0 = acc[ai][bj][m][0] * rs, v1 = acc[ai][bj][m][1] * rs;
;                         *(u32x4*)(Q + ((size_t)h * NTOK + row) * 192 + 128 + 32 * (wc & 1) + 8 * fq) = pack8bf(v0 * c4 - v1 * s4, v1 * c4 + v0 * s4); } }
.LBB0_4077:
	v_lshl_add_u64 v[52:53], v[72:73], 0, v[136:137]
	global_store_dwordx4 v[52:53], v[48:51], off
	v_cvt_f32_i32_e32 v45, v45
	v_cvt_f32_i32_e32 v44, v44
	v_add_u32_e32 v48, 0x90, v152
	v_ashrrev_i32_e32 v49, 31, v48
	v_mov_b32_e32 v54, v230
	v_mov_b32_e32 v55, v231
	v_mov_b32_e32 v56, v232
	v_mov_b32_e32 v57, v233
	v_mov_b32_e32 v58, v234
	v_mov_b32_e32 v59, v235
	v_mov_b32_e32 v60, v236
	v_mov_b32_e32 v61, v237
	v_cvt_f32_i32_e32 v47, v47
	v_cvt_f32_i32_e32 v46, v46
	v_cvt_f32_i32_e32 v41, v41
	v_cvt_f32_i32_e32 v40, v40
	v_pk_mul_f32 v[52:53], v[44:45], s[26:27] op_sel_hi:[1,0]
	v_pk_mul_f32 v[50:51], v[46:47], s[26:27] op_sel_hi:[1,0]
	v_cvt_f32_i32_e32 v37, v37
	v_pk_mul_f32 v[46:47], v[40:41], s[26:27] op_sel_hi:[1,0]
	v_cvt_f32_i32_e32 v36, v36
	v_cvt_f32_i32_e32 v35, v35
	v_cvt_f32_i32_e32 v34, v34
	v_cvt_f32_i32_e32 v33, v33
	v_cvt_f32_i32_e32 v32, v32
	v_cvt_f32_i32_e32 v43, v43
	v_cvt_f32_i32_e32 v42, v42
	v_cvt_f32_i32_e32 v39, v39
	v_cvt_f32_i32_e32 v38, v38
	v_pk_mul_f32 v[42:43], v[42:43], s[26:27] op_sel_hi:[1,0]
	v_pk_mul_f32 v[38:39], v[38:39], s[26:27] op_sel_hi:[1,0]
	v_add_f32_e32 v40, v54, v55
	v_add_f32_e32 v41, v56, v57
	v_add_f32_e32 v44, v58, v59
	v_add_f32_e32 v45, v60, v61
	v_add_f32_e32 v40, v40, v41
	v_add_f32_e32 v41, v44, v45
	v_add_f32_e32 v40, v40, v41
	v_fmamk_f32 v40, v40, 0x3b000000, v162
	v_rsq_f32_e32 v254, v40
	s_nop 1
	v_pk_mul_f32 v[40:41], v[36:37], s[26:27] op_sel_hi:[1,0]
	v_pk_mul_f32 v[36:37], v[34:35], s[26:27] op_sel_hi:[1,0]
	s_nop 1
	s_nop 1
	s_nop 1
	v_pk_mul_f32 v[44:45], v[32:33], s[26:27] op_sel_hi:[1,0]
	s_and_b64 vcc, exec, s[4:5]
	v_mov_b32_e32 v54, v254
	s_mov_b64 s[6:7], -1
	s_cbranch_vccnz .LBB0_4079
	v_lshlrev_b64 v[56:57], 7, v[48:49]
	v_lshl_add_u64 v[32:33], v[142:143], 0, v[56:57]
	global_load_dwordx4 v[32:35], v[32:33], off
	v_lshl_add_u64 v[56:57], v[140:141], 0, v[56:57]
	global_load_dwordx4 v[58:61], v[56:57], off
	s_or_b32 s6, s40, 2
	s_ashr_i32 s41, s40, 31
	s_ashr_i32 s7, s6, 31
	s_lshl_b64 s[44:45], s[40:41], 14
	s_lshl_b64 s[6:7], s[6:7], 14
	v_mov_b64_e32 v[56:57], s[20:21]
	v_lshl_add_u64 v[78:79], s[44:45], 0, v[48:49]
	v_lshl_add_u64 v[82:83], s[6:7], 0, v[48:49]
	v_pk_mul_f32 v[62:63], v[50:51], v[54:55] op_sel_hi:[1,0]
	v_pk_mul_f32 v[64:65], v[52:53], v[54:55] op_sel_hi:[1,0]
	v_pk_mul_f32 v[66:67], v[42:43], v[54:55] op_sel_hi:[1,0]
	v_pk_mul_f32 v[68:69], v[46:47], v[54:55] op_sel_hi:[1,0]
	v_pk_mul_f32 v[70:71], v[38:39], v[54:55] op_sel_hi:[1,0]
	v_pk_mul_f32 v[72:73], v[40:41], v[54:55] op_sel_hi:[1,0]
	v_pk_mul_f32 v[74:75], v[36:37], v[54:55] op_sel_hi:[1,0]
	v_pk_mul_f32 v[76:77], v[44:45], v[54:55] op_sel_hi:[1,0]
	v_mad_u64_u32 v[80:81], s[44:45], v78, s81, v[146:147]
	v_mad_u64_u32 v[56:57], s[6:7], v82, s81, v[56:57]
	v_mad_i32_i24 v81, v79, s81, v81
	v_mad_i32_i24 v57, v83, s81, v57
	v_lshl_add_u64 v[56:57], v[56:57], 0, s[24:25]
	s_mov_b64 s[6:7], 0
	s_waitcnt vmcnt(1)
	v_pk_mul_f32 v[78:79], v[66:67], v[34:35]
	v_pk_mul_f32 v[82:83], v[68:69], v[32:33]
	v_pk_mul_f32 v[84:85], v[62:63], v[34:35]
	v_pk_mul_f32 v[86:87], v[64:65], v[32:33]
	v_pk_mul_f32 v[88:89], v[74:75], v[34:35]
	v_pk_mul_f32 v[90:91], v[76:77], v[32:33]
	v_pk_mul_f32 v[34:35], v[70:71], v[34:35]
	v_pk_mul_f32 v[32:33], v[72:73], v[32:33]
	s_waitcnt vmcnt(0)
	v_pk_fma_f32 v[62:63], v[62:63], v[60:61], v[78:79] neg_lo:[0,0,1] neg_hi:[0,0,1]
	v_pk_fma_f32 v[64:65], v[64:65], v[58:59], v[82:83] neg_lo:[0,0,1] neg_hi:[0,0,1]
	v_pk_fma_f32 v[66:67], v[66:67], v[60:61], v[84:85]
	v_pk_fma_f32 v[68:69], v[68:69], v[58:59], v[86:87]
	v_pk_fma_f32 v[70:71], v[70:71], v[60:61], v[88:89] neg_lo:[0,0,1] neg_hi:[0,0,1]
	v_pk_fma_f32 v[72:73], v[72:73], v[58:59], v[90:91] neg_lo:[0,0,1] neg_hi:[0,0,1]
	v_pk_fma_f32 v[60:61], v[74:75], v[60:61], v[34:35]
	v_pk_fma_f32 v[58:59], v[76:77], v[58:59], v[32:33]
	v_cvt_pk_bf16_f32 v32, v64, v65
	v_cvt_pk_bf16_f32 v33, v62, v63
	v_cvt_pk_bf16_f32 v34, v68, v69
	v_cvt_pk_bf16_f32 v35, v66, v67
	global_store_dwordx4 v[80:81], v[32:35], off offset:256
	s_nop 1
	v_cvt_pk_bf16_f32 v32, v72, v73
	v_cvt_pk_bf16_f32 v33, v70, v71
	v_cvt_pk_bf16_f32 v34, v58, v59
	v_cvt_pk_bf16_f32 v35, v60, v61

; __device__ __forceinline__ u32x4 pack8bf(const f32x4 a, const f32x4 b) { u32x4 w; w.x = cvt_pk_bf16(a[0], a[1]); w.y = cvt_pk_bf16(a[2], a[3]); w.z = cvt_pk_bf16(b[0], b[1]); w.w = cvt_pk_bf16(b[2], b[3]); return w; }
; __device__ __forceinline__ float rms_scale(const float* ssq, int row, int which) {
;     const f32x4 a = *(const f32x4*)(ssq + (size_t)row * 16 + which * 8), b = *(const f32x4*)(ssq + (size_t)row * 16 + which * 8 + 4);
;     const float s = ((a[0] + a[1]) + (a[2] + a[3])) + ((b[0] + b[1]) + (b[2] + b[3]));
;     return 1.0f / sqrtf(s * (1.0f / 512.0f) + RMS_EPS);
; }
;     __device__ __forceinline__ void operator()(EPI_ARGS) const {
;     ...
;             for (int m = 0; m < 4; ++m) { const int row = row0 + ai * HALF + m * 16; const float rs = rms_scale(ssq, row, 0);
;                 if (u.pn < 8) {
; #pragma unroll
;                     for (int bj = 0; bj < 2; ++bj) { const int h = 2 * u.pn + bj;
;                         *(u32x4*)(Q + ((size_t)h * NTOK + row) * 192 + 32 * wc + 8 * fq) = pack8bf(acc[ai][bj][m][0] * rs, acc[ai][bj][m][1] * rs); }
;                 } else { const int fi = 16 * (wc & 1) + 4 * fq;
;                     const f32x4 c4 = *(const f32x4*)(cs + (size_t)row * 32 + fi), s4 = *(const f32x4*)(sn + (size_t)row * 32 + fi);
; #pragma unroll
;                     for (int bj = 0; bj < 2; ++bj) { const int h = 4 * (u.pn - 8) + 2 * bj + (wc >> 1); const f32x4 v0 = acc[ai][bj][m][0] * rs, v1 = acc[ai][bj][m][1] * rs;
;                         *(u32x4*)(Q + ((size_t)h * NTOK + row) * 192 + 128 + 32 * (wc & 1) + 8 * fq) = pack8bf(v0 * c4 - v1 * s4, v1 * c4 + v0 * s4); } }
.LBB0_4081:
	v_lshl_add_u64 v[36:37], v[56:57], 0, v[136:137]
	global_store_dwordx4 v[36:37], v[32:35], off
	v_cvt_f32_i32_e32 v29, v29
	v_cvt_f32_i32_e32 v28, v28
	v_add_u32_e32 v32, 0xa0, v152
	v_ashrrev_i32_e32 v33, 31, v32
	v_mov_b32_e32 v38, v238
	v_mov_b32_e32 v39, v239
	v_mov_b32_e32 v40, v240
	v_mov_b32_e32 v41, v241
	v_mov_b32_e32 v42, v242
	v_mov_b32_e32 v43, v243
	v_mov_b32_e32 v44, v244
	v_mov_b32_e32 v45, v245
	v_cvt_f32_i32_e32 v31, v31
	v_cvt_f32_i32_e32 v30, v30
	v_cvt_f32_i32_e32 v25, v25
	v_cvt_f32_i32_e32 v24, v24
	v_pk_mul_f32 v[36:37], v[28:29], s[26:27] op_sel_hi:[1,0]
	v_pk_mul_f32 v[34:35], v[30:31], s[26:27] op_sel_hi:[1,0]
	v_cvt_f32_i32_e32 v21, v21
	v_pk_mul_f32 v[30:31], v[24:25], s[26:27] op_sel_hi:[1,0]
	v_cvt_f32_i32_e32 v20, v20
	v_cvt_f32_i32_e32 v19, v19
	v_cvt_f32_i32_e32 v18, v18
	v_cvt_f32_i32_e32 v17, v17
	v_cvt_f32_i32_e32 v16, v16
	v_cvt_f32_i32_e32 v27, v27
	v_cvt_f32_i32_e32 v26, v26
	v_cvt_f32_i32_e32 v23, v23
	v_cvt_f32_i32_e32 v22, v22
	v_pk_mul_f32 v[26:27], v[26:27], s[26:27] op_sel_hi:[1,0]
	v_pk_mul_f32 v[22:23], v[22:23], s[26:27] op_sel_hi:[1,0]
	v_add_f32_e32 v24, v38, v39
	v_add_f32_e32 v25, v40, v41
	v_add_f32_e32 v28, v42, v43
	v_add_f32_e32 v29, v44, v45
	v_add_f32_e32 v24, v24, v25
	v_add_f32_e32 v25, v28, v29
	v_add_f32_e32 v24, v24, v25
	v_fmamk_f32 v24, v24, 0x3b000000, v162
	v_rsq_f32_e32 v254, v24
	s_nop 1
	v_pk_mul_f32 v[24:25], v[20:21], s[26:27] op_sel_hi:[1,0]
	v_pk_mul_f32 v[20:21], v[18:19], s[26:27] op_sel_hi:[1,0]
	s_nop 1
	s_nop 1
	s_nop 1
	v_pk_mul_f32 v[28:29], v[16:17], s[26:27] op_sel_hi:[1,0]
	s_and_b64 vcc, exec, s[4:5]
	v_mov_b32_e32 v38, v254
	s_mov_b64 s[6:7], -1
	s_cbranch_vccnz .LBB0_4083
	v_lshlrev_b64 v[40:41], 7, v[32:33]
	v_lshl_add_u64 v[16:17], v[142:143], 0, v[40:41]
	global_load_dwordx4 v[16:19], v[16:17], off
	v_lshl_add_u64 v[40:41], v[140:141], 0, v[40:41]
	global_load_dwordx4 v[42:45], v[40:41], off
	s_or_b32 s6, s40, 2
	s_ashr_i32 s41, s40, 31
	s_ashr_i32 s7, s6, 31
	s_lshl_b64 s[44:45], s[40:41], 14
	s_lshl_b64 s[6:7], s[6:7], 14
	v_mov_b64_e32 v[40:41], s[20:21]
	v_lshl_add_u64 v[62:63], s[44:45], 0, v[32:33]
	v_lshl_add_u64 v[66:67], s[6:7], 0, v[32:33]
	v_pk_mul_f32 v[46:47], v[34:35], v[38:39] op_sel_hi:[1,0]
	v_pk_mul_f32 v[48:49], v[36:37], v[38:39] op_sel_hi:[1,0]
	v_pk_mul_f32 v[50:51], v[26:27], v[38:39] op_sel_hi:[1,0]
	v_pk_mul_f32 v[52:53], v[30:31], v[38:39] op_sel_hi:[1,0]
	v_pk_mul_f32 v[54:55], v[22:23], v[38:39] op_sel_hi:[1,0]
	v_pk_mul_f32 v[56:57], v[24:25], v[38:39] op_sel_hi:[1,0]
	v_pk_mul_f32 v[58:59], v[20:21], v[38:39] op_sel_hi:[1,0]
	v_pk_mul_f32 v[60:61], v[28:29], v[38:39] op_sel_hi:[1,0]
	v_mad_u64_u32 v[64:65], s[44:45], v62, s81, v[146:147]
	v_mad_u64_u32 v[40:41], s[6:7], v66, s81, v[40:41]
	v_mad_i32_i24 v65, v63, s81, v65
	v_mad_i32_i24 v41, v67, s81, v41
	v_lshl_add_u64 v[40:41], v[40:41], 0, s[24:25]
	s_mov_b64 s[6:7], 0
	s_waitcnt vmcnt(1)
	v_pk_mul_f32 v[62:63], v[50:51], v[18:19]
	v_pk_mul_f32 v[66:67], v[52:53], v[16:17]
	v_pk_mul_f32 v[68:69], v[46:47], v[18:19]
	v_pk_mul_f32 v[70:71], v[48:49], v[16:17]
	v_pk_mul_f32 v[72:73], v[58:59], v[18:19]
	v_pk_mul_f32 v[74:75], v[60:61], v[16:17]
	v_pk_mul_f32 v[18:19], v[54:55], v[18:19]
	v_pk_mul_f32 v[16:17], v[56:57], v[16:17]
	s_waitcnt vmcnt(0)
	v_pk_fma_f32 v[46:47], v[46:47], v[44:45], v[62:63] neg_lo:[0,0,1] neg_hi:[0,0,1]
	v_pk_fma_f32 v[48:49], v[48:49], v[42:43], v[66:67] neg_lo:[0,0,1] neg_hi:[0,0,1]
	v_pk_fma_f32 v[50:51], v[50:51], v[44:45], v[68:69]
	v_pk_fma_f32 v[52:53], v[52:53], v[42:43], v[70:71]
	v_pk_fma_f32 v[54:55], v[54:55], v[44:45], v[72:73] neg_lo:[0,0,1] neg_hi:[0,0,1]
	v_pk_fma_f32 v[56:57], v[56:57], v[42:43], v[74:75] neg_lo:[0,0,1] neg_hi:[0,0,1]
	v_pk_fma_f32 v[44:45], v[58:59], v[44:45], v[18:19]
	v_pk_fma_f32 v[42:43], v[60:61], v[42:43], v[16:17]
	v_cvt_pk_bf16_f32 v16, v48, v49
	v_cvt_pk_bf16_f32 v17, v46, v47
	v_cvt_pk_bf16_f32 v18, v52, v53
	v_cvt_pk_bf16_f32 v19, v50, v51
	global_store_dwordx4 v[64:65], v[16:19], off offset:256
	s_nop 1
	v_cvt_pk_bf16_f32 v16, v56, v57
	v_cvt_pk_bf16_f32 v17, v54, v55
	v_cvt_pk_bf16_f32 v18, v42, v43
	v_cvt_pk_bf16_f32 v19, v44, v45

; __device__ __forceinline__ u32x4 pack8bf(const f32x4 a, const f32x4 b) { u32x4 w; w.x = cvt_pk_bf16(a[0], a[1]); w.y = cvt_pk_bf16(a[2], a[3]); w.z = cvt_pk_bf16(b[0], b[1]); w.w = cvt_pk_bf16(b[2], b[3]); return w; }
; __device__ __forceinline__ float rms_scale(const float* ssq, int row, int which) {
;     const f32x4 a = *(const f32x4*)(ssq + (size_t)row * 16 + which * 8), b = *(const f32x4*)(ssq + (size_t)row * 16 + which * 8 + 4);
;     const float s = ((a[0] + a[1]) + (a[2] + a[3])) + ((b[0] + b[1]) + (b[2] + b[3]));
;     return 1.0f / sqrtf(s * (1.0f / 512.0f) + RMS_EPS);
; }
;     __device__ __forceinline__ void operator()(EPI_ARGS) const {
;     ...
;             for (int m = 0; m < 4; ++m) { const int row = row0 + ai * HALF + m * 16; const float rs = rms_scale(ssq, row, 0);
;                 if (u.pn < 8) {
; #pragma unroll
;                     for (int bj = 0; bj < 2; ++bj) { const int h = 2 * u.pn + bj;
;                         *(u32x4*)(Q + ((size_t)h * NTOK + row) * 192 + 32 * wc + 8 * fq) = pack8bf(acc[ai][bj][m][0] * rs, acc[ai][bj][m][1] * rs); }
;                 } else { const int fi = 16 * (wc & 1) + 4 * fq;
;                     const f32x4 c4 = *(const f32x4*)(cs + (size_t)row * 32 + fi), s4 = *(const f32x4*)(sn + (size_t)row * 32 + fi);
; #pragma unroll
;                     for (int bj = 0; bj < 2; ++bj) { const int h = 4 * (u.pn - 8) + 2 * bj + (wc >> 1); const f32x4 v0 = acc[ai][bj][m][0] * rs, v1 = acc[ai][bj][m][1] * rs;
;                         *(u32x4*)(Q + ((size_t)h * NTOK + row) * 192 + 128 + 32 * (wc & 1) + 8 * fq) = pack8bf(v0 * c4 - v1 * s4, v1 * c4 + v0 * s4); } }
.LBB0_4085:
	v_lshl_add_u64 v[20:21], v[40:41], 0, v[136:137]
	global_store_dwordx4 v[20:21], v[16:19], off
	v_cvt_f32_i32_e32 v13, v13
	v_cvt_f32_i32_e32 v12, v12
	v_add_u32_e32 v16, 0xb0, v152
	v_ashrrev_i32_e32 v17, 31, v16
	v_mov_b32_e32 v22, v246
	v_mov_b32_e32 v23, v247
	v_mov_b32_e32 v24, v248
	v_mov_b32_e32 v25, v249
	v_mov_b32_e32 v26, v250
	v_mov_b32_e32 v27, v251
	v_mov_b32_e32 v28, v252
	v_mov_b32_e32 v29, v253
	v_cvt_f32_i32_e32 v15, v15
	v_cvt_f32_i32_e32 v14, v14
	v_cvt_f32_i32_e32 v9, v9
	v_cvt_f32_i32_e32 v8, v8
	v_pk_mul_f32 v[20:21], v[12:13], s[26:27] op_sel_hi:[1,0]
	v_pk_mul_f32 v[18:19], v[14:15], s[26:27] op_sel_hi:[1,0]
	v_cvt_f32_i32_e32 v5, v5
	v_pk_mul_f32 v[14:15], v[8:9], s[26:27] op_sel_hi:[1,0]
	v_cvt_f32_i32_e32 v4, v4
	v_cvt_f32_i32_e32 v3, v3
	v_cvt_f32_i32_e32 v2, v2
	v_cvt_f32_i32_e32 v1, v1
	v_cvt_f32_i32_e32 v0, v0
	v_cvt_f32_i32_e32 v11, v11
	v_cvt_f32_i32_e32 v10, v10
	v_cvt_f32_i32_e32 v7, v7
	v_cvt_f32_i32_e32 v6, v6
	v_pk_mul_f32 v[10:11], v[10:11], s[26:27] op_sel_hi:[1,0]
	v_pk_mul_f32 v[6:7], v[6:7], s[26:27] op_sel_hi:[1,0]
	v_add_f32_e32 v8, v22, v23
	v_add_f32_e32 v9, v24, v25
	v_add_f32_e32 v12, v26, v27
	v_add_f32_e32 v13, v28, v29
	v_add_f32_e32 v8, v8, v9
	v_add_f32_e32 v9, v12, v13
	v_add_f32_e32 v8, v8, v9
	v_fmamk_f32 v8, v8, 0x3b000000, v162
	v_rsq_f32_e32 v254, v8
	s_nop 1
	v_pk_mul_f32 v[8:9], v[4:5], s[26:27] op_sel_hi:[1,0]
	v_pk_mul_f32 v[4:5], v[2:3], s[26:27] op_sel_hi:[1,0]
	s_nop 1
	s_nop 1
	s_nop 1
	v_pk_mul_f32 v[12:13], v[0:1], s[26:27] op_sel_hi:[1,0]
	s_and_b64 vcc, exec, s[4:5]
	v_mov_b32_e32 v22, v254
	s_mov_b64 s[4:5], -1
	s_cbranch_vccnz .LBB0_4087
	v_lshlrev_b64 v[24:25], 7, v[16:17]
	v_lshl_add_u64 v[0:1], v[142:143], 0, v[24:25]
	global_load_dwordx4 v[0:3], v[0:1], off
	v_lshl_add_u64 v[24:25], v[140:141], 0, v[24:25]
	global_load_dwordx4 v[26:29], v[24:25], off
	s_or_b32 s4, s40, 2
	s_ashr_i32 s41, s40, 31
	s_ashr_i32 s5, s4, 31
	s_lshl_b64 s[6:7], s[40:41], 14
	s_lshl_b64 s[4:5], s[4:5], 14
	v_mov_b64_e32 v[24:25], s[20:21]
	v_lshl_add_u64 v[46:47], s[6:7], 0, v[16:17]
	v_lshl_add_u64 v[50:51], s[4:5], 0, v[16:17]
	v_pk_mul_f32 v[30:31], v[18:19], v[22:23] op_sel_hi:[1,0]
	v_pk_mul_f32 v[32:33], v[20:21], v[22:23] op_sel_hi:[1,0]
	v_pk_mul_f32 v[34:35], v[10:11], v[22:23] op_sel_hi:[1,0]
	v_pk_mul_f32 v[36:37], v[14:15], v[22:23] op_sel_hi:[1,0]
	v_pk_mul_f32 v[38:39], v[6:7], v[22:23] op_sel_hi:[1,0]
	v_pk_mul_f32 v[40:41], v[8:9], v[22:23] op_sel_hi:[1,0]
	v_pk_mul_f32 v[42:43], v[4:5], v[22:23] op_sel_hi:[1,0]
	v_pk_mul_f32 v[44:45], v[12:13], v[22:23] op_sel_hi:[1,0]
	v_mad_u64_u32 v[48:49], s[6:7], v46, s81, v[146:147]
	v_mad_u64_u32 v[24:25], s[4:5], v50, s81, v[24:25]
	v_mad_i32_i24 v49, v47, s81, v49
	v_mad_i32_i24 v25, v51, s81, v25
	v_lshl_add_u64 v[24:25], v[24:25], 0, s[24:25]
	s_mov_b64 s[4:5], 0
	s_waitcnt vmcnt(1)
	v_pk_mul_f32 v[46:47], v[34:35], v[2:3]
	v_pk_mul_f32 v[50:51], v[36:37], v[0:1]
	v_pk_mul_f32 v[52:53], v[30:31], v[2:3]
	v_pk_mul_f32 v[54:55], v[32:33], v[0:1]
	v_pk_mul_f32 v[56:57], v[42:43], v[2:3]
	v_pk_mul_f32 v[58:59], v[44:45], v[0:1]
	v_pk_mul_f32 v[2:3], v[38:39], v[2:3]
	v_pk_mul_f32 v[0:1], v[40:41], v[0:1]
	s_waitcnt vmcnt(0)
	v_pk_fma_f32 v[30:31], v[30:31], v[28:29], v[46:47] neg_lo:[0,0,1] neg_hi:[0,0,1]
	v_pk_fma_f32 v[32:33], v[32:33], v[26:27], v[50:51] neg_lo:[0,0,1] neg_hi:[0,0,1]
	v_pk_fma_f32 v[34:35], v[34:35], v[28:29], v[52:53]
	v_pk_fma_f32 v[36:37], v[36:37], v[26:27], v[54:55]
	v_pk_fma_f32 v[38:39], v[38:39], v[28:29], v[56:57] neg_lo:[0,0,1] neg_hi:[0,0,1]
	v_pk_fma_f32 v[40:41], v[40:41], v[26:27], v[58:59] neg_lo:[0,0,1] neg_hi:[0,0,1]
	v_pk_fma_f32 v[28:29], v[42:43], v[28:29], v[2:3]
	v_pk_fma_f32 v[26:27], v[44:45], v[26:27], v[0:1]
	v_cvt_pk_bf16_f32 v0, v32, v33
	v_cvt_pk_bf16_f32 v1, v30, v31
	v_cvt_pk_bf16_f32 v2, v36, v37
	v_cvt_pk_bf16_f32 v3, v34, v35
	global_store_dwordx4 v[48:49], v[0:3], off offset:256
	s_nop 1
	v_cvt_pk_bf16_f32 v0, v40, v41
	v_cvt_pk_bf16_f32 v1, v38, v39
	v_cvt_pk_bf16_f32 v2, v26, v27
	v_cvt_pk_bf16_f32 v3, v28, v29

;     __device__ __forceinline__ float qscale(const Unit& u) const { return ((u.pn >= 8 && u.pn <= 11) || u.pn == 17) ? 0.5f : 1.0f; }
;     ...
;         if constexpr (QM == 2) { const float qs0_ = g.qs * E.qscale(cur), qs1_ = qs0_ * g.qs_b1; _Pragma("unroll") for (int a = 0; a < 2; ++a) _Pragma("unroll") for (int b = 0; b < 2; ++b) _Pragma("unroll") for (int m = 0; m < 4; ++m) _Pragma("unroll") for (int n = 0; n < 2; ++n) { const v4i t_ = __builtin_bit_cast(v4i, acc[a][b][m][n]); acc[a][b][m][n] = (f32x4){(float)t_[0], (float)t_[1], (float)t_[2], (float)t_[3]} * (b == 0 ? qs0_ : qs1_); } }
;     __device__ __forceinline__ void operator()(EPI_ARGS) const {
;         const int row0 = u.pm * BM + wr * 64 + fr; bf16_t* dst = (u.pn < 8) ? KN : V; const int h0 = 2 * (u.pn & 7);
; #pragma unroll
;         for (int ai = 0; ai < 2; ++ai)
; #pragma unroll
;             for (int m = 0; m < 4; ++m) { const int row = row0 + ai * HALF + m * 16; const float rs = rms_scale(ssq, row, 1);
; #pragma unroll
;                 for (int bj = 0; bj < 2; ++bj)
;                     *(u32x2*)((unsigned char*)dst + ((size_t)(h0 + bj) * NTOK + row) * 128 + 64 * (wc >> 1) + 32 * (fq & 1) + 8 * ((2 * wc + (fq >> 1)) & 3)) = pack8fp8(acc[ai][bj][m][0] * rs, acc[ai][bj][m][1] * rs); }
.LBB0_4141:
	v_lshl_add_u32 v144, s4, 8, v146
	v_ashrrev_i32_e32 v145, 31, v144
	v_lshlrev_b64 v[154:155], 6, v[144:145]
	v_lshl_add_u64 v[158:159], s[8:9], 0, v[154:155]
	global_load_dwordx4 v[198:201], v[158:159], off offset:1056
	global_load_dwordx4 v[202:205], v[158:159], off offset:1072
	global_load_dwordx4 v[206:209], v[158:159], off offset:2080
	global_load_dwordx4 v[210:213], v[158:159], off offset:2096
	global_load_dwordx4 v[214:217], v[158:159], off offset:3104
	global_load_dwordx4 v[218:221], v[158:159], off offset:3120
	v_mov_b32_e32 v252, 0x2000
	v_mov_b32_e32 v253, 0
	v_lshl_add_u64 v[252:253], v[158:159], 0, v[252:253]
	global_load_dwordx4 v[222:225], v[252:253], off offset:32
	global_load_dwordx4 v[226:229], v[252:253], off offset:48
	global_load_dwordx4 v[230:233], v[252:253], off offset:1056
	global_load_dwordx4 v[234:237], v[252:253], off offset:1072
	global_load_dwordx4 v[238:241], v[252:253], off offset:2080
	global_load_dwordx4 v[242:245], v[252:253], off offset:2096
	global_load_dwordx4 v[246:249], v[252:253], off offset:3104
	global_load_dwordx4 v[250:253], v[252:253], off offset:3120
	global_load_dwordx4 v[154:157], v[158:159], off offset:32
	s_nop 0
	global_load_dwordx4 v[158:161], v[158:159], off offset:48
	s_cmp_gt_i32 s5, 7
	v_cvt_f32_i32_e32 v113, v113
	v_cvt_f32_i32_e32 v112, v112
	s_cselect_b64 vcc, -1, 0
	s_cmp_lt_i32 s5, 8
	s_cselect_b32 s25, s67, s7
	s_cselect_b32 s4, s66, s6
	s_lshl_b32 s5, s5, 15
	v_cvt_f32_i32_e32 v162, v114
	v_cndmask_b32_e32 v114, v151, v152, vcc
	s_and_b32 s14, s5, 0x38000
	v_pk_mul_f32 v[168:169], v[114:115], v[112:113] op_sel_hi:[0,1]
	v_lshl_add_u64 v[112:113], v[144:145], 0, s[14:15]
	v_lshlrev_b64 v[170:171], 7, v[112:113]
	v_cvt_f32_i32_e32 v127, v127
	v_cvt_f32_i32_e32 v126, v126
	v_cvt_f32_i32_e32 v125, v125
	v_cvt_f32_i32_e32 v124, v124
	v_cvt_f32_i32_e32 v123, v123
	v_cvt_f32_i32_e32 v122, v122
	v_cvt_f32_i32_e32 v121, v121
	v_cvt_f32_i32_e32 v120, v120
	v_cvt_f32_i32_e32 v119, v119
	v_cvt_f32_i32_e32 v118, v118
	v_cvt_f32_i32_e32 v117, v117
	v_cvt_f32_i32_e32 v116, v116
	v_cvt_f32_i32_e32 v163, v115
	v_pk_mul_f32 v[124:125], v[114:115], v[124:125] op_sel_hi:[0,1]
	v_pk_mul_f32 v[126:127], v[114:115], v[126:127] op_sel_hi:[0,1]
	v_pk_mul_f32 v[120:121], v[114:115], v[120:121] op_sel_hi:[0,1]
	v_pk_mul_f32 v[122:123], v[114:115], v[122:123] op_sel_hi:[0,1]
	v_pk_mul_f32 v[116:117], v[114:115], v[116:117] op_sel_hi:[0,1]
	v_pk_mul_f32 v[118:119], v[114:115], v[118:119] op_sel_hi:[0,1]
	v_pk_mul_f32 v[162:163], v[114:115], v[162:163] op_sel_hi:[0,1]
	s_add_u32 s4, s4, s70
	s_mov_b32 s37, s15
	s_addc_u32 s5, s25, 0
	s_or_b32 s36, s14, 0x4000
	v_mov_b32_e32 v166, 0
	v_mov_b32_e32 v167, 0
	v_mov_b32_e32 v164, 0
	v_mov_b32_e32 v165, 0
	v_cvt_f32_i32_e32 v111, v111
	v_cvt_f32_i32_e32 v110, v110
	v_cvt_f32_i32_e32 v109, v109
	v_cvt_f32_i32_e32 v108, v108
	v_cvt_f32_i32_e32 v107, v107
	v_cvt_f32_i32_e32 v106, v106
	v_cvt_f32_i32_e32 v105, v105
	v_cvt_f32_i32_e32 v104, v104
	v_cvt_f32_i32_e32 v103, v103
	v_cvt_f32_i32_e32 v102, v102
	v_cvt_f32_i32_e32 v101, v101
	v_cvt_f32_i32_e32 v100, v100
	v_cvt_f32_i32_e32 v99, v99
	v_cvt_f32_i32_e32 v98, v98
	v_cvt_f32_i32_e32 v97, v97
	v_cvt_f32_i32_e32 v96, v96
	v_cvt_f32_i32_e32 v95, v95
	v_cvt_f32_i32_e32 v94, v94
	v_cvt_f32_i32_e32 v93, v93
	v_cvt_f32_i32_e32 v92, v92
	v_cvt_f32_i32_e32 v91, v91
	v_cvt_f32_i32_e32 v90, v90
	v_cvt_f32_i32_e32 v89, v89
	v_cvt_f32_i32_e32 v88, v88
	v_cvt_f32_i32_e32 v87, v87
	v_cvt_f32_i32_e32 v86, v86
	v_cvt_f32_i32_e32 v85, v85
	v_cvt_f32_i32_e32 v84, v84
	v_cvt_f32_i32_e32 v83, v83
	v_cvt_f32_i32_e32 v82, v82
	v_cvt_f32_i32_e32 v81, v81
	v_cvt_f32_i32_e32 v80, v80
	v_cvt_f32_i32_e32 v77, v77
	v_cvt_f32_i32_e32 v76, v76
	v_cvt_f32_i32_e32 v73, v73
	v_cvt_f32_i32_e32 v72, v72
	s_waitcnt vmcnt(0)
	v_mov_b32_e32 v112, v154
	v_mov_b32_e32 v113, v158
	v_mov_b32_e32 v158, v155
	v_mov_b32_e32 v154, v156
	v_mov_b32_e32 v155, v160
	v_mov_b32_e32 v160, v157
	v_pk_add_f32 v[112:113], v[112:113], v[158:159]
	v_pk_add_f32 v[154:155], v[154:155], v[160:161]
	v_cvt_f32_i32_e32 v69, v69
	v_pk_add_f32 v[112:113], v[112:113], v[154:155]
	v_lshl_add_u64 v[154:155], v[144:145], 0, s[36:37]
	v_add_f32_e32 v112, v112, v113
	v_fmamk_f32 v112, v112, 0x3b000000, v149
	v_rsq_f32_e32 v254, v112
	v_cvt_f32_i32_e32 v68, v68
	v_cvt_f32_i32_e32 v65, v65
	v_lshl_add_u64 v[112:113], s[4:5], 0, v[136:137]
	v_lshl_add_u64 v[112:113], v[112:113], 0, v[138:139]
	v_cvt_f32_i32_e32 v64, v64
	v_cvt_f32_i32_e32 v79, v79
	v_cvt_f32_i32_e32 v78, v78
	v_cvt_f32_i32_e32 v75, v75
	v_cvt_f32_i32_e32 v74, v74
	v_lshl_add_u64 v[156:157], v[112:113], 0, v[170:171]
	v_cvt_f32_i32_e32 v71, v71
	v_cvt_f32_i32_e32 v70, v70
	v_mov_b32_e32 v158, v254
	v_pk_mul_f32 v[126:127], v[126:127], v[158:159] op_sel_hi:[1,0]
	v_pk_mul_f32 v[124:125], v[124:125], v[158:159] op_sel_hi:[1,0]
	v_pk_mul_f32 v[122:123], v[122:123], v[158:159] op_sel_hi:[1,0]
	v_pk_mul_f32 v[120:121], v[120:121], v[158:159] op_sel_hi:[1,0]
	v_pk_mul_f32 v[118:119], v[118:119], v[158:159] op_sel_hi:[1,0]
	v_pk_mul_f32 v[116:117], v[116:117], v[158:159] op_sel_hi:[1,0]
	v_pk_mul_f32 v[160:161], v[162:163], v[158:159] op_sel_hi:[1,0]
	v_pk_mul_f32 v[158:159], v[168:169], v[158:159] op_sel_hi:[1,0]
	v_med3_f32 v115, v124, s74, v153
	v_med3_f32 v124, v125, s74, v153
	v_med3_f32 v125, v126, s74, v153
	v_med3_f32 v126, v127, s74, v153
	v_med3_f32 v116, v116, s74, v153
	v_med3_f32 v117, v117, s74, v153
	v_med3_f32 v127, v158, s74, v153
	v_med3_f32 v145, v159, s74, v153
	v_med3_f32 v120, v120, s74, v153
	v_med3_f32 v121, v121, s74, v153
	v_cvt_pk_fp8_f32 v166, v116, v117
	v_cvt_pk_fp8_f32 v167, v127, v145
; __device__ __forceinline__ float rms_scale(const float* ssq, int row, int which) {
;     const f32x4 a = *(const f32x4*)(ssq + (size_t)row * 16 + which * 8), b = *(const f32x4*)(ssq + (size_t)row * 16 + which * 8 + 4);
;     const float s = ((a[0] + a[1]) + (a[2] + a[3])) + ((b[0] + b[1]) + (b[2] + b[3]));
;     return 1.0f / sqrtf(s * (1.0f / 512.0f) + RMS_EPS);
; }
;     __device__ __forceinline__ void operator()(EPI_ARGS) const {
;         const int row0 = u.pm * BM + wr * 64 + fr; bf16_t* dst = (u.pn < 8) ? KN : V; const int h0 = 2 * (u.pn & 7);
; #pragma unroll
;         for (int ai = 0; ai < 2; ++ai)
; #pragma unroll
;             for (int m = 0; m < 4; ++m) { const int row = row0 + ai * HALF + m * 16; const float rs = rms_scale(ssq, row, 1);
; #pragma unroll
;                 for (int bj = 0; bj < 2; ++bj)
;                     *(u32x2*)((unsigned char*)dst + ((size_t)(h0 + bj) * NTOK + row) * 128 + 64 * (wc >> 1) + 32 * (fq & 1) + 8 * ((2 * wc + (fq >> 1)) & 3)) = pack8fp8(acc[ai][bj][m][0] * rs, acc[ai][bj][m][1] * rs); }
	v_cvt_pk_fp8_f32 v164, v115, v124
	v_cvt_pk_fp8_f32 v165, v120, v121
	v_med3_f32 v118, v118, s74, v153
	v_med3_f32 v119, v119, s74, v153
	v_med3_f32 v158, v160, s74, v153
	v_med3_f32 v115, v161, s74, v153
	v_med3_f32 v122, v122, s74, v153
	v_med3_f32 v123, v123, s74, v153
	v_cvt_pk_fp8_f32 v166, v118, v119 op_sel:[0,0,1]
	v_cvt_pk_fp8_f32 v167, v158, v115 op_sel:[0,0,1]
	v_cvt_pk_fp8_f32 v164, v125, v126 op_sel:[0,0,1]
	v_cvt_pk_fp8_f32 v165, v122, v123 op_sel:[0,0,1]
	v_lshlrev_b64 v[116:117], 7, v[154:155]
	v_or_b32_e32 v124, 16, v144
	v_lshl_add_u64 v[116:117], v[112:113], 0, v[116:117]
	v_ashrrev_i32_e32 v125, 31, v124
	global_store_dwordx2 v[116:117], v[166:167], off
	global_store_dwordx2 v[156:157], v[164:165], off
	v_mov_b32_e32 v116, v198
	v_mov_b32_e32 v117, v199
	v_mov_b32_e32 v118, v200
	v_mov_b32_e32 v119, v201
	s_nop 0
	v_mov_b32_e32 v120, v202
	v_mov_b32_e32 v121, v203
	v_mov_b32_e32 v122, v204
	v_mov_b32_e32 v123, v205
	v_pk_mul_f32 v[108:109], v[114:115], v[108:109] op_sel_hi:[0,1]
	v_pk_mul_f32 v[110:111], v[114:115], v[110:111] op_sel_hi:[0,1]
	v_pk_mul_f32 v[104:105], v[114:115], v[104:105] op_sel_hi:[0,1]
	v_pk_mul_f32 v[106:107], v[114:115], v[106:107] op_sel_hi:[0,1]
	v_pk_mul_f32 v[100:101], v[114:115], v[100:101] op_sel_hi:[0,1]
	v_pk_mul_f32 v[102:103], v[114:115], v[102:103] op_sel_hi:[0,1]
	v_pk_mul_f32 v[96:97], v[114:115], v[96:97] op_sel_hi:[0,1]
	v_pk_mul_f32 v[98:99], v[114:115], v[98:99] op_sel_hi:[0,1]
	v_lshl_add_u64 v[160:161], v[124:125], 0, s[14:15]
	v_mov_b32_e32 v126, 0
	v_mov_b32_e32 v127, 0
	v_mov_b32_e32 v154, 0
	v_mov_b32_e32 v155, 0
	v_or_b32_e32 v156, 32, v144
	v_ashrrev_i32_e32 v157, 31, v156
	v_lshlrev_b64 v[158:159], 6, v[156:157]
	v_cvt_f32_i32_e32 v67, v67
	v_cvt_f32_i32_e32 v66, v66
	v_cvt_f32_i32_e32 v61, v61
	v_cvt_f32_i32_e32 v60, v60
	v_cvt_f32_i32_e32 v57, v57
	v_cvt_f32_i32_e32 v56, v56
	v_cvt_f32_i32_e32 v53, v53
	v_cvt_f32_i32_e32 v52, v52
	v_cvt_f32_i32_e32 v49, v49
	v_cvt_f32_i32_e32 v48, v48
	v_cvt_f32_i32_e32 v63, v63
	v_cvt_f32_i32_e32 v62, v62
	v_cvt_f32_i32_e32 v59, v59
	v_cvt_f32_i32_e32 v58, v58
	v_cvt_f32_i32_e32 v55, v55
	v_cvt_f32_i32_e32 v54, v54
	v_cvt_f32_i32_e32 v51, v51
	v_cvt_f32_i32_e32 v50, v50
	v_cvt_f32_i32_e32 v45, v45
	v_cvt_f32_i32_e32 v44, v44
	v_cvt_f32_i32_e32 v41, v41
	v_cvt_f32_i32_e32 v40, v40
	v_cvt_f32_i32_e32 v37, v37
	v_cvt_f32_i32_e32 v36, v36
	v_cvt_f32_i32_e32 v33, v33
	v_cvt_f32_i32_e32 v32, v32
	v_cvt_f32_i32_e32 v47, v47
	v_cvt_f32_i32_e32 v46, v46
	v_cvt_f32_i32_e32 v43, v43
	v_cvt_f32_i32_e32 v42, v42
	v_cvt_f32_i32_e32 v39, v39
	v_cvt_f32_i32_e32 v38, v38
	v_cvt_f32_i32_e32 v35, v35
	v_cvt_f32_i32_e32 v34, v34
	v_cvt_f32_i32_e32 v29, v29
	v_cvt_f32_i32_e32 v28, v28
	v_cvt_f32_i32_e32 v25, v25
	v_cvt_f32_i32_e32 v24, v24
	v_cvt_f32_i32_e32 v21, v21
	v_cvt_f32_i32_e32 v20, v20
	v_cvt_f32_i32_e32 v17, v17
	v_cvt_f32_i32_e32 v16, v16
	v_cvt_f32_i32_e32 v31, v31
	v_cvt_f32_i32_e32 v30, v30
	v_cvt_f32_i32_e32 v27, v27
	v_cvt_f32_i32_e32 v26, v26
	v_cvt_f32_i32_e32 v23, v23
	v_cvt_f32_i32_e32 v22, v22
	v_cvt_f32_i32_e32 v19, v19
	v_cvt_f32_i32_e32 v18, v18
	v_cvt_f32_i32_e32 v13, v13
	v_cvt_f32_i32_e32 v12, v12
	v_cvt_f32_i32_e32 v9, v9
	v_cvt_f32_i32_e32 v8, v8
	v_cvt_f32_i32_e32 v5, v5
	v_cvt_f32_i32_e32 v4, v4
	v_cvt_f32_i32_e32 v1, v1
	v_cvt_f32_i32_e32 v0, v0
	v_cvt_f32_i32_e32 v15, v15
	v_cvt_f32_i32_e32 v14, v14
	v_cvt_f32_i32_e32 v11, v11
	v_cvt_f32_i32_e32 v10, v10
	v_mov_b32_e32 v162, v116
	v_mov_b32_e32 v163, v120
	v_mov_b32_e32 v120, v117
	v_mov_b32_e32 v116, v118
	v_mov_b32_e32 v117, v122
	v_mov_b32_e32 v122, v119
	v_pk_add_f32 v[118:119], v[162:163], v[120:121]
	v_pk_add_f32 v[116:117], v[116:117], v[122:123]
	v_lshl_add_u64 v[120:121], v[124:125], 0, s[36:37]
	v_pk_add_f32 v[116:117], v[118:119], v[116:117]
	v_lshlrev_b64 v[118:119], 7, v[160:161]
	v_add_f32_e32 v115, v116, v117
	v_fmamk_f32 v115, v115, 0x3b000000, v149
	v_rsq_f32_e32 v254, v115
	v_lshlrev_b64 v[120:121], 7, v[120:121]
	v_cvt_f32_i32_e32 v7, v7
	v_cvt_f32_i32_e32 v6, v6
	v_cvt_f32_i32_e32 v3, v3
	v_cvt_f32_i32_e32 v2, v2
	s_nop 0
	s_nop 1
	s_nop 1
	v_pk_mul_f32 v[92:93], v[114:115], v[92:93] op_sel_hi:[0,1]
	v_mov_b32_e32 v122, v254
	v_pk_mul_f32 v[108:109], v[108:109], v[122:123] op_sel_hi:[1,0]
	v_pk_mul_f32 v[104:105], v[104:105], v[122:123] op_sel_hi:[1,0]
	v_pk_mul_f32 v[100:101], v[100:101], v[122:123] op_sel_hi:[1,0]
	v_pk_mul_f32 v[96:97], v[96:97], v[122:123] op_sel_hi:[1,0]
	v_med3_f32 v108, v108, s74, v153
	v_med3_f32 v109, v109, s74, v153
	v_med3_f32 v104, v104, s74, v153
	v_med3_f32 v105, v105, s74, v153
	v_med3_f32 v100, v100, s74, v153
	v_med3_f32 v101, v101, s74, v153
	v_med3_f32 v96, v96, s74, v153
	v_med3_f32 v97, v97, s74, v153
	v_cvt_pk_fp8_f32 v126, v108, v109
	v_cvt_pk_fp8_f32 v127, v104, v105
	v_cvt_pk_fp8_f32 v154, v100, v101
	v_cvt_pk_fp8_f32 v155, v96, v97
	v_pk_mul_f32 v[110:111], v[110:111], v[122:123] op_sel_hi:[1,0]
	v_pk_mul_f32 v[106:107], v[106:107], v[122:123] op_sel_hi:[1,0]
	v_pk_mul_f32 v[102:103], v[102:103], v[122:123] op_sel_hi:[1,0]
	v_pk_mul_f32 v[98:99], v[98:99], v[122:123] op_sel_hi:[1,0]
	v_med3_f32 v110, v110, s74, v153
	v_med3_f32 v111, v111, s74, v153
	v_med3_f32 v106, v106, s74, v153
	v_med3_f32 v107, v107, s74, v153
	v_med3_f32 v102, v102, s74, v153
	v_med3_f32 v103, v103, s74, v153
	v_med3_f32 v98, v98, s74, v153
	v_med3_f32 v99, v99, s74, v153
	v_cvt_pk_fp8_f32 v126, v110, v111 op_sel:[0,0,1]
	v_cvt_pk_fp8_f32 v127, v106, v107 op_sel:[0,0,1]
	v_cvt_pk_fp8_f32 v154, v102, v103 op_sel:[0,0,1]
	v_cvt_pk_fp8_f32 v155, v98, v99 op_sel:[0,0,1]
	v_lshl_add_u64 v[96:97], v[112:113], 0, v[118:119]
; __device__ __forceinline__ float rms_scale(const float* ssq, int row, int which) {
;     const f32x4 a = *(const f32x4*)(ssq + (size_t)row * 16 + which * 8), b = *(const f32x4*)(ssq + (size_t)row * 16 + which * 8 + 4);
;     const float s = ((a[0] + a[1]) + (a[2] + a[3])) + ((b[0] + b[1]) + (b[2] + b[3]));
;     return 1.0f / sqrtf(s * (1.0f / 512.0f) + RMS_EPS);
; }
;     __device__ __forceinline__ void operator()(EPI_ARGS) const {
;         const int row0 = u.pm * BM + wr * 64 + fr; bf16_t* dst = (u.pn < 8) ? KN : V; const int h0 = 2 * (u.pn & 7);
; #pragma unroll
;         for (int ai = 0; ai < 2; ++ai)
; #pragma unroll
;             for (int m = 0; m < 4; ++m) { const int row = row0 + ai * HALF + m * 16; const float rs = rms_scale(ssq, row, 1);
; #pragma unroll
;                 for (int bj = 0; bj < 2; ++bj)
;                     *(u32x2*)((unsigned char*)dst + ((size_t)(h0 + bj) * NTOK + row) * 128 + 64 * (wc >> 1) + 32 * (fq & 1) + 8 * ((2 * wc + (fq >> 1)) & 3)) = pack8fp8(acc[ai][bj][m][0] * rs, acc[ai][bj][m][1] * rs); }
	v_lshl_add_u64 v[98:99], v[112:113], 0, v[120:121]
	global_store_dwordx2 v[96:97], v[126:127], off
	global_store_dwordx2 v[98:99], v[154:155], off
	v_mov_b32_e32 v96, v206
	v_mov_b32_e32 v97, v207
	v_mov_b32_e32 v98, v208
	v_mov_b32_e32 v99, v209
	s_nop 0
	v_mov_b32_e32 v100, v210
	v_mov_b32_e32 v101, v211
	v_mov_b32_e32 v102, v212
	v_mov_b32_e32 v103, v213
	v_or_b32_e32 v108, 48, v144
	v_ashrrev_i32_e32 v109, 31, v108
	v_lshlrev_b64 v[110:111], 6, v[108:109]
	v_pk_mul_f32 v[94:95], v[114:115], v[94:95] op_sel_hi:[0,1]
	v_pk_mul_f32 v[88:89], v[114:115], v[88:89] op_sel_hi:[0,1]
	v_pk_mul_f32 v[90:91], v[114:115], v[90:91] op_sel_hi:[0,1]
	v_pk_mul_f32 v[84:85], v[114:115], v[84:85] op_sel_hi:[0,1]
	v_pk_mul_f32 v[86:87], v[114:115], v[86:87] op_sel_hi:[0,1]
	v_pk_mul_f32 v[80:81], v[114:115], v[80:81] op_sel_hi:[0,1]
	v_pk_mul_f32 v[82:83], v[114:115], v[82:83] op_sel_hi:[0,1]
	v_lshl_add_u64 v[116:117], v[156:157], 0, s[14:15]
	v_mov_b32_e32 v118, v96
	v_mov_b32_e32 v119, v100
	v_mov_b32_e32 v100, v97
	v_mov_b32_e32 v96, v98
	v_mov_b32_e32 v97, v102
	v_mov_b32_e32 v102, v99
	v_pk_add_f32 v[98:99], v[118:119], v[100:101]
	v_pk_add_f32 v[96:97], v[96:97], v[102:103]
	v_lshl_add_u64 v[100:101], v[156:157], 0, s[36:37]
	v_pk_add_f32 v[96:97], v[98:99], v[96:97]
	v_lshlrev_b64 v[98:99], 7, v[116:117]
	v_add_f32_e32 v96, v96, v97
	v_fmamk_f32 v96, v96, 0x3b000000, v149
	v_rsq_f32_e32 v254, v96
	v_lshlrev_b64 v[100:101], 7, v[100:101]
	s_nop 0
	v_lshl_add_u64 v[96:97], s[8:9], 0, v[110:111]
	s_nop 1
	s_nop 1
	s_nop 1
	v_mov_b32_e32 v102, v254
	v_pk_mul_f32 v[92:93], v[92:93], v[102:103] op_sel_hi:[1,0]
	v_pk_mul_f32 v[88:89], v[88:89], v[102:103] op_sel_hi:[1,0]
	v_pk_mul_f32 v[84:85], v[84:85], v[102:103] op_sel_hi:[1,0]
	v_pk_mul_f32 v[80:81], v[80:81], v[102:103] op_sel_hi:[1,0]
	v_med3_f32 v92, v92, s74, v153
	v_med3_f32 v93, v93, s74, v153
	v_med3_f32 v88, v88, s74, v153
	v_med3_f32 v89, v89, s74, v153
	v_med3_f32 v84, v84, s74, v153
	v_med3_f32 v85, v85, s74, v153
	v_med3_f32 v80, v80, s74, v153
	v_med3_f32 v81, v81, s74, v153
	v_cvt_pk_fp8_f32 v104, v92, v93
	v_cvt_pk_fp8_f32 v105, v88, v89
	v_cvt_pk_fp8_f32 v106, v84, v85
	v_cvt_pk_fp8_f32 v107, v80, v81
	v_pk_mul_f32 v[94:95], v[94:95], v[102:103] op_sel_hi:[1,0]
	v_pk_mul_f32 v[90:91], v[90:91], v[102:103] op_sel_hi:[1,0]
	v_pk_mul_f32 v[86:87], v[86:87], v[102:103] op_sel_hi:[1,0]
	v_pk_mul_f32 v[82:83], v[82:83], v[102:103] op_sel_hi:[1,0]
	v_med3_f32 v94, v94, s74, v153
	v_med3_f32 v95, v95, s74, v153
	v_med3_f32 v90, v90, s74, v153
	v_med3_f32 v91, v91, s74, v153
	v_med3_f32 v86, v86, s74, v153
	v_med3_f32 v87, v87, s74, v153
	v_med3_f32 v82, v82, s74, v153
	v_med3_f32 v83, v83, s74, v153
	v_cvt_pk_fp8_f32 v104, v94, v95 op_sel:[0,0,1]
	v_cvt_pk_fp8_f32 v105, v90, v91 op_sel:[0,0,1]
	v_cvt_pk_fp8_f32 v106, v86, v87 op_sel:[0,0,1]
	v_cvt_pk_fp8_f32 v107, v82, v83 op_sel:[0,0,1]
	v_lshl_add_u64 v[80:81], v[112:113], 0, v[98:99]
	v_lshl_add_u64 v[82:83], v[112:113], 0, v[100:101]
	global_store_dwordx2 v[80:81], v[104:105], off
	global_store_dwordx2 v[82:83], v[106:107], off
	v_mov_b32_e32 v80, v214
	v_mov_b32_e32 v81, v215
	v_mov_b32_e32 v82, v216
	v_mov_b32_e32 v83, v217
	s_nop 0
	v_mov_b32_e32 v84, v218
	v_mov_b32_e32 v85, v219
	v_mov_b32_e32 v86, v220
	v_mov_b32_e32 v87, v221
	v_add_u32_e32 v92, 0x80, v144
	v_ashrrev_i32_e32 v93, 31, v92
	v_lshlrev_b64 v[94:95], 6, v[92:93]
	v_lshl_add_u64 v[96:97], v[108:109], 0, s[14:15]
	v_pk_mul_f32 v[76:77], v[114:115], v[76:77] op_sel_hi:[0,1]
	v_pk_mul_f32 v[72:73], v[114:115], v[72:73] op_sel_hi:[0,1]
	v_pk_mul_f32 v[68:69], v[114:115], v[68:69] op_sel_hi:[0,1]
	v_pk_mul_f32 v[64:65], v[114:115], v[64:65] op_sel_hi:[0,1]
	v_mov_b32_e32 v88, 0
	v_mov_b32_e32 v89, 0
	v_mov_b32_e32 v90, 0
	v_mov_b32_e32 v91, 0
	v_pk_mul_f32 v[78:79], v[114:115], v[78:79] op_sel_hi:[0,1]
	v_pk_mul_f32 v[74:75], v[114:115], v[74:75] op_sel_hi:[0,1]
	v_pk_mul_f32 v[70:71], v[114:115], v[70:71] op_sel_hi:[0,1]
	v_pk_mul_f32 v[66:67], v[114:115], v[66:67] op_sel_hi:[0,1]
	v_pk_mul_f32 v[60:61], v[114:115], v[60:61] op_sel_hi:[0,1]
	v_pk_mul_f32 v[56:57], v[114:115], v[56:57] op_sel_hi:[0,1]
	v_pk_mul_f32 v[52:53], v[114:115], v[52:53] op_sel_hi:[0,1]
	v_pk_mul_f32 v[48:49], v[114:115], v[48:49] op_sel_hi:[0,1]
	v_pk_mul_f32 v[62:63], v[114:115], v[62:63] op_sel_hi:[0,1]
	v_pk_mul_f32 v[58:59], v[114:115], v[58:59] op_sel_hi:[0,1]
	v_pk_mul_f32 v[54:55], v[114:115], v[54:55] op_sel_hi:[0,1]
	v_pk_mul_f32 v[50:51], v[114:115], v[50:51] op_sel_hi:[0,1]
	v_pk_mul_f32 v[44:45], v[114:115], v[44:45] op_sel_hi:[0,1]
	v_pk_mul_f32 v[40:41], v[114:115], v[40:41] op_sel_hi:[0,1]
	v_pk_mul_f32 v[36:37], v[114:115], v[36:37] op_sel_hi:[0,1]
	v_pk_mul_f32 v[32:33], v[114:115], v[32:33] op_sel_hi:[0,1]
	v_pk_mul_f32 v[46:47], v[114:115], v[46:47] op_sel_hi:[0,1]
	v_pk_mul_f32 v[42:43], v[114:115], v[42:43] op_sel_hi:[0,1]
	v_pk_mul_f32 v[38:39], v[114:115], v[38:39] op_sel_hi:[0,1]
	v_pk_mul_f32 v[34:35], v[114:115], v[34:35] op_sel_hi:[0,1]
	v_pk_mul_f32 v[28:29], v[114:115], v[28:29] op_sel_hi:[0,1]
	v_pk_mul_f32 v[24:25], v[114:115], v[24:25] op_sel_hi:[0,1]
	v_pk_mul_f32 v[20:21], v[114:115], v[20:21] op_sel_hi:[0,1]
	v_pk_mul_f32 v[16:17], v[114:115], v[16:17] op_sel_hi:[0,1]
	v_pk_mul_f32 v[30:31], v[114:115], v[30:31] op_sel_hi:[0,1]
	v_pk_mul_f32 v[26:27], v[114:115], v[26:27] op_sel_hi:[0,1]
	v_pk_mul_f32 v[22:23], v[114:115], v[22:23] op_sel_hi:[0,1]
	v_pk_mul_f32 v[18:19], v[114:115], v[18:19] op_sel_hi:[0,1]
	v_pk_mul_f32 v[12:13], v[114:115], v[12:13] op_sel_hi:[0,1]
	v_pk_mul_f32 v[8:9], v[114:115], v[8:9] op_sel_hi:[0,1]
	v_pk_mul_f32 v[4:5], v[114:115], v[4:5] op_sel_hi:[0,1]
; __device__ __forceinline__ float rms_scale(const float* ssq, int row, int which) {
;     const f32x4 a = *(const f32x4*)(ssq + (size_t)row * 16 + which * 8), b = *(const f32x4*)(ssq + (size_t)row * 16 + which * 8 + 4);
;     const float s = ((a[0] + a[1]) + (a[2] + a[3])) + ((b[0] + b[1]) + (b[2] + b[3]));
;     return 1.0f / sqrtf(s * (1.0f / 512.0f) + RMS_EPS);
; }
;     __device__ __forceinline__ void operator()(EPI_ARGS) const {
;         const int row0 = u.pm * BM + wr * 64 + fr; bf16_t* dst = (u.pn < 8) ? KN : V; const int h0 = 2 * (u.pn & 7);
; #pragma unroll
;         for (int ai = 0; ai < 2; ++ai)
; #pragma unroll
;             for (int m = 0; m < 4; ++m) { const int row = row0 + ai * HALF + m * 16; const float rs = rms_scale(ssq, row, 1);
; #pragma unroll
;                 for (int bj = 0; bj < 2; ++bj)
;                     *(u32x2*)((unsigned char*)dst + ((size_t)(h0 + bj) * NTOK + row) * 128 + 64 * (wc >> 1) + 32 * (fq & 1) + 8 * ((2 * wc + (fq >> 1)) & 3)) = pack8fp8(acc[ai][bj][m][0] * rs, acc[ai][bj][m][1] * rs); }
	v_pk_mul_f32 v[0:1], v[114:115], v[0:1] op_sel_hi:[0,1]
	v_pk_mul_f32 v[14:15], v[114:115], v[14:15] op_sel_hi:[0,1]
	v_pk_mul_f32 v[10:11], v[114:115], v[10:11] op_sel_hi:[0,1]
	v_pk_mul_f32 v[6:7], v[114:115], v[6:7] op_sel_hi:[0,1]
	v_pk_mul_f32 v[2:3], v[114:115], v[2:3] op_sel_hi:[0,1]
	v_mov_b32_e32 v98, v80
	v_mov_b32_e32 v99, v84
	v_mov_b32_e32 v84, v81
	v_mov_b32_e32 v80, v82
	v_mov_b32_e32 v81, v86
	v_mov_b32_e32 v86, v83
	v_pk_add_f32 v[82:83], v[98:99], v[84:85]
	v_pk_add_f32 v[80:81], v[80:81], v[86:87]
	v_lshl_add_u64 v[84:85], v[108:109], 0, s[36:37]
	v_pk_add_f32 v[80:81], v[82:83], v[80:81]
	v_lshlrev_b64 v[82:83], 7, v[96:97]
	v_add_f32_e32 v80, v80, v81
	v_fmamk_f32 v80, v80, 0x3b000000, v149
	v_rsq_f32_e32 v254, v80
	v_lshlrev_b64 v[84:85], 7, v[84:85]
	s_nop 0
	v_lshl_add_u64 v[80:81], s[8:9], 0, v[94:95]
	s_nop 1
	s_nop 1
	s_nop 1
	v_mov_b32_e32 v86, v254
	v_pk_mul_f32 v[76:77], v[76:77], v[86:87] op_sel_hi:[1,0]
	v_pk_mul_f32 v[72:73], v[72:73], v[86:87] op_sel_hi:[1,0]
	v_pk_mul_f32 v[68:69], v[68:69], v[86:87] op_sel_hi:[1,0]
	v_pk_mul_f32 v[64:65], v[64:65], v[86:87] op_sel_hi:[1,0]
	v_med3_f32 v76, v76, s74, v153
	v_med3_f32 v77, v77, s74, v153
	v_med3_f32 v72, v72, s74, v153
	v_med3_f32 v73, v73, s74, v153
	v_med3_f32 v68, v68, s74, v153
	v_med3_f32 v69, v69, s74, v153
	v_med3_f32 v64, v64, s74, v153
	v_med3_f32 v65, v65, s74, v153
	v_cvt_pk_fp8_f32 v88, v76, v77
	v_cvt_pk_fp8_f32 v89, v72, v73
	v_cvt_pk_fp8_f32 v90, v68, v69
	v_cvt_pk_fp8_f32 v91, v64, v65
	v_pk_mul_f32 v[78:79], v[78:79], v[86:87] op_sel_hi:[1,0]
	v_pk_mul_f32 v[74:75], v[74:75], v[86:87] op_sel_hi:[1,0]
	v_pk_mul_f32 v[70:71], v[70:71], v[86:87] op_sel_hi:[1,0]
	v_pk_mul_f32 v[66:67], v[66:67], v[86:87] op_sel_hi:[1,0]
	v_med3_f32 v78, v78, s74, v153
	v_med3_f32 v79, v79, s74, v153
	v_med3_f32 v74, v74, s74, v153
	v_med3_f32 v75, v75, s74, v153
	v_med3_f32 v70, v70, s74, v153
	v_med3_f32 v71, v71, s74, v153
	v_med3_f32 v66, v66, s74, v153
	v_med3_f32 v67, v67, s74, v153
	v_cvt_pk_fp8_f32 v88, v78, v79 op_sel:[0,0,1]
	v_cvt_pk_fp8_f32 v89, v74, v75 op_sel:[0,0,1]
	v_cvt_pk_fp8_f32 v90, v70, v71 op_sel:[0,0,1]
	v_cvt_pk_fp8_f32 v91, v66, v67 op_sel:[0,0,1]
	v_lshl_add_u64 v[64:65], v[112:113], 0, v[82:83]
	v_lshl_add_u64 v[66:67], v[112:113], 0, v[84:85]
	global_store_dwordx2 v[64:65], v[88:89], off
	global_store_dwordx2 v[66:67], v[90:91], off
	v_mov_b32_e32 v64, v222
	v_mov_b32_e32 v65, v223
	v_mov_b32_e32 v66, v224
	v_mov_b32_e32 v67, v225
	s_nop 0
	v_mov_b32_e32 v68, v226
	v_mov_b32_e32 v69, v227
	v_mov_b32_e32 v70, v228
	v_mov_b32_e32 v71, v229
	v_add_u32_e32 v76, 0x90, v144
	v_ashrrev_i32_e32 v77, 31, v76
	v_lshlrev_b64 v[78:79], 6, v[76:77]
	v_lshl_add_u64 v[80:81], v[92:93], 0, s[14:15]
	v_mov_b32_e32 v82, v64
	v_mov_b32_e32 v83, v68
	v_mov_b32_e32 v68, v65
	v_mov_b32_e32 v64, v66
	v_mov_b32_e32 v65, v70
	v_mov_b32_e32 v70, v67
	v_pk_add_f32 v[66:67], v[82:83], v[68:69]
	v_pk_add_f32 v[64:65], v[64:65], v[70:71]
	v_lshl_add_u64 v[68:69], v[92:93], 0, s[36:37]
	v_pk_add_f32 v[64:65], v[66:67], v[64:65]
	v_lshlrev_b64 v[66:67], 7, v[80:81]
	v_add_f32_e32 v64, v64, v65
	v_fmamk_f32 v64, v64, 0x3b000000, v149
	v_rsq_f32_e32 v254, v64
	v_lshlrev_b64 v[68:69], 7, v[68:69]
	s_nop 0
	v_lshl_add_u64 v[64:65], s[8:9], 0, v[78:79]
	s_nop 1
	s_nop 1
	s_nop 1
	v_mov_b32_e32 v70, v254
	v_pk_mul_f32 v[60:61], v[60:61], v[70:71] op_sel_hi:[1,0]
	v_pk_mul_f32 v[56:57], v[56:57], v[70:71] op_sel_hi:[1,0]
	v_pk_mul_f32 v[52:53], v[52:53], v[70:71] op_sel_hi:[1,0]
	v_pk_mul_f32 v[48:49], v[48:49], v[70:71] op_sel_hi:[1,0]
	v_med3_f32 v60, v60, s74, v153
	v_med3_f32 v61, v61, s74, v153
	v_med3_f32 v56, v56, s74, v153
	v_med3_f32 v57, v57, s74, v153
	v_med3_f32 v52, v52, s74, v153
	v_med3_f32 v53, v53, s74, v153
	v_med3_f32 v48, v48, s74, v153
	v_med3_f32 v49, v49, s74, v153
	v_cvt_pk_fp8_f32 v72, v60, v61
	v_cvt_pk_fp8_f32 v73, v56, v57
	v_cvt_pk_fp8_f32 v74, v52, v53
	v_cvt_pk_fp8_f32 v75, v48, v49
	v_pk_mul_f32 v[62:63], v[62:63], v[70:71] op_sel_hi:[1,0]
	v_pk_mul_f32 v[58:59], v[58:59], v[70:71] op_sel_hi:[1,0]
	v_pk_mul_f32 v[54:55], v[54:55], v[70:71] op_sel_hi:[1,0]
	v_pk_mul_f32 v[50:51], v[50:51], v[70:71] op_sel_hi:[1,0]
	v_med3_f32 v62, v62, s74, v153
	v_med3_f32 v63, v63, s74, v153
	v_med3_f32 v58, v58, s74, v153
	v_med3_f32 v59, v59, s74, v153
	v_med3_f32 v54, v54, s74, v153
	v_med3_f32 v55, v55, s74, v153
	v_med3_f32 v50, v50, s74, v153
	v_med3_f32 v51, v51, s74, v153
	v_cvt_pk_fp8_f32 v72, v62, v63 op_sel:[0,0,1]
	v_cvt_pk_fp8_f32 v73, v58, v59 op_sel:[0,0,1]
	v_cvt_pk_fp8_f32 v74, v54, v55 op_sel:[0,0,1]
	v_cvt_pk_fp8_f32 v75, v50, v51 op_sel:[0,0,1]
	v_lshl_add_u64 v[48:49], v[112:113], 0, v[66:67]
	v_lshl_add_u64 v[50:51], v[112:113], 0, v[68:69]
	global_store_dwordx2 v[48:49], v[72:73], off
	global_store_dwordx2 v[50:51], v[74:75], off
	v_mov_b32_e32 v48, v230
	v_mov_b32_e32 v49, v231
	v_mov_b32_e32 v50, v232
	v_mov_b32_e32 v51, v233
	s_nop 0
	v_mov_b32_e32 v52, v234
	v_mov_b32_e32 v53, v235
	v_mov_b32_e32 v54, v236
	v_mov_b32_e32 v55, v237
	v_add_u32_e32 v60, 0xa0, v144
	v_ashrrev_i32_e32 v61, 31, v60
	v_lshlrev_b64 v[62:63], 6, v[60:61]
	v_lshl_add_u64 v[64:65], v[76:77], 0, s[14:15]
	v_mov_b32_e32 v66, v48
	v_mov_b32_e32 v67, v52
	v_mov_b32_e32 v52, v49
	v_mov_b32_e32 v48, v50
	v_mov_b32_e32 v49, v54
	v_mov_b32_e32 v54, v51
	v_pk_add_f32 v[50:51], v[66:67], v[52:53]
	v_pk_add_f32 v[48:49], v[48:49], v[54:55]
	v_lshl_add_u64 v[52:53], v[76:77], 0, s[36:37]
	v_pk_add_f32 v[48:49], v[50:51], v[48:49]
	v_lshlrev_b64 v[50:51], 7, v[64:65]
	v_add_f32_e32 v48, v48, v49
	v_fmamk_f32 v48, v48, 0x3b000000, v149
	v_rsq_f32_e32 v254, v48
; #define PG8_BAR __builtin_amdgcn_s_barrier()
;     ...
;         if (!has_next) break;
; #pragma unroll
;         for (int a = 0; a < 2; ++a)
; #pragma unroll
;             for (int b = 0; b < 2; ++b)
; #pragma unroll
;                 for (int m = 0; m < 4; ++m)
; #pragma unroll
;                     for (int n = 0; n < 2; ++n) acc[a][b][m][n] = (f32x4){0.f, 0.f, 0.f, 0.f};
;         cur = nxt; cA = nA; cB = nB; ++ui;
;         if (wr == 1) PG8_BAR;
;     __device__ __forceinline__ void operator()(EPI_ARGS) const {
;         const int row0 = u.pm * BM + wr * 64 + fr; bf16_t* dst = (u.pn < 8) ? KN : V; const int h0 = 2 * (u.pn & 7);
; #pragma unroll
;         for (int ai = 0; ai < 2; ++ai)
; #pragma unroll
;             for (int m = 0; m < 4; ++m) { const int row = row0 + ai * HALF + m * 16; const float rs = rms_scale(ssq, row, 1);
; #pragma unroll
;                 for (int bj = 0; bj < 2; ++bj)
;                     *(u32x2*)((unsigned char*)dst + ((size_t)(h0 + bj) * NTOK + row) * 128 + 64 * (wc >> 1) + 32 * (fq & 1) + 8 * ((2 * wc + (fq >> 1)) & 3)) = pack8fp8(acc[ai][bj][m][0] * rs, acc[ai][bj][m][1] * rs); }
	v_lshlrev_b64 v[52:53], 7, v[52:53]
	s_nop 0
	v_lshl_add_u64 v[48:49], s[8:9], 0, v[62:63]
	s_nop 1
	s_nop 1
	s_nop 1
	v_mov_b32_e32 v54, v254
	v_pk_mul_f32 v[44:45], v[44:45], v[54:55] op_sel_hi:[1,0]
	v_pk_mul_f32 v[40:41], v[40:41], v[54:55] op_sel_hi:[1,0]
	v_pk_mul_f32 v[36:37], v[36:37], v[54:55] op_sel_hi:[1,0]
	v_pk_mul_f32 v[32:33], v[32:33], v[54:55] op_sel_hi:[1,0]
	v_med3_f32 v44, v44, s74, v153
	v_med3_f32 v45, v45, s74, v153
	v_med3_f32 v40, v40, s74, v153
	v_med3_f32 v41, v41, s74, v153
	v_med3_f32 v36, v36, s74, v153
	v_med3_f32 v37, v37, s74, v153
	v_med3_f32 v32, v32, s74, v153
	v_med3_f32 v33, v33, s74, v153
	v_cvt_pk_fp8_f32 v56, v44, v45
	v_cvt_pk_fp8_f32 v57, v40, v41
	v_cvt_pk_fp8_f32 v58, v36, v37
	v_cvt_pk_fp8_f32 v59, v32, v33
	v_pk_mul_f32 v[46:47], v[46:47], v[54:55] op_sel_hi:[1,0]
	v_pk_mul_f32 v[42:43], v[42:43], v[54:55] op_sel_hi:[1,0]
	v_pk_mul_f32 v[38:39], v[38:39], v[54:55] op_sel_hi:[1,0]
	v_pk_mul_f32 v[34:35], v[34:35], v[54:55] op_sel_hi:[1,0]
	v_med3_f32 v46, v46, s74, v153
	v_med3_f32 v47, v47, s74, v153
	v_med3_f32 v42, v42, s74, v153
	v_med3_f32 v43, v43, s74, v153
	v_med3_f32 v38, v38, s74, v153
	v_med3_f32 v39, v39, s74, v153
	v_med3_f32 v34, v34, s74, v153
	v_med3_f32 v35, v35, s74, v153
	v_cvt_pk_fp8_f32 v56, v46, v47 op_sel:[0,0,1]
	v_cvt_pk_fp8_f32 v57, v42, v43 op_sel:[0,0,1]
	v_cvt_pk_fp8_f32 v58, v38, v39 op_sel:[0,0,1]
	v_cvt_pk_fp8_f32 v59, v34, v35 op_sel:[0,0,1]
	v_lshl_add_u64 v[32:33], v[112:113], 0, v[50:51]
	v_lshl_add_u64 v[34:35], v[112:113], 0, v[52:53]
	global_store_dwordx2 v[32:33], v[56:57], off
	global_store_dwordx2 v[34:35], v[58:59], off
	v_mov_b32_e32 v32, v238
	v_mov_b32_e32 v33, v239
	v_mov_b32_e32 v34, v240
	v_mov_b32_e32 v35, v241
	s_nop 0
	v_mov_b32_e32 v36, v242
	v_mov_b32_e32 v37, v243
	v_mov_b32_e32 v38, v244
	v_mov_b32_e32 v39, v245
	v_add_u32_e32 v44, 0xb0, v144
	v_ashrrev_i32_e32 v45, 31, v44
	v_lshlrev_b64 v[46:47], 6, v[44:45]
	v_lshl_add_u64 v[48:49], v[60:61], 0, s[14:15]
	v_mov_b32_e32 v50, v32
	v_mov_b32_e32 v51, v36
	v_mov_b32_e32 v36, v33
	v_mov_b32_e32 v32, v34
	v_mov_b32_e32 v33, v38
	v_mov_b32_e32 v38, v35
	v_pk_add_f32 v[34:35], v[50:51], v[36:37]
	v_pk_add_f32 v[32:33], v[32:33], v[38:39]
	v_lshl_add_u64 v[36:37], v[60:61], 0, s[36:37]
	v_pk_add_f32 v[32:33], v[34:35], v[32:33]
	v_lshlrev_b64 v[34:35], 7, v[48:49]
	v_add_f32_e32 v32, v32, v33
	v_fmamk_f32 v32, v32, 0x3b000000, v149
	v_rsq_f32_e32 v254, v32
	v_lshlrev_b64 v[36:37], 7, v[36:37]
	s_nop 0
	v_lshl_add_u64 v[32:33], s[8:9], 0, v[46:47]
	s_nop 1
	s_nop 1
	s_nop 1
	v_mov_b32_e32 v38, v254
	v_pk_mul_f32 v[28:29], v[28:29], v[38:39] op_sel_hi:[1,0]
	v_pk_mul_f32 v[24:25], v[24:25], v[38:39] op_sel_hi:[1,0]
	v_pk_mul_f32 v[20:21], v[20:21], v[38:39] op_sel_hi:[1,0]
	v_pk_mul_f32 v[16:17], v[16:17], v[38:39] op_sel_hi:[1,0]
	v_med3_f32 v28, v28, s74, v153
	v_med3_f32 v29, v29, s74, v153
	v_med3_f32 v24, v24, s74, v153
	v_med3_f32 v25, v25, s74, v153
	v_med3_f32 v20, v20, s74, v153
	v_med3_f32 v21, v21, s74, v153
	v_med3_f32 v16, v16, s74, v153
	v_med3_f32 v17, v17, s74, v153
	v_cvt_pk_fp8_f32 v40, v28, v29
	v_cvt_pk_fp8_f32 v41, v24, v25
	v_cvt_pk_fp8_f32 v42, v20, v21
	v_cvt_pk_fp8_f32 v43, v16, v17
	v_pk_mul_f32 v[30:31], v[30:31], v[38:39] op_sel_hi:[1,0]
	v_pk_mul_f32 v[26:27], v[26:27], v[38:39] op_sel_hi:[1,0]
	v_pk_mul_f32 v[22:23], v[22:23], v[38:39] op_sel_hi:[1,0]
	v_pk_mul_f32 v[18:19], v[18:19], v[38:39] op_sel_hi:[1,0]
	v_med3_f32 v30, v30, s74, v153
	v_med3_f32 v31, v31, s74, v153
	v_med3_f32 v26, v26, s74, v153
	v_med3_f32 v27, v27, s74, v153
	v_med3_f32 v22, v22, s74, v153
	v_med3_f32 v23, v23, s74, v153
	v_med3_f32 v18, v18, s74, v153
	v_med3_f32 v19, v19, s74, v153
	v_cvt_pk_fp8_f32 v40, v30, v31 op_sel:[0,0,1]
	v_cvt_pk_fp8_f32 v41, v26, v27 op_sel:[0,0,1]
	v_cvt_pk_fp8_f32 v42, v22, v23 op_sel:[0,0,1]
	v_cvt_pk_fp8_f32 v43, v18, v19 op_sel:[0,0,1]
	v_lshl_add_u64 v[16:17], v[112:113], 0, v[34:35]
	v_lshl_add_u64 v[18:19], v[112:113], 0, v[36:37]
	global_store_dwordx2 v[16:17], v[40:41], off
	global_store_dwordx2 v[18:19], v[42:43], off
	v_mov_b32_e32 v16, v246
	v_mov_b32_e32 v17, v247
	v_mov_b32_e32 v18, v248
	v_mov_b32_e32 v19, v249
	s_nop 0
	v_mov_b32_e32 v20, v250
	v_mov_b32_e32 v21, v251
	v_mov_b32_e32 v22, v252
	v_mov_b32_e32 v23, v253
	v_lshl_add_u64 v[28:29], v[44:45], 0, s[14:15]
	v_mov_b32_e32 v30, v16
	v_mov_b32_e32 v31, v20
	v_mov_b32_e32 v20, v17
	v_mov_b32_e32 v16, v18
	v_mov_b32_e32 v17, v22
	v_mov_b32_e32 v22, v19
	v_pk_add_f32 v[18:19], v[30:31], v[20:21]
	v_pk_add_f32 v[16:17], v[16:17], v[22:23]
	s_nop 0
	v_pk_add_f32 v[16:17], v[18:19], v[16:17]
	v_lshl_add_u64 v[18:19], v[44:45], 0, s[36:37]
	v_add_f32_e32 v16, v16, v17
	v_fmamk_f32 v16, v16, 0x3b000000, v149
	v_rsq_f32_e32 v254, v16
	v_lshlrev_b64 v[18:19], 7, v[18:19]
	s_nop 0
	v_lshlrev_b64 v[16:17], 7, v[28:29]
	v_lshl_add_u64 v[16:17], v[112:113], 0, v[16:17]
	s_nop 1
	s_nop 1
	s_nop 1
	v_mov_b32_e32 v20, v254
	v_pk_mul_f32 v[12:13], v[12:13], v[20:21] op_sel_hi:[1,0]
	v_pk_mul_f32 v[8:9], v[8:9], v[20:21] op_sel_hi:[1,0]
	v_pk_mul_f32 v[4:5], v[4:5], v[20:21] op_sel_hi:[1,0]
	v_pk_mul_f32 v[0:1], v[0:1], v[20:21] op_sel_hi:[1,0]
	v_med3_f32 v12, v12, s74, v153
	v_med3_f32 v13, v13, s74, v153
	v_med3_f32 v8, v8, s74, v153
	v_med3_f32 v9, v9, s74, v153
	v_med3_f32 v4, v4, s74, v153
	v_med3_f32 v5, v5, s74, v153
	v_med3_f32 v0, v0, s74, v153
	v_med3_f32 v1, v1, s74, v153
	v_cvt_pk_fp8_f32 v24, v12, v13
	v_cvt_pk_fp8_f32 v25, v8, v9
	v_cvt_pk_fp8_f32 v26, v4, v5
	v_cvt_pk_fp8_f32 v27, v0, v1
	v_pk_mul_f32 v[14:15], v[14:15], v[20:21] op_sel_hi:[1,0]
	v_pk_mul_f32 v[10:11], v[10:11], v[20:21] op_sel_hi:[1,0]
	v_pk_mul_f32 v[6:7], v[6:7], v[20:21] op_sel_hi:[1,0]
	v_pk_mul_f32 v[2:3], v[2:3], v[20:21] op_sel_hi:[1,0]
	v_med3_f32 v14, v14, s74, v153
	v_med3_f32 v15, v15, s74, v153
	v_med3_f32 v10, v10, s74, v153
	v_med3_f32 v11, v11, s74, v153
	v_med3_f32 v6, v6, s74, v153
	v_med3_f32 v7, v7, s74, v153
	v_med3_f32 v2, v2, s74, v153
	v_med3_f32 v3, v3, s74, v153
	v_cvt_pk_fp8_f32 v24, v14, v15 op_sel:[0,0,1]
	v_cvt_pk_fp8_f32 v25, v10, v11 op_sel:[0,0,1]
	v_cvt_pk_fp8_f32 v26, v6, v7 op_sel:[0,0,1]
	v_cvt_pk_fp8_f32 v27, v2, v3 op_sel:[0,0,1]
	s_andn2_b64 vcc, exec, s[2:3]
	s_mov_b64 s[2:3], -1
	v_lshl_add_u64 v[0:1], v[112:113], 0, v[18:19]
	global_store_dwordx2 v[16:17], v[24:25], off
	global_store_dwordx2 v[0:1], v[26:27], off
	s_cbranch_vccnz .LBB0_4130
	s_andn2_b64 vcc, exec, s[16:17]
	s_cbranch_vccnz .LBB0_4129
	s_barrier
	s_branch .LBB0_4129
